# f32->bf16 RNE pack idiom (bfe/add3/lshr/and_or) replaced by v_cvt_pk_bf16_f32 at 324 sites (same round-to-nearest-even bf16 conversion)
# speedup vs baseline: 1.0699x; 1.0092x over previous
.LBB0_120:
	s_or_b64 exec, exec, s[8:9]
	v_lshl_add_u64 v[6:7], v[6:7], 0, v[2:3]
	global_load_dwordx4 v[12:15], v[6:7], off
	v_lshlrev_b64 v[20:21], 11, v[8:9]
	v_lshl_add_u32 v9, v10, 2, v1
	ds_read_b128 v[16:19], v9 offset:4096
	v_lshl_add_u64 v[32:33], v[4:5], 0, v[20:21]
	ds_read_b128 v[20:23], v9
	ds_read_b128 v[24:27], v9 offset:1024
	ds_read_b128 v[28:31], v9 offset:5120
	s_waitcnt lgkmcnt(3)
	v_pk_add_f32 v[10:11], v[18:19], 1.0 op_sel_hi:[1,0]
	v_pk_add_f32 v[16:17], v[16:17], 1.0 op_sel_hi:[1,0]
	s_waitcnt vmcnt(0) lgkmcnt(2)
	v_pk_fma_f32 v[10:11], v[14:15], v[10:11], v[22:23]
	v_pk_fma_f32 v[12:13], v[12:13], v[16:17], v[20:21]
	v_bfe_u32 v16, v10, 16, 1
	s_nop 0
	s_nop 0
	v_bfe_u32 v17, v11, 16, 1
	s_nop 0
	v_add3_u32 v10, v10, v16, s13
	s_nop 0
	v_add3_u32 v11, v11, v17, s13
	s_nop 0
	v_lshrrev_b32_e32 v14, 16, v10
	v_cvt_pk_bf16_f32 v10, v12, v13
	v_and_or_b32 v11, v11, s14, v14
	global_store_dwordx2 v[32:33], v[10:11], off
	global_load_dwordx4 v[10:13], v[6:7], off offset:1024
	s_waitcnt lgkmcnt(0)
	v_pk_add_f32 v[14:15], v[30:31], 1.0 op_sel_hi:[1,0]
	v_pk_add_f32 v[16:17], v[28:29], 1.0 op_sel_hi:[1,0]
	s_waitcnt vmcnt(0)
	v_pk_fma_f32 v[12:13], v[12:13], v[14:15], v[26:27]
	v_pk_fma_f32 v[10:11], v[10:11], v[16:17], v[24:25]
	s_nop 0
	s_nop 0
	s_nop 0
	s_nop 0
	s_nop 0
	s_nop 0
	s_nop 0
	s_nop 0
	s_nop 0
	s_nop 0
	v_cvt_pk_bf16_f32 v10, v10, v11
	v_cvt_pk_bf16_f32 v11, v12, v13
	global_store_dwordx2 v[32:33], v[10:11], off offset:512
	global_load_dwordx4 v[10:13], v[6:7], off offset:2048
	ds_read_b128 v[14:17], v9 offset:6144
	ds_read_b128 v[18:21], v9 offset:2048
	ds_read_b128 v[22:25], v9 offset:3072
	ds_read_b128 v[26:29], v9 offset:7168
	s_waitcnt lgkmcnt(3)
	v_pk_add_f32 v[16:17], v[16:17], 1.0 op_sel_hi:[1,0]
	v_pk_add_f32 v[14:15], v[14:15], 1.0 op_sel_hi:[1,0]
	s_waitcnt vmcnt(0) lgkmcnt(2)
	v_pk_fma_f32 v[12:13], v[12:13], v[16:17], v[20:21]
	v_pk_fma_f32 v[10:11], v[10:11], v[14:15], v[18:19]
	s_nop 0
	v_bfe_u32 v9, v10, 16, 1
	v_bfe_u32 v14, v11, 16, 1
	s_nop 0
	v_add3_u32 v9, v10, v9, s13
	v_add3_u32 v10, v11, v14, s13
	s_nop 0
	s_nop 0
	v_lshrrev_b32_e32 v9, 16, v9
	s_nop 0
	v_and_or_b32 v10, v10, s14, v9
	v_cvt_pk_bf16_f32 v11, v12, v13
	global_store_dwordx2 v[32:33], v[10:11], off offset:1024
	global_load_dwordx4 v[10:13], v[6:7], off offset:3072
	v_add_u32_e32 v6, s11, v8
	s_waitcnt lgkmcnt(0)
	v_pk_add_f32 v[8:9], v[28:29], 1.0 op_sel_hi:[1,0]
	v_pk_add_f32 v[14:15], v[26:27], 1.0 op_sel_hi:[1,0]
	v_cmp_lt_i32_e32 vcc, s15, v6
	s_orn2_b64 s[8:9], vcc, exec
	s_waitcnt vmcnt(0)
	v_pk_fma_f32 v[8:9], v[12:13], v[8:9], v[24:25]
	v_pk_fma_f32 v[10:11], v[10:11], v[14:15], v[22:23]
	v_bfe_u32 v13, v8, 16, 1
	v_bfe_u32 v7, v10, 16, 1
	v_bfe_u32 v12, v11, 16, 1
	v_bfe_u32 v14, v9, 16, 1
	v_add3_u32 v7, v10, v7, s13
	v_add3_u32 v8, v8, v13, s13
	v_add3_u32 v10, v11, v12, s13
	v_add3_u32 v9, v9, v14, s13
	v_lshrrev_b32_e32 v7, 16, v7
	v_lshrrev_b32_e32 v11, 16, v8
	v_and_or_b32 v8, v10, s14, v7
	v_and_or_b32 v9, v9, s14, v11
	global_store_dwordx2 v[32:33], v[8:9], off offset:1536

.LBB0_122:
	v_cmp_lt_i32_e32 vcc, s12, v6
	s_and_saveexec_b64 s[6:7], vcc
	s_xor_b64 s[6:7], exec, s[6:7]
	v_add_u32_e32 v8, 0xffffc000, v6
	v_mov_b32_e32 v9, v3
	v_lshlrev_b64 v[8:9], 12, v[8:9]
	v_lshl_add_u64 v[8:9], s[56:57], 0, v[8:9]
	v_mov_b32_e32 v7, v3
	s_or_saveexec_b64 s[6:7], s[6:7]
	v_mov_b32_e32 v10, 0x800
	s_xor_b64 exec, exec, s[6:7]
	v_ashrrev_i32_e32 v7, 31, v6
	v_lshlrev_b64 v[8:9], 12, v[6:7]
	v_lshl_add_u64 v[8:9], s[52:53], 0, v[8:9]
	v_mov_b32_e32 v10, 0
	s_or_b64 exec, exec, s[6:7]
	v_lshl_add_u64 v[28:29], v[8:9], 0, v[2:3]
	global_load_dwordx4 v[12:15], v[28:29], off
	v_lshlrev_b64 v[16:17], 11, v[6:7]
	v_lshl_add_u32 v7, v10, 2, v1
	ds_read_b128 v[8:11], v7 offset:4096
	v_lshl_add_u64 v[30:31], v[4:5], 0, v[16:17]
	ds_read_b128 v[16:19], v7
	ds_read_b128 v[20:23], v7 offset:1024
	ds_read_b128 v[24:27], v7 offset:5120
	s_mov_b64 s[8:9], -1
	s_waitcnt lgkmcnt(3)
	v_pk_add_f32 v[10:11], v[10:11], 1.0 op_sel_hi:[1,0]
	v_pk_add_f32 v[8:9], v[8:9], 1.0 op_sel_hi:[1,0]
	s_waitcnt vmcnt(0) lgkmcnt(2)
	v_pk_fma_f32 v[10:11], v[14:15], v[10:11], v[18:19]
	v_pk_fma_f32 v[8:9], v[12:13], v[8:9], v[16:17]
	s_nop 0
	s_nop 0
	s_nop 0
	s_nop 0
	s_nop 0
	s_nop 0
	s_nop 0
	s_nop 0
	s_nop 0
	s_nop 0
	v_cvt_pk_bf16_f32 v8, v8, v9
	v_cvt_pk_bf16_f32 v9, v10, v11
	global_store_dwordx2 v[30:31], v[8:9], off
	global_load_dwordx4 v[8:11], v[28:29], off offset:1024
	s_waitcnt lgkmcnt(0)
	v_pk_add_f32 v[12:13], v[26:27], 1.0 op_sel_hi:[1,0]
	v_pk_add_f32 v[14:15], v[24:25], 1.0 op_sel_hi:[1,0]
	s_waitcnt vmcnt(0)
	v_pk_fma_f32 v[10:11], v[10:11], v[12:13], v[22:23]
	v_pk_fma_f32 v[8:9], v[8:9], v[14:15], v[20:21]
	s_nop 0
	s_nop 0
	s_nop 0
	s_nop 0
	s_nop 0
	s_nop 0
	s_nop 0
	s_nop 0
	s_nop 0
	s_nop 0
	v_cvt_pk_bf16_f32 v8, v8, v9
	v_cvt_pk_bf16_f32 v9, v10, v11
	global_store_dwordx2 v[30:31], v[8:9], off offset:512
	global_load_dwordx4 v[8:11], v[28:29], off offset:2048
	ds_read_b128 v[12:15], v7 offset:6144
	ds_read_b128 v[16:19], v7 offset:2048
	ds_read_b128 v[20:23], v7 offset:3072
	ds_read_b128 v[24:27], v7 offset:7168
	s_waitcnt lgkmcnt(3)
	v_pk_add_f32 v[14:15], v[14:15], 1.0 op_sel_hi:[1,0]
	v_pk_add_f32 v[12:13], v[12:13], 1.0 op_sel_hi:[1,0]
	s_waitcnt vmcnt(0) lgkmcnt(2)
	v_pk_fma_f32 v[10:11], v[10:11], v[14:15], v[18:19]
	v_pk_fma_f32 v[8:9], v[8:9], v[12:13], v[16:17]
	s_nop 0
	v_bfe_u32 v7, v8, 16, 1
	v_bfe_u32 v12, v9, 16, 1
	s_nop 0
	v_add3_u32 v7, v8, v7, s13
	v_add3_u32 v8, v9, v12, s13
	s_nop 0
	s_nop 0
	v_lshrrev_b32_e32 v7, 16, v7
	s_nop 0
	v_and_or_b32 v8, v8, s14, v7
	v_cvt_pk_bf16_f32 v9, v10, v11
	global_store_dwordx2 v[30:31], v[8:9], off offset:1024
	global_load_dwordx4 v[10:13], v[28:29], off offset:3072
	v_add_u32_e32 v8, s11, v6
	s_waitcnt lgkmcnt(0)
	v_pk_add_f32 v[6:7], v[26:27], 1.0 op_sel_hi:[1,0]
	v_pk_add_f32 v[14:15], v[24:25], 1.0 op_sel_hi:[1,0]
	v_cmp_gt_i32_e32 vcc, s10, v8
	s_waitcnt vmcnt(0)
	v_pk_fma_f32 v[6:7], v[12:13], v[6:7], v[22:23]
	v_pk_fma_f32 v[10:11], v[10:11], v[14:15], v[20:21]
	v_bfe_u32 v13, v6, 16, 1
	v_bfe_u32 v9, v10, 16, 1
	v_bfe_u32 v12, v11, 16, 1
	v_bfe_u32 v14, v7, 16, 1
	v_add3_u32 v9, v10, v9, s13
	v_add3_u32 v6, v6, v13, s13
	v_add3_u32 v10, v11, v12, s13
	v_add3_u32 v7, v7, v14, s13
	v_lshrrev_b32_e32 v9, 16, v9
	v_lshrrev_b32_e32 v11, 16, v6
	v_and_or_b32 v6, v10, s14, v9
	v_and_or_b32 v7, v7, s14, v11
	global_store_dwordx2 v[30:31], v[6:7], off offset:1536
	s_and_saveexec_b64 s[6:7], vcc
	s_cbranch_execz .LBB0_121
	v_cmp_lt_i32_e32 vcc, s12, v8
	s_and_saveexec_b64 s[8:9], vcc
	s_xor_b64 s[8:9], exec, s[8:9]
	v_add_u32_e32 v6, 0xffffc000, v8
	v_mov_b32_e32 v7, v3
	v_lshlrev_b64 v[6:7], 12, v[6:7]
	v_lshl_add_u64 v[6:7], s[56:57], 0, v[6:7]
	v_mov_b32_e32 v9, v3
	s_or_saveexec_b64 s[8:9], s[8:9]
	v_mov_b32_e32 v10, 0x800
	s_xor_b64 exec, exec, s[8:9]
	s_cbranch_execz .LBB0_120
	v_ashrrev_i32_e32 v9, 31, v8
	v_lshlrev_b64 v[6:7], 12, v[8:9]
	v_lshl_add_u64 v[6:7], s[52:53], 0, v[6:7]
	v_mov_b32_e32 v10, 0
	s_branch .LBB0_120

.LBB0_219:
	s_nop 0
	s_nop 0
	s_nop 0
	s_nop 0
	s_nop 0
	v_cvt_pk_bf16_f32 v126, v126, v127
	s_nop 0
	s_nop 0
	s_nop 0
	s_nop 0
	s_nop 0
	v_cvt_pk_bf16_f32 v127, v128, v129
	s_nop 0
	s_nop 0
	s_nop 0
	s_nop 0
	s_nop 0
	v_cvt_pk_bf16_f32 v128, v122, v123
	s_nop 0
	s_nop 0
	s_nop 0
	s_nop 0
	s_nop 0
	v_cvt_pk_bf16_f32 v129, v124, v125
	s_nop 0
	s_nop 0
	s_nop 0
	s_nop 0
	s_nop 0
	v_cvt_pk_bf16_f32 v118, v118, v119
	s_nop 0
	s_nop 0
	s_nop 0
	s_nop 0
	s_nop 0
	v_cvt_pk_bf16_f32 v119, v120, v121
	s_nop 0
	s_nop 0
	s_nop 0
	s_nop 0
	s_nop 0
	v_cvt_pk_bf16_f32 v120, v110, v111
	s_nop 0
	v_lshl_or_b32 v148, s43, 8, v151
	s_nop 0
	s_nop 0
	v_lshl_add_u32 v155, s18, 8, v1
	v_ashrrev_i32_e32 v149, 31, v148
	v_mov_b64_e32 v[146:147], s[88:89]
	s_nop 0
	s_nop 0
	v_mad_i64_i32 v[156:157], s[20:21], v155, s40, v[146:147]
	v_lshlrev_b64 v[148:149], 1, v[148:149]
	v_cvt_pk_bf16_f32 v121, v112, v113
	v_or_b32_e32 v110, 16, v155
	v_lshl_add_u64 v[156:157], v[156:157], 0, v[148:149]
	v_mad_i64_i32 v[110:111], s[20:21], v110, s40, v[146:147]
	global_store_dwordx4 v[156:157], v[118:121], off offset:256
	s_nop 0
	s_nop 0
	v_lshl_add_u64 v[118:119], v[110:111], 0, v[148:149]
	s_nop 0
	s_nop 0
	s_nop 0
	s_nop 0
	s_nop 0
	v_cvt_pk_bf16_f32 v110, v114, v115
	s_nop 0
	s_nop 0
	s_nop 0
	v_cvt_pk_bf16_f32 v111, v116, v117
	s_nop 0
	s_nop 0
	s_nop 0
	s_nop 0
	s_nop 0
	v_cvt_pk_bf16_f32 v112, v106, v107
	s_nop 0
	s_nop 0
	s_nop 0
	s_nop 0
	s_nop 0
	v_cvt_pk_bf16_f32 v113, v108, v109
	s_nop 0
	s_nop 0
	s_nop 0
	s_nop 0
	s_nop 0
	v_cvt_pk_bf16_f32 v102, v102, v103
	s_nop 0
	s_nop 0
	s_nop 0
	s_nop 0
	s_nop 0
	v_cvt_pk_bf16_f32 v103, v104, v105
	s_nop 0
	s_nop 0
	s_nop 0
	s_nop 0
	s_nop 0
	v_cvt_pk_bf16_f32 v104, v94, v95
	s_nop 0
	s_nop 0
	s_nop 0
	s_nop 0
	s_nop 0
	v_cvt_pk_bf16_f32 v105, v96, v97
	v_or_b32_e32 v94, 32, v155
	v_mad_i64_i32 v[94:95], s[20:21], v94, s40, v[146:147]
	global_store_dwordx4 v[118:119], v[102:105], off offset:256
	s_nop 0
	s_nop 0
	v_lshl_add_u64 v[102:103], v[94:95], 0, v[148:149]
	s_nop 0
	s_nop 0
	s_nop 0
	s_nop 0
	s_nop 0
	v_cvt_pk_bf16_f32 v94, v98, v99
	s_nop 0
	s_nop 0
	s_nop 0
	v_cvt_pk_bf16_f32 v95, v100, v101
	s_nop 0
	s_nop 0
	s_nop 0
	s_nop 0
	s_nop 0
	v_cvt_pk_bf16_f32 v96, v90, v91
	s_nop 0
	s_nop 0
	s_nop 0
	s_nop 0
	s_nop 0
	v_cvt_pk_bf16_f32 v97, v92, v93
	s_nop 0
	s_nop 0
	s_nop 0
	s_nop 0
	s_nop 0
	v_cvt_pk_bf16_f32 v86, v86, v87
	s_nop 0
	s_nop 0
	s_nop 0
	s_nop 0
	s_nop 0
	v_cvt_pk_bf16_f32 v87, v88, v89
	s_nop 0
	s_nop 0
	s_nop 0
	s_nop 0
	s_nop 0
	v_cvt_pk_bf16_f32 v88, v78, v79
	s_nop 0
	s_nop 0
	s_nop 0
	s_nop 0
	s_nop 0
	v_cvt_pk_bf16_f32 v89, v80, v81
	v_or_b32_e32 v78, 48, v155
	v_mad_i64_i32 v[78:79], s[20:21], v78, s40, v[146:147]
	global_store_dwordx4 v[102:103], v[86:89], off offset:256
	s_nop 0
	s_nop 0
	v_lshl_add_u64 v[86:87], v[78:79], 0, v[148:149]
	s_nop 0
	s_nop 0
	s_nop 0
	s_nop 0
	s_nop 0
	v_cvt_pk_bf16_f32 v78, v82, v83
	s_nop 0
	s_nop 0
	s_nop 0
	v_cvt_pk_bf16_f32 v79, v84, v85
	s_nop 0
	s_nop 0
	s_nop 0
	s_nop 0
	s_nop 0
	v_cvt_pk_bf16_f32 v80, v74, v75
	s_nop 0
	s_nop 0
	s_nop 0
	s_nop 0
	s_nop 0
	v_cvt_pk_bf16_f32 v81, v76, v77
	s_nop 0
	s_nop 0
	s_nop 0
	s_nop 0
	s_nop 0
	v_cvt_pk_bf16_f32 v70, v70, v71
	s_nop 0
	s_nop 0
	s_nop 0
	s_nop 0
	s_nop 0
	v_cvt_pk_bf16_f32 v71, v72, v73
	s_nop 0
	s_nop 0
	s_nop 0
	s_nop 0
	s_nop 0
	v_cvt_pk_bf16_f32 v72, v66, v67
	s_nop 0
	s_nop 0
	s_nop 0
	s_nop 0
	s_nop 0
	s_nop 0
	s_nop 0
	v_cvt_pk_bf16_f32 v62, v62, v63
	s_nop 0
	s_nop 0
	s_nop 0
	s_nop 0
	s_nop 0
	v_cvt_pk_bf16_f32 v63, v64, v65
	s_nop 0
	s_nop 0
	s_nop 0
	s_nop 0
	s_nop 0
	v_cvt_pk_bf16_f32 v64, v58, v59
	s_nop 0
	s_nop 0
	s_nop 0
	s_nop 0
	s_nop 0
	v_cvt_pk_bf16_f32 v65, v60, v61
	s_nop 0
	s_nop 0
	s_nop 0
	s_nop 0
	s_nop 0
	v_cvt_pk_bf16_f32 v54, v54, v55
	s_nop 0
	s_nop 0
	s_nop 0
	s_nop 0
	s_nop 0
	v_cvt_pk_bf16_f32 v55, v56, v57
	s_nop 0
	s_nop 0
	s_nop 0
	s_nop 0
	s_nop 0
	s_nop 0
	v_cvt_pk_bf16_f32 v56, v46, v47
	s_nop 0
	s_nop 0
	s_nop 0
	s_nop 0
	s_nop 0
	v_cvt_pk_bf16_f32 v73, v68, v69
	v_add_u32_e32 v66, 0x80, v155
	s_nop 0
	s_nop 0
	v_mad_i64_i32 v[66:67], s[20:21], v66, s40, v[146:147]
	v_cvt_pk_bf16_f32 v57, v48, v49
	v_add_u32_e32 v46, 0x90, v155
	v_lshl_add_u64 v[66:67], v[66:67], 0, v[148:149]
	v_mad_i64_i32 v[46:47], s[20:21], v46, s40, v[146:147]
	global_store_dwordx4 v[66:67], v[54:57], off offset:256
	s_nop 0
	s_nop 0
	v_lshl_add_u64 v[54:55], v[46:47], 0, v[148:149]
	s_nop 0
	s_nop 0
	s_nop 0
	s_nop 0
	s_nop 0
	v_cvt_pk_bf16_f32 v46, v50, v51
	s_nop 0
	s_nop 0
	s_nop 0
	v_cvt_pk_bf16_f32 v47, v52, v53
	s_nop 0
	s_nop 0
	s_nop 0
	s_nop 0
	s_nop 0
	v_cvt_pk_bf16_f32 v48, v42, v43
	s_nop 0
	s_nop 0
	s_nop 0
	s_nop 0
	s_nop 0
	v_cvt_pk_bf16_f32 v49, v44, v45
	s_nop 0
	s_nop 0
	s_nop 0
	s_nop 0
	s_nop 0
	v_cvt_pk_bf16_f32 v38, v38, v39
	s_nop 0
	s_nop 0
	s_nop 0
	s_nop 0
	s_nop 0
	v_cvt_pk_bf16_f32 v39, v40, v41
	s_nop 0
	s_nop 0
	s_nop 0
	s_nop 0
	s_nop 0
	v_cvt_pk_bf16_f32 v40, v30, v31
	s_nop 0
	s_nop 0
	s_nop 0
	s_nop 0
	s_nop 0
	v_cvt_pk_bf16_f32 v41, v32, v33
	v_add_u32_e32 v30, 0xa0, v155
	v_mad_i64_i32 v[30:31], s[20:21], v30, s40, v[146:147]
	global_store_dwordx4 v[54:55], v[38:41], off offset:256
	s_nop 0
	s_nop 0
	v_lshl_add_u64 v[38:39], v[30:31], 0, v[148:149]
	s_nop 0
	s_nop 0
	s_nop 0
	s_nop 0
	s_nop 0
	v_cvt_pk_bf16_f32 v30, v34, v35
	s_nop 0
	s_nop 0
	s_nop 0
	v_cvt_pk_bf16_f32 v31, v36, v37
	s_nop 0
	s_nop 0
	s_nop 0
	s_nop 0
	s_nop 0
	v_cvt_pk_bf16_f32 v32, v26, v27
	s_nop 0
	s_nop 0
	s_nop 0
	s_nop 0
	s_nop 0
	v_cvt_pk_bf16_f32 v33, v28, v29
	s_nop 0
	s_nop 0
	s_nop 0
	s_nop 0
	s_nop 0
	v_cvt_pk_bf16_f32 v22, v22, v23
	s_nop 0
	s_nop 0
	s_nop 0
	s_nop 0
	s_nop 0
	v_cvt_pk_bf16_f32 v23, v24, v25
	s_nop 0
	s_nop 0
	s_nop 0
	s_nop 0
	s_nop 0
	v_cvt_pk_bf16_f32 v24, v14, v15
	s_nop 0
	s_nop 0
	s_nop 0
	s_nop 0
	s_nop 0
	v_cvt_pk_bf16_f32 v25, v16, v17
	v_add_u32_e32 v14, 0xb0, v155
	v_mad_i64_i32 v[14:15], s[20:21], v14, s40, v[146:147]
	global_store_dwordx4 v[38:39], v[22:25], off offset:256
	s_nop 0
	s_nop 0
	v_lshl_add_u64 v[22:23], v[14:15], 0, v[148:149]
	s_nop 0
	s_nop 0
	s_nop 0
	s_nop 0
	s_nop 0
	v_cvt_pk_bf16_f32 v14, v18, v19
	s_nop 0
	s_nop 0
	s_nop 0
	v_cvt_pk_bf16_f32 v15, v20, v21
	s_nop 0
	s_nop 0
	s_nop 0
	s_nop 0
	s_nop 0
	v_cvt_pk_bf16_f32 v16, v10, v11
	s_nop 0
	s_nop 0
	s_nop 0
	s_nop 0
	s_nop 0
	v_cvt_pk_bf16_f32 v17, v12, v13
	s_nop 0
	s_nop 0
	s_nop 0
	s_nop 0
	s_nop 0
	v_cvt_pk_bf16_f32 v6, v6, v7
	s_nop 0
	s_nop 0
	s_nop 0
	s_nop 0
	s_nop 0
	v_cvt_pk_bf16_f32 v7, v8, v9
	s_nop 0
	s_nop 0
	s_nop 0
	s_nop 0
	s_nop 0
	v_cvt_pk_bf16_f32 v8, v2, v3
	s_nop 0
	s_nop 0
	s_nop 0
	s_nop 0
	s_nop 0
	v_cvt_pk_bf16_f32 v9, v4, v5
	s_andn2_b64 vcc, exec, s[2:3]
	s_mov_b64 s[2:3], -1
	global_store_dwordx4 v[156:157], v[126:129], off
	global_store_dwordx4 v[118:119], v[110:113], off
	global_store_dwordx4 v[102:103], v[94:97], off
	global_store_dwordx4 v[86:87], v[78:81], off
	global_store_dwordx4 v[86:87], v[70:73], off offset:256
	global_store_dwordx4 v[66:67], v[62:65], off
	global_store_dwordx4 v[54:55], v[46:49], off
	global_store_dwordx4 v[38:39], v[30:33], off
	global_store_dwordx4 v[22:23], v[14:17], off
	global_store_dwordx4 v[22:23], v[6:9], off offset:256
	s_cbranch_vccnz .LBB0_208
	s_andn2_b64 vcc, exec, s[4:5]
	s_cbranch_vccnz .LBB0_207
	s_barrier
	s_branch .LBB0_207

.LBB0_369:
	s_or_b64 exec, exec, s[10:11]
	s_waitcnt vmcnt(0)
	v_lshlrev_b32_e32 v169, 16, v72
	v_lshlrev_b32_e32 v47, 16, v71
	v_lshlrev_b32_e32 v177, 16, v46
	v_and_b32_e32 v178, 0xffff0000, v46
	v_sub_f32_e32 v46, v47, v169
	v_and_b32_e32 v176, 0xffff0000, v72
	v_and_b32_e32 v71, 0xffff0000, v71
	v_fma_f32 v46, v4, v46, v169
	v_sub_f32_e32 v47, v177, v169
	v_fmac_f32_e32 v46, v6, v47
	v_sub_f32_e32 v47, v71, v176
	v_fma_f32 v47, v5, v47, v176
	v_sub_f32_e32 v71, v178, v176
	v_mul_f32_e32 v46, 0xbfb8aa3b, v46
	v_fmac_f32_e32 v47, v7, v71
	v_exp_f32_e32 v46, v46
	v_mul_f32_e32 v47, 0xbfb8aa3b, v47
	v_exp_f32_e32 v47, v47
	v_add3_u32 v144, v131, v130, v13
	v_add_f32_e32 v46, 1.0, v46
	v_rcp_f32_e32 v46, v46
	v_add_f32_e32 v47, 1.0, v47
	v_rcp_f32_e32 v47, v47
	v_add3_u32 v145, v129, v130, v13
	s_nop 0
	s_nop 0
	s_nop 0
	v_and_b32_e32 v101, 0xffff0000, v48
	v_lshlrev_b32_e32 v100, 16, v48
	v_add_u32_e32 v48, 8, v144
	v_add_u32_e32 v13, 8, v145
	s_nop 0
	s_nop 0
	v_max_i32_e32 v48, 0, v48
	v_min_i32_e32 v13, v13, v136
	v_cvt_pk_bf16_f32 v72, v46, v47
	v_mov_b64_e32 v[46:47], s[62:63]
	v_sub_u32_e32 v13, v13, v48
	v_mad_i64_i32 v[170:171], s[10:11], v70, s1, v[46:47]
	v_cvt_f32_i32_e32 v13, v13
	v_lshl_add_u64 v[70:71], v[170:171], 0, v[2:3]
	global_store_dword v[70:71], v72, off
	v_pk_add_f32 v[172:173], v[42:43], 0 op_sel_hi:[1,0]
	v_pk_add_f32 v[174:175], v[44:45], 0 op_sel_hi:[1,0]
	v_and_b32_e32 v95, 0xffff0000, v58
	v_lshlrev_b32_e32 v94, 16, v58
	v_and_b32_e32 v97, 0xffff0000, v59
	v_lshlrev_b32_e32 v96, 16, v59
	v_and_b32_e32 v89, 0xffff0000, v56
	v_lshlrev_b32_e32 v88, 16, v56
	v_and_b32_e32 v91, 0xffff0000, v57
	v_lshlrev_b32_e32 v90, 16, v57
	v_and_b32_e32 v71, 0xffff0000, v122
	v_lshlrev_b32_e32 v70, 16, v122
	v_and_b32_e32 v73, 0xffff0000, v123
	v_lshlrev_b32_e32 v72, 16, v123
	v_and_b32_e32 v57, 0xffff0000, v118
	v_lshlrev_b32_e32 v56, 16, v118
	v_and_b32_e32 v59, 0xffff0000, v119
	v_lshlrev_b32_e32 v58, 16, v119
	v_lshlrev_b32_e32 v118, 16, v120
	v_lshlrev_b32_e32 v122, 16, v121
	v_and_b32_e32 v119, 0xffff0000, v120
	v_and_b32_e32 v123, 0xffff0000, v121
	v_pk_add_f32 v[120:121], v[174:175], v[122:123]
	v_pk_add_f32 v[172:173], v[172:173], v[118:119]
	v_and_b32_e32 v111, 0xffff0000, v52
	v_lshlrev_b32_e32 v110, 16, v52
	v_and_b32_e32 v113, 0xffff0000, v53
	v_lshlrev_b32_e32 v112, 16, v53
	v_and_b32_e32 v103, 0xffff0000, v49
	v_lshlrev_b32_e32 v102, 16, v49
	v_and_b32_e32 v49, 0xffff0000, v126
	v_lshlrev_b32_e32 v48, 16, v126
	v_and_b32_e32 v53, 0xffff0000, v127
	v_lshlrev_b32_e32 v52, 16, v127
	v_rcp_iflag_f32_e32 v126, v13
	v_cndmask_b32_e64 v13, 0, v172, s[4:5]
	v_cndmask_b32_e64 v127, 0, v120, s[4:5]
	v_cndmask_b32_e64 v174, 0, v173, s[4:5]
	v_cndmask_b32_e64 v175, 0, v121, s[4:5]
	v_pk_add_f32 v[120:121], v[120:121], v[54:55]
	v_pk_add_f32 v[172:173], v[172:173], v[50:51]
	v_pk_add_f32 v[120:121], v[120:121], v[112:113]
	v_pk_add_f32 v[172:173], v[172:173], v[110:111]
	v_cndmask_b32_e64 v175, v175, v121, s[6:7]
	v_cndmask_b32_e64 v174, v174, v173, s[6:7]
	v_cndmask_b32_e64 v127, v127, v120, s[6:7]
	v_cndmask_b32_e64 v13, v13, v172, s[6:7]
	v_pk_add_f32 v[172:173], v[172:173], v[64:65]
	v_pk_add_f32 v[120:121], v[120:121], v[74:75]
	v_pk_add_f32 v[172:173], v[172:173], v[60:61]
	v_pk_add_f32 v[120:121], v[120:121], v[62:63]
	v_pk_add_f32 v[172:173], v[172:173], v[100:101]
	v_pk_add_f32 v[120:121], v[120:121], v[102:103]
	v_pk_add_f32 v[172:173], v[172:173], v[94:95]
	v_pk_add_f32 v[120:121], v[120:121], v[96:97]
	v_pk_add_f32 v[104:105], v[172:173], v[104:105]
	v_pk_add_f32 v[106:107], v[120:121], v[106:107]
	v_pk_add_f32 v[104:105], v[104:105], v[66:67]
	v_pk_add_f32 v[106:107], v[106:107], v[68:69]
	v_pk_add_f32 v[104:105], v[104:105], v[82:83]
	v_pk_add_f32 v[106:107], v[106:107], v[86:87]
	v_pk_add_f32 v[104:105], v[104:105], v[80:81]
	v_pk_add_f32 v[106:107], v[106:107], v[84:85]
	v_pk_add_f32 v[104:105], v[104:105], v[88:89]
	v_pk_add_f32 v[106:107], v[106:107], v[90:91]
	v_pk_add_f32 v[104:105], v[104:105], v[70:71]
	v_pk_add_f32 v[106:107], v[106:107], v[72:73]
	v_pk_add_f32 v[104:105], v[104:105], v[56:57]
	v_pk_add_f32 v[106:107], v[106:107], v[58:59]
	v_cndmask_b32_e64 v13, v13, v172, s[8:9]
	v_cndmask_b32_e64 v127, v127, v120, s[8:9]
	v_cndmask_b32_e64 v174, v174, v173, s[8:9]
	v_cndmask_b32_e64 v175, v175, v121, s[8:9]
	v_pk_add_f32 v[104:105], v[104:105], v[48:49]
	v_pk_add_f32 v[106:107], v[106:107], v[52:53]
	v_cndmask_b32_e64 v120, v174, v105, s[2:3]
	v_cndmask_b32_e64 v121, v175, v107, s[2:3]
	v_cndmask_b32_e64 v105, v127, v106, s[2:3]
	v_cndmask_b32_e64 v104, v13, v104, s[2:3]
	v_mov_b32_e32 v106, v118
	v_mov_b32_e32 v107, v122
	v_pk_fma_f32 v[104:105], v[126:127], v[104:105], v[106:107] op_sel_hi:[0,1,1] neg_lo:[0,0,1] neg_hi:[0,0,1]
	v_mov_b32_e32 v106, v119
	v_mov_b32_e32 v107, v123
	v_pk_fma_f32 v[106:107], v[126:127], v[120:121], v[106:107] op_sel_hi:[0,1,1] neg_lo:[0,0,1] neg_hi:[0,0,1]
	v_and_b32_sdwa v120, v104, v135 dst_sel:DWORD dst_unused:UNUSED_PAD src0_sel:WORD_1 src1_sel:DWORD
	v_add3_u32 v104, v104, v120, s0
	v_and_b32_sdwa v120, v106, v135 dst_sel:DWORD dst_unused:UNUSED_PAD src0_sel:WORD_1 src1_sel:DWORD
	v_add3_u32 v106, v106, v120, s0
	v_lshlrev_b32_e32 v127, 16, v168
	v_sub_f32_e32 v120, v169, v177
	v_fma_f32 v120, v4, v120, v177
	v_sub_f32_e32 v121, v127, v177
	v_and_b32_e32 v168, 0xffff0000, v168
	v_fmac_f32_e32 v120, v6, v121
	v_sub_f32_e32 v121, v176, v178
	v_fma_f32 v121, v5, v121, v178
	v_sub_f32_e32 v126, v168, v178
	v_and_b32_sdwa v13, v105, v135 dst_sel:DWORD dst_unused:UNUSED_PAD src0_sel:WORD_1 src1_sel:DWORD
	v_mul_f32_e32 v120, 0xbfb8aa3b, v120
	v_fmac_f32_e32 v121, v7, v126
	v_add3_u32 v13, v105, v13, s0
	v_and_b32_sdwa v105, v107, v135 dst_sel:DWORD dst_unused:UNUSED_PAD src0_sel:WORD_1 src1_sel:DWORD
	v_exp_f32_e32 v120, v120
	v_mul_f32_e32 v121, 0xbfb8aa3b, v121
	v_add3_u32 v105, v107, v105, s0
	v_exp_f32_e32 v121, v121
	v_and_b32_e32 v105, 0xffff0000, v105
	v_and_b32_e32 v106, 0xffff0000, v106
	v_or_b32_sdwa v105, v105, v13 dst_sel:DWORD dst_unused:UNUSED_PAD src0_sel:DWORD src1_sel:WORD_1
	v_mov_b32_e32 v13, v3
	v_or_b32_sdwa v104, v106, v104 dst_sel:DWORD dst_unused:UNUSED_PAD src0_sel:DWORD src1_sel:WORD_1
	v_lshl_add_u64 v[106:107], v[170:171], 0, v[12:13]
	v_add_f32_e32 v120, 1.0, v120
	v_rcp_f32_e32 v120, v120
	global_store_dwordx2 v[106:107], v[104:105], off offset:256
	v_add_f32_e32 v104, 1.0, v121
	v_rcp_f32_e32 v104, v104
	s_nop 0
	s_nop 0
	s_nop 0
	s_nop 0
	s_nop 0
	v_cvt_pk_bf16_f32 v120, v120, v104
	v_mad_i64_i32 v[104:105], s[10:11], v161, s1, v[46:47]
	v_lshl_add_u64 v[106:107], v[104:105], 0, v[2:3]
	global_store_dword v[106:107], v120, off
	v_pk_add_f32 v[106:107], v[118:119], 0 op_sel_hi:[1,0]
	v_pk_add_f32 v[120:121], v[122:123], 0 op_sel_hi:[1,0]
	v_pk_add_f32 v[106:107], v[106:107], v[110:111]
	v_pk_add_f32 v[120:121], v[120:121], v[112:113]
	v_cndmask_b32_e64 v126, 0, v106, s[4:5]
	v_cndmask_b32_e64 v161, 0, v120, s[4:5]
	v_cndmask_b32_e64 v169, 0, v107, s[4:5]
	v_cndmask_b32_e64 v170, 0, v121, s[4:5]
	v_pk_add_f32 v[120:121], v[120:121], v[44:45]
	v_pk_add_f32 v[106:107], v[106:107], v[42:43]
	v_pk_add_f32 v[120:121], v[120:121], v[102:103]
	v_pk_add_f32 v[106:107], v[106:107], v[100:101]
	v_cndmask_b32_e64 v170, v170, v121, s[6:7]
	v_cndmask_b32_e64 v169, v169, v107, s[6:7]
	v_cndmask_b32_e64 v161, v161, v120, s[6:7]
	v_cndmask_b32_e64 v126, v126, v106, s[6:7]
	v_pk_add_f32 v[106:107], v[106:107], v[60:61]
	v_pk_add_f32 v[120:121], v[120:121], v[62:63]
	v_pk_add_f32 v[106:107], v[106:107], v[50:51]
	v_pk_add_f32 v[120:121], v[120:121], v[54:55]
	v_pk_add_f32 v[106:107], v[106:107], v[94:95]
	v_pk_add_f32 v[120:121], v[120:121], v[96:97]
	v_pk_add_f32 v[106:107], v[106:107], v[88:89]
	v_pk_add_f32 v[120:121], v[120:121], v[90:91]
	v_pk_add_f32 v[66:67], v[106:107], v[66:67]
	v_pk_add_f32 v[68:69], v[120:121], v[68:69]
	v_pk_add_f32 v[66:67], v[66:67], v[82:83]
	v_pk_add_f32 v[68:69], v[68:69], v[86:87]
	v_pk_add_f32 v[66:67], v[66:67], v[80:81]
	v_pk_add_f32 v[68:69], v[68:69], v[84:85]
	v_pk_add_f32 v[66:67], v[66:67], v[64:65]
	v_pk_add_f32 v[68:69], v[68:69], v[74:75]
	v_pk_add_f32 v[66:67], v[66:67], v[70:71]
	v_pk_add_f32 v[68:69], v[68:69], v[72:73]
	v_pk_add_f32 v[66:67], v[66:67], v[56:57]
	v_pk_add_f32 v[68:69], v[68:69], v[58:59]
	v_cndmask_b32_e64 v171, v126, v106, s[8:9]
	v_cndmask_b32_e64 v126, v161, v120, s[8:9]
	v_cndmask_b32_e64 v161, v169, v107, s[8:9]
	v_cndmask_b32_e64 v169, v170, v121, s[8:9]
	v_pk_add_f32 v[106:107], v[68:69], v[52:53]
	v_pk_add_f32 v[120:121], v[66:67], v[48:49]
	v_and_b32_e32 v67, 0xffff0000, v124
	v_lshlrev_b32_e32 v66, 16, v124
	v_and_b32_e32 v69, 0xffff0000, v125
	v_lshlrev_b32_e32 v68, 16, v125
	v_add_u32_e32 v124, 9, v144
	v_add_u32_e32 v125, 9, v145
	v_max_i32_e32 v124, 0, v124
	v_min_i32_e32 v125, v125, v136
	v_sub_u32_e32 v124, v125, v124
	v_cvt_f32_i32_e32 v170, v124
	v_pk_add_f32 v[106:107], v[106:107], v[68:69]
	v_pk_add_f32 v[120:121], v[120:121], v[66:67]
	v_cndmask_b32_e64 v125, v169, v107, s[2:3]
	v_cndmask_b32_e64 v107, v126, v106, s[2:3]
	v_rcp_iflag_f32_e32 v126, v170
	v_cndmask_b32_e64 v124, v161, v121, s[2:3]
	v_cndmask_b32_e64 v106, v171, v120, s[2:3]
	v_mov_b32_e32 v120, v110
	v_mov_b32_e32 v121, v112
	v_pk_fma_f32 v[106:107], v[126:127], v[106:107], v[120:121] op_sel_hi:[0,1,1] neg_lo:[0,0,1] neg_hi:[0,0,1]
	v_mov_b32_e32 v120, v111
	v_mov_b32_e32 v121, v113
	v_pk_fma_f32 v[120:121], v[126:127], v[124:125], v[120:121] op_sel_hi:[0,1,1] neg_lo:[0,0,1] neg_hi:[0,0,1]
	v_and_b32_sdwa v125, v106, v135 dst_sel:DWORD dst_unused:UNUSED_PAD src0_sel:WORD_1 src1_sel:DWORD
	v_and_b32_sdwa v124, v107, v135 dst_sel:DWORD dst_unused:UNUSED_PAD src0_sel:WORD_1 src1_sel:DWORD
	v_add3_u32 v106, v106, v125, s0
	v_and_b32_sdwa v125, v120, v135 dst_sel:DWORD dst_unused:UNUSED_PAD src0_sel:WORD_1 src1_sel:DWORD
	v_add3_u32 v107, v107, v124, s0
	v_and_b32_sdwa v124, v121, v135 dst_sel:DWORD dst_unused:UNUSED_PAD src0_sel:WORD_1 src1_sel:DWORD
	v_add3_u32 v120, v120, v125, s0
	v_add3_u32 v121, v121, v124, s0
	v_and_b32_e32 v120, 0xffff0000, v120
	v_and_b32_e32 v121, 0xffff0000, v121
	v_or_b32_sdwa v106, v120, v106 dst_sel:DWORD dst_unused:UNUSED_PAD src0_sel:DWORD src1_sel:WORD_1
	v_lshlrev_b32_e32 v125, 16, v167
	v_sub_f32_e32 v120, v177, v127
	v_or_b32_sdwa v107, v121, v107 dst_sel:DWORD dst_unused:UNUSED_PAD src0_sel:DWORD src1_sel:WORD_1
	v_fma_f32 v120, v4, v120, v127
	v_sub_f32_e32 v121, v125, v127
	v_and_b32_e32 v126, 0xffff0000, v167
	v_fmac_f32_e32 v120, v6, v121
	v_sub_f32_e32 v121, v178, v168
	v_fma_f32 v121, v5, v121, v168
	v_sub_f32_e32 v124, v126, v168
	v_mul_f32_e32 v120, 0xbfb8aa3b, v120
	v_fmac_f32_e32 v121, v7, v124
	v_exp_f32_e32 v120, v120
	v_mul_f32_e32 v121, 0xbfb8aa3b, v121
	v_exp_f32_e32 v121, v121
	v_lshl_add_u64 v[104:105], v[104:105], 0, v[12:13]
	v_add_f32_e32 v120, 1.0, v120
	v_rcp_f32_e32 v120, v120
	global_store_dwordx2 v[104:105], v[106:107], off offset:256
	v_add_f32_e32 v104, 1.0, v121
	v_rcp_f32_e32 v104, v104
	s_nop 0
	s_nop 0
	s_nop 0
	s_nop 0
	s_nop 0
	v_cvt_pk_bf16_f32 v120, v120, v104
	v_mad_i64_i32 v[104:105], s[10:11], v159, s1, v[46:47]
	v_lshl_add_u64 v[106:107], v[104:105], 0, v[2:3]
	global_store_dword v[106:107], v120, off
	v_pk_add_f32 v[106:107], v[110:111], 0 op_sel_hi:[1,0]
	v_pk_add_f32 v[120:121], v[112:113], 0 op_sel_hi:[1,0]
	v_pk_add_f32 v[106:107], v[106:107], v[100:101]
	v_pk_add_f32 v[120:121], v[120:121], v[102:103]
	v_cndmask_b32_e64 v124, 0, v106, s[4:5]
	v_cndmask_b32_e64 v161, 0, v107, s[4:5]
	v_pk_add_f32 v[106:107], v[106:107], v[118:119]
	v_cndmask_b32_e64 v159, 0, v120, s[4:5]
	v_cndmask_b32_e64 v167, 0, v121, s[4:5]
	v_pk_add_f32 v[120:121], v[120:121], v[122:123]
	v_pk_add_f32 v[106:107], v[106:107], v[94:95]
	v_pk_add_f32 v[120:121], v[120:121], v[96:97]
	v_cndmask_b32_e64 v161, v161, v107, s[6:7]
	v_cndmask_b32_e64 v124, v124, v106, s[6:7]
	v_pk_add_f32 v[106:107], v[106:107], v[50:51]
	v_cndmask_b32_e64 v167, v167, v121, s[6:7]
	v_cndmask_b32_e64 v159, v159, v120, s[6:7]
	v_pk_add_f32 v[120:121], v[120:121], v[54:55]
	v_pk_add_f32 v[106:107], v[106:107], v[42:43]
	v_pk_add_f32 v[120:121], v[120:121], v[44:45]
	v_pk_add_f32 v[106:107], v[106:107], v[88:89]
	v_pk_add_f32 v[120:121], v[120:121], v[90:91]
	v_pk_add_f32 v[106:107], v[106:107], v[70:71]
	v_pk_add_f32 v[120:121], v[120:121], v[72:73]
	v_pk_add_f32 v[82:83], v[106:107], v[82:83]
	v_pk_add_f32 v[86:87], v[120:121], v[86:87]
	v_pk_add_f32 v[82:83], v[82:83], v[80:81]
	v_pk_add_f32 v[86:87], v[86:87], v[84:85]
	v_pk_add_f32 v[82:83], v[82:83], v[64:65]
	v_pk_add_f32 v[86:87], v[86:87], v[74:75]
	v_pk_add_f32 v[82:83], v[82:83], v[60:61]
	v_pk_add_f32 v[86:87], v[86:87], v[62:63]
	v_pk_add_f32 v[82:83], v[82:83], v[56:57]
	v_pk_add_f32 v[86:87], v[86:87], v[58:59]
	v_pk_add_f32 v[82:83], v[82:83], v[48:49]
	v_cndmask_b32_e64 v169, v124, v106, s[8:9]
	v_cndmask_b32_e64 v124, v159, v120, s[8:9]
	v_cndmask_b32_e64 v159, v161, v107, s[8:9]
	v_cndmask_b32_e64 v161, v167, v121, s[8:9]
	v_pk_add_f32 v[86:87], v[86:87], v[52:53]
	v_pk_add_f32 v[120:121], v[82:83], v[66:67]
	v_and_b32_e32 v83, 0xffff0000, v116
	v_lshlrev_b32_e32 v82, 16, v116
	v_pk_add_f32 v[106:107], v[86:87], v[68:69]
	v_and_b32_e32 v87, 0xffff0000, v117
	v_lshlrev_b32_e32 v86, 16, v117
	v_pk_add_f32 v[116:117], v[120:121], v[82:83]
	v_add_u32_e32 v120, 10, v144
	v_add_u32_e32 v121, 10, v145
	v_max_i32_e32 v120, 0, v120
	v_min_i32_e32 v121, v121, v136
	v_sub_u32_e32 v120, v121, v120
	v_cvt_f32_i32_e32 v167, v120
	v_pk_add_f32 v[106:107], v[106:107], v[86:87]
	v_cndmask_b32_e64 v120, v159, v117, s[2:3]
	v_cndmask_b32_e64 v121, v161, v107, s[2:3]
	v_cndmask_b32_e64 v107, v124, v106, s[2:3]
	v_rcp_iflag_f32_e32 v124, v167
	v_cndmask_b32_e64 v106, v169, v116, s[2:3]
	v_mov_b32_e32 v116, v100
	v_mov_b32_e32 v117, v102
	v_pk_fma_f32 v[106:107], v[124:125], v[106:107], v[116:117] op_sel_hi:[0,1,1] neg_lo:[0,0,1] neg_hi:[0,0,1]
	v_mov_b32_e32 v116, v101
	v_mov_b32_e32 v117, v103
	v_pk_fma_f32 v[116:117], v[124:125], v[120:121], v[116:117] op_sel_hi:[0,1,1] neg_lo:[0,0,1] neg_hi:[0,0,1]
	v_and_b32_sdwa v121, v106, v135 dst_sel:DWORD dst_unused:UNUSED_PAD src0_sel:WORD_1 src1_sel:DWORD
	v_and_b32_sdwa v120, v107, v135 dst_sel:DWORD dst_unused:UNUSED_PAD src0_sel:WORD_1 src1_sel:DWORD
	v_add3_u32 v106, v106, v121, s0
	v_and_b32_sdwa v121, v116, v135 dst_sel:DWORD dst_unused:UNUSED_PAD src0_sel:WORD_1 src1_sel:DWORD
	v_add3_u32 v107, v107, v120, s0
	v_and_b32_sdwa v120, v117, v135 dst_sel:DWORD dst_unused:UNUSED_PAD src0_sel:WORD_1 src1_sel:DWORD
	v_add3_u32 v116, v116, v121, s0
	v_add3_u32 v117, v117, v120, s0
	v_and_b32_e32 v116, 0xffff0000, v116
	v_and_b32_e32 v117, 0xffff0000, v117
	v_or_b32_sdwa v106, v116, v106 dst_sel:DWORD dst_unused:UNUSED_PAD src0_sel:DWORD src1_sel:WORD_1
	v_lshlrev_b32_e32 v121, 16, v166
	v_sub_f32_e32 v116, v127, v125
	v_or_b32_sdwa v107, v117, v107 dst_sel:DWORD dst_unused:UNUSED_PAD src0_sel:DWORD src1_sel:WORD_1
	v_fma_f32 v116, v4, v116, v125
	v_sub_f32_e32 v117, v121, v125
	v_and_b32_e32 v124, 0xffff0000, v166
	v_fmac_f32_e32 v116, v6, v117
	v_sub_f32_e32 v117, v168, v126
	v_fma_f32 v117, v5, v117, v126
	v_sub_f32_e32 v120, v124, v126
	v_mul_f32_e32 v116, 0xbfb8aa3b, v116
	v_fmac_f32_e32 v117, v7, v120
	v_exp_f32_e32 v116, v116
	v_mul_f32_e32 v117, 0xbfb8aa3b, v117
	v_exp_f32_e32 v117, v117
	v_lshl_add_u64 v[104:105], v[104:105], 0, v[12:13]
	v_add_f32_e32 v116, 1.0, v116
	v_rcp_f32_e32 v116, v116
	global_store_dwordx2 v[104:105], v[106:107], off offset:256
	v_add_f32_e32 v104, 1.0, v117
	v_rcp_f32_e32 v104, v104
	s_nop 0
	s_nop 0
	s_nop 0
	s_nop 0
	s_nop 0
	v_cvt_pk_bf16_f32 v116, v116, v104
	v_mad_i64_i32 v[104:105], s[10:11], v157, s1, v[46:47]
	v_lshl_add_u64 v[106:107], v[104:105], 0, v[2:3]
	global_store_dword v[106:107], v116, off
	v_pk_add_f32 v[106:107], v[100:101], 0 op_sel_hi:[1,0]
	v_pk_add_f32 v[116:117], v[102:103], 0 op_sel_hi:[1,0]
	v_pk_add_f32 v[106:107], v[106:107], v[94:95]
	v_pk_add_f32 v[116:117], v[116:117], v[96:97]
	v_cndmask_b32_e64 v120, 0, v106, s[4:5]
	v_cndmask_b32_e64 v157, 0, v107, s[4:5]
	v_pk_add_f32 v[106:107], v[106:107], v[110:111]
	v_cndmask_b32_e64 v127, 0, v116, s[4:5]
	v_cndmask_b32_e64 v159, 0, v117, s[4:5]
	v_pk_add_f32 v[116:117], v[116:117], v[112:113]
	v_pk_add_f32 v[106:107], v[106:107], v[88:89]
	v_pk_add_f32 v[116:117], v[116:117], v[90:91]
	v_cndmask_b32_e64 v157, v157, v107, s[6:7]
	v_cndmask_b32_e64 v120, v120, v106, s[6:7]
	v_pk_add_f32 v[106:107], v[106:107], v[42:43]
	v_cndmask_b32_e64 v159, v159, v117, s[6:7]
	v_cndmask_b32_e64 v127, v127, v116, s[6:7]
	v_pk_add_f32 v[116:117], v[116:117], v[44:45]
	v_pk_add_f32 v[106:107], v[106:107], v[118:119]
	v_pk_add_f32 v[116:117], v[116:117], v[122:123]
	v_pk_add_f32 v[106:107], v[106:107], v[70:71]
	v_pk_add_f32 v[116:117], v[116:117], v[72:73]
	v_pk_add_f32 v[106:107], v[106:107], v[56:57]
	v_pk_add_f32 v[116:117], v[116:117], v[58:59]
	v_pk_add_f32 v[80:81], v[106:107], v[80:81]
	v_pk_add_f32 v[84:85], v[116:117], v[84:85]
	v_pk_add_f32 v[80:81], v[80:81], v[64:65]
	v_pk_add_f32 v[84:85], v[84:85], v[74:75]
	v_pk_add_f32 v[80:81], v[80:81], v[60:61]
	v_pk_add_f32 v[84:85], v[84:85], v[62:63]
	v_pk_add_f32 v[80:81], v[80:81], v[50:51]
	v_pk_add_f32 v[84:85], v[84:85], v[54:55]
	v_pk_add_f32 v[80:81], v[80:81], v[48:49]
	v_pk_add_f32 v[84:85], v[84:85], v[52:53]
	v_pk_add_f32 v[80:81], v[80:81], v[66:67]
	v_cndmask_b32_e64 v161, v120, v106, s[8:9]
	v_cndmask_b32_e64 v120, v127, v116, s[8:9]
	v_cndmask_b32_e64 v127, v157, v107, s[8:9]
	v_cndmask_b32_e64 v157, v159, v117, s[8:9]
	v_pk_add_f32 v[84:85], v[84:85], v[68:69]
	v_pk_add_f32 v[116:117], v[80:81], v[82:83]
	v_and_b32_e32 v81, 0xffff0000, v114
	v_lshlrev_b32_e32 v80, 16, v114
	v_pk_add_f32 v[106:107], v[84:85], v[86:87]
	v_and_b32_e32 v85, 0xffff0000, v115
	v_lshlrev_b32_e32 v84, 16, v115
	v_pk_add_f32 v[114:115], v[116:117], v[80:81]
	v_add_u32_e32 v116, 11, v144
	v_add_u32_e32 v117, 11, v145
	v_max_i32_e32 v116, 0, v116
	v_min_i32_e32 v117, v117, v136
	v_sub_u32_e32 v116, v117, v116
	v_cvt_f32_i32_e32 v159, v116
	v_pk_add_f32 v[106:107], v[106:107], v[84:85]
	v_cndmask_b32_e64 v116, v127, v115, s[2:3]
	v_cndmask_b32_e64 v117, v157, v107, s[2:3]
	v_cndmask_b32_e64 v107, v120, v106, s[2:3]
	v_rcp_iflag_f32_e32 v120, v159
	v_cndmask_b32_e64 v106, v161, v114, s[2:3]
	v_mov_b32_e32 v114, v94
	v_mov_b32_e32 v115, v96
	v_pk_fma_f32 v[106:107], v[120:121], v[106:107], v[114:115] op_sel_hi:[0,1,1] neg_lo:[0,0,1] neg_hi:[0,0,1]
	v_mov_b32_e32 v114, v95
	v_mov_b32_e32 v115, v97
	v_pk_fma_f32 v[114:115], v[120:121], v[116:117], v[114:115] op_sel_hi:[0,1,1] neg_lo:[0,0,1] neg_hi:[0,0,1]
	v_and_b32_sdwa v117, v106, v135 dst_sel:DWORD dst_unused:UNUSED_PAD src0_sel:WORD_1 src1_sel:DWORD
	v_and_b32_sdwa v116, v107, v135 dst_sel:DWORD dst_unused:UNUSED_PAD src0_sel:WORD_1 src1_sel:DWORD
	v_add3_u32 v106, v106, v117, s0
	v_and_b32_sdwa v117, v114, v135 dst_sel:DWORD dst_unused:UNUSED_PAD src0_sel:WORD_1 src1_sel:DWORD
	v_add3_u32 v107, v107, v116, s0
	v_and_b32_sdwa v116, v115, v135 dst_sel:DWORD dst_unused:UNUSED_PAD src0_sel:WORD_1 src1_sel:DWORD
	v_add3_u32 v114, v114, v117, s0
	v_add3_u32 v115, v115, v116, s0
	v_and_b32_e32 v114, 0xffff0000, v114
	v_and_b32_e32 v115, 0xffff0000, v115
	v_or_b32_sdwa v106, v114, v106 dst_sel:DWORD dst_unused:UNUSED_PAD src0_sel:DWORD src1_sel:WORD_1
	v_lshlrev_b32_e32 v117, 16, v165
	v_sub_f32_e32 v114, v125, v121
	v_or_b32_sdwa v107, v115, v107 dst_sel:DWORD dst_unused:UNUSED_PAD src0_sel:DWORD src1_sel:WORD_1
	v_fma_f32 v114, v4, v114, v121
	v_sub_f32_e32 v115, v117, v121
	v_and_b32_e32 v120, 0xffff0000, v165
	v_fmac_f32_e32 v114, v6, v115
	v_sub_f32_e32 v115, v126, v124
	v_fma_f32 v115, v5, v115, v124
	v_sub_f32_e32 v116, v120, v124
	v_mul_f32_e32 v114, 0xbfb8aa3b, v114
	v_fmac_f32_e32 v115, v7, v116
	v_exp_f32_e32 v114, v114
	v_mul_f32_e32 v115, 0xbfb8aa3b, v115
	v_exp_f32_e32 v115, v115
	v_lshl_add_u64 v[104:105], v[104:105], 0, v[12:13]
	v_add_f32_e32 v114, 1.0, v114
	v_rcp_f32_e32 v114, v114
	global_store_dwordx2 v[104:105], v[106:107], off offset:256
	v_add_f32_e32 v104, 1.0, v115
	v_rcp_f32_e32 v104, v104
	s_nop 0
	s_nop 0
	s_nop 0
	s_nop 0
	s_nop 0
	v_cvt_pk_bf16_f32 v114, v114, v104
	v_mad_i64_i32 v[104:105], s[10:11], v156, s1, v[46:47]
	v_lshl_add_u64 v[106:107], v[104:105], 0, v[2:3]
	global_store_dword v[106:107], v114, off
	v_pk_add_f32 v[106:107], v[94:95], 0 op_sel_hi:[1,0]
	v_pk_add_f32 v[114:115], v[96:97], 0 op_sel_hi:[1,0]
	v_pk_add_f32 v[106:107], v[106:107], v[88:89]
	v_pk_add_f32 v[114:115], v[114:115], v[90:91]
	v_cndmask_b32_e64 v116, 0, v106, s[4:5]
	v_cndmask_b32_e64 v126, 0, v107, s[4:5]
	v_pk_add_f32 v[106:107], v[106:107], v[100:101]
	v_cndmask_b32_e64 v125, 0, v114, s[4:5]
	v_cndmask_b32_e64 v127, 0, v115, s[4:5]
	v_pk_add_f32 v[114:115], v[114:115], v[102:103]
	v_pk_add_f32 v[106:107], v[106:107], v[70:71]
	v_pk_add_f32 v[114:115], v[114:115], v[72:73]
	v_cndmask_b32_e64 v126, v126, v107, s[6:7]
	v_cndmask_b32_e64 v116, v116, v106, s[6:7]
	v_pk_add_f32 v[106:107], v[106:107], v[118:119]
	v_cndmask_b32_e64 v127, v127, v115, s[6:7]
	v_cndmask_b32_e64 v125, v125, v114, s[6:7]
	v_pk_add_f32 v[114:115], v[114:115], v[122:123]
	v_pk_add_f32 v[106:107], v[106:107], v[110:111]
	v_pk_add_f32 v[114:115], v[114:115], v[112:113]
	v_pk_add_f32 v[106:107], v[106:107], v[56:57]
	v_pk_add_f32 v[114:115], v[114:115], v[58:59]
	v_pk_add_f32 v[106:107], v[106:107], v[48:49]
	v_pk_add_f32 v[114:115], v[114:115], v[52:53]
	v_pk_add_f32 v[64:65], v[106:107], v[64:65]
	v_pk_add_f32 v[74:75], v[114:115], v[74:75]
	v_pk_add_f32 v[64:65], v[64:65], v[60:61]
	v_pk_add_f32 v[74:75], v[74:75], v[62:63]
	v_pk_add_f32 v[64:65], v[64:65], v[50:51]
	v_pk_add_f32 v[74:75], v[74:75], v[54:55]
	v_pk_add_f32 v[64:65], v[64:65], v[42:43]
	v_pk_add_f32 v[74:75], v[74:75], v[44:45]
	v_pk_add_f32 v[64:65], v[64:65], v[66:67]
	v_pk_add_f32 v[74:75], v[74:75], v[68:69]
	v_pk_add_f32 v[64:65], v[64:65], v[82:83]
	v_cndmask_b32_e64 v156, v116, v106, s[8:9]
	v_cndmask_b32_e64 v116, v125, v114, s[8:9]
	v_cndmask_b32_e64 v125, v126, v107, s[8:9]
	v_cndmask_b32_e64 v126, v127, v115, s[8:9]
	v_pk_add_f32 v[74:75], v[74:75], v[86:87]
	v_pk_add_f32 v[114:115], v[64:65], v[80:81]
	v_and_b32_e32 v65, 0xffff0000, v108
	v_lshlrev_b32_e32 v64, 16, v108
	v_pk_add_f32 v[106:107], v[74:75], v[84:85]
	v_and_b32_e32 v75, 0xffff0000, v109
	v_lshlrev_b32_e32 v74, 16, v109
	v_pk_add_f32 v[108:109], v[114:115], v[64:65]
	v_add_u32_e32 v114, 12, v144
	v_add_u32_e32 v115, 12, v145
	v_max_i32_e32 v114, 0, v114
	v_min_i32_e32 v115, v115, v136
	v_sub_u32_e32 v114, v115, v114
	v_cvt_f32_i32_e32 v127, v114
	v_pk_add_f32 v[106:107], v[106:107], v[74:75]
	v_cndmask_b32_e64 v114, v125, v109, s[2:3]
	v_cndmask_b32_e64 v115, v126, v107, s[2:3]
	v_cndmask_b32_e64 v107, v116, v106, s[2:3]
	v_rcp_iflag_f32_e32 v116, v127
	v_cndmask_b32_e64 v106, v156, v108, s[2:3]
	v_mov_b32_e32 v108, v88
	v_mov_b32_e32 v109, v90
	v_pk_fma_f32 v[106:107], v[116:117], v[106:107], v[108:109] op_sel_hi:[0,1,1] neg_lo:[0,0,1] neg_hi:[0,0,1]
	v_mov_b32_e32 v108, v89
	v_mov_b32_e32 v109, v91
	v_pk_fma_f32 v[108:109], v[116:117], v[114:115], v[108:109] op_sel_hi:[0,1,1] neg_lo:[0,0,1] neg_hi:[0,0,1]
	v_and_b32_sdwa v115, v106, v135 dst_sel:DWORD dst_unused:UNUSED_PAD src0_sel:WORD_1 src1_sel:DWORD
	v_and_b32_sdwa v114, v107, v135 dst_sel:DWORD dst_unused:UNUSED_PAD src0_sel:WORD_1 src1_sel:DWORD
	v_add3_u32 v106, v106, v115, s0
	v_and_b32_sdwa v115, v108, v135 dst_sel:DWORD dst_unused:UNUSED_PAD src0_sel:WORD_1 src1_sel:DWORD
	v_add3_u32 v107, v107, v114, s0
	v_and_b32_sdwa v114, v109, v135 dst_sel:DWORD dst_unused:UNUSED_PAD src0_sel:WORD_1 src1_sel:DWORD
	v_add3_u32 v108, v108, v115, s0
	v_add3_u32 v109, v109, v114, s0
	v_and_b32_e32 v108, 0xffff0000, v108
	v_and_b32_e32 v109, 0xffff0000, v109
	v_or_b32_sdwa v106, v108, v106 dst_sel:DWORD dst_unused:UNUSED_PAD src0_sel:DWORD src1_sel:WORD_1
	v_lshlrev_b32_e32 v116, 16, v164
	v_sub_f32_e32 v108, v121, v117
	v_or_b32_sdwa v107, v109, v107 dst_sel:DWORD dst_unused:UNUSED_PAD src0_sel:DWORD src1_sel:WORD_1
	v_fma_f32 v108, v4, v108, v117
	v_sub_f32_e32 v109, v116, v117
	v_and_b32_e32 v125, 0xffff0000, v164
	v_fmac_f32_e32 v108, v6, v109
	v_sub_f32_e32 v109, v124, v120
	v_fma_f32 v109, v5, v109, v120
	v_sub_f32_e32 v114, v125, v120
	v_mul_f32_e32 v108, 0xbfb8aa3b, v108
	v_fmac_f32_e32 v109, v7, v114
	v_exp_f32_e32 v108, v108
	v_mul_f32_e32 v109, 0xbfb8aa3b, v109
	v_exp_f32_e32 v109, v109
	v_lshl_add_u64 v[104:105], v[104:105], 0, v[12:13]
	v_add_f32_e32 v108, 1.0, v108
	v_rcp_f32_e32 v108, v108
	global_store_dwordx2 v[104:105], v[106:107], off offset:256
	v_add_f32_e32 v104, 1.0, v109
	v_rcp_f32_e32 v104, v104
	s_nop 0
	s_nop 0
	s_nop 0
	s_nop 0
	s_nop 0
	v_cvt_pk_bf16_f32 v108, v108, v104
	v_mad_i64_i32 v[104:105], s[10:11], v154, s1, v[46:47]
	v_lshl_add_u64 v[106:107], v[104:105], 0, v[2:3]
	global_store_dword v[106:107], v108, off
	v_pk_add_f32 v[106:107], v[88:89], 0 op_sel_hi:[1,0]
	v_pk_add_f32 v[108:109], v[90:91], 0 op_sel_hi:[1,0]
	v_pk_add_f32 v[106:107], v[106:107], v[70:71]
	v_pk_add_f32 v[108:109], v[108:109], v[72:73]
	v_cndmask_b32_e64 v114, 0, v106, s[4:5]
	v_cndmask_b32_e64 v121, 0, v107, s[4:5]
	v_pk_add_f32 v[106:107], v[106:107], v[94:95]
	v_cndmask_b32_e64 v115, 0, v108, s[4:5]
	v_cndmask_b32_e64 v124, 0, v109, s[4:5]
	v_pk_add_f32 v[108:109], v[108:109], v[96:97]
	v_pk_add_f32 v[106:107], v[106:107], v[56:57]
	v_pk_add_f32 v[108:109], v[108:109], v[58:59]
	v_cndmask_b32_e64 v121, v121, v107, s[6:7]
	v_cndmask_b32_e64 v114, v114, v106, s[6:7]
	v_pk_add_f32 v[106:107], v[106:107], v[110:111]
	v_cndmask_b32_e64 v124, v124, v109, s[6:7]
	v_cndmask_b32_e64 v115, v115, v108, s[6:7]
	v_pk_add_f32 v[108:109], v[108:109], v[112:113]
	v_pk_add_f32 v[106:107], v[106:107], v[100:101]
	v_pk_add_f32 v[108:109], v[108:109], v[102:103]
	v_pk_add_f32 v[106:107], v[106:107], v[48:49]
	v_pk_add_f32 v[108:109], v[108:109], v[52:53]
	v_pk_add_f32 v[106:107], v[106:107], v[66:67]
	v_pk_add_f32 v[108:109], v[108:109], v[68:69]
	v_pk_add_f32 v[60:61], v[106:107], v[60:61]
	v_pk_add_f32 v[62:63], v[108:109], v[62:63]
	v_pk_add_f32 v[60:61], v[60:61], v[50:51]
	v_pk_add_f32 v[62:63], v[62:63], v[54:55]
	v_pk_add_f32 v[60:61], v[60:61], v[42:43]
	v_pk_add_f32 v[62:63], v[62:63], v[44:45]
	v_pk_add_f32 v[60:61], v[60:61], v[118:119]
	v_pk_add_f32 v[62:63], v[62:63], v[122:123]
	v_pk_add_f32 v[60:61], v[60:61], v[82:83]
	v_pk_add_f32 v[62:63], v[62:63], v[86:87]
	v_pk_add_f32 v[60:61], v[60:61], v[80:81]
	v_cndmask_b32_e64 v115, v115, v108, s[8:9]
	v_cndmask_b32_e64 v124, v124, v109, s[8:9]
	v_pk_add_f32 v[62:63], v[62:63], v[84:85]
	v_pk_add_f32 v[108:109], v[60:61], v[64:65]
	v_and_b32_e32 v61, 0xffff0000, v98
	v_lshlrev_b32_e32 v60, 16, v98
	v_cndmask_b32_e64 v114, v114, v106, s[8:9]
	v_cndmask_b32_e64 v121, v121, v107, s[8:9]
	v_pk_add_f32 v[106:107], v[62:63], v[74:75]
	v_and_b32_e32 v63, 0xffff0000, v99
	v_lshlrev_b32_e32 v62, 16, v99
	v_pk_add_f32 v[98:99], v[108:109], v[60:61]
	v_add_u32_e32 v108, 13, v144
	v_add_u32_e32 v109, 13, v145
	v_max_i32_e32 v108, 0, v108
	v_min_i32_e32 v109, v109, v136
	v_sub_u32_e32 v108, v109, v108
	v_cvt_f32_i32_e32 v126, v108
	v_pk_add_f32 v[106:107], v[106:107], v[62:63]
	v_cndmask_b32_e64 v108, v121, v99, s[2:3]
	v_cndmask_b32_e64 v99, v115, v106, s[2:3]
	v_rcp_iflag_f32_e32 v106, v126
	v_cndmask_b32_e64 v98, v114, v98, s[2:3]
	v_mov_b32_e32 v114, v70
	v_mov_b32_e32 v115, v72
	v_cndmask_b32_e64 v109, v124, v107, s[2:3]
	v_pk_fma_f32 v[98:99], v[106:107], v[98:99], v[114:115] op_sel_hi:[0,1,1] neg_lo:[0,0,1] neg_hi:[0,0,1]
	v_mov_b32_e32 v114, v71
	v_mov_b32_e32 v115, v73
	v_pk_fma_f32 v[106:107], v[106:107], v[108:109], v[114:115] op_sel_hi:[0,1,1] neg_lo:[0,0,1] neg_hi:[0,0,1]
	v_and_b32_sdwa v109, v98, v135 dst_sel:DWORD dst_unused:UNUSED_PAD src0_sel:WORD_1 src1_sel:DWORD
	v_and_b32_sdwa v108, v99, v135 dst_sel:DWORD dst_unused:UNUSED_PAD src0_sel:WORD_1 src1_sel:DWORD
	v_add3_u32 v98, v98, v109, s0
	v_and_b32_sdwa v109, v106, v135 dst_sel:DWORD dst_unused:UNUSED_PAD src0_sel:WORD_1 src1_sel:DWORD
	v_add3_u32 v99, v99, v108, s0
	v_and_b32_sdwa v108, v107, v135 dst_sel:DWORD dst_unused:UNUSED_PAD src0_sel:WORD_1 src1_sel:DWORD
	v_add3_u32 v106, v106, v109, s0
	v_add3_u32 v107, v107, v108, s0
	v_and_b32_e32 v106, 0xffff0000, v106
	v_and_b32_e32 v107, 0xffff0000, v107
	v_or_b32_sdwa v98, v106, v98 dst_sel:DWORD dst_unused:UNUSED_PAD src0_sel:DWORD src1_sel:WORD_1
	v_lshlrev_b32_e32 v114, 16, v163
	v_sub_f32_e32 v106, v117, v116
	v_or_b32_sdwa v99, v107, v99 dst_sel:DWORD dst_unused:UNUSED_PAD src0_sel:DWORD src1_sel:WORD_1
	v_fma_f32 v106, v4, v106, v116
	v_sub_f32_e32 v107, v114, v116
	v_and_b32_e32 v115, 0xffff0000, v163
	v_fmac_f32_e32 v106, v6, v107
	v_sub_f32_e32 v107, v120, v125
	v_fma_f32 v107, v5, v107, v125
	v_sub_f32_e32 v108, v115, v125
	v_mul_f32_e32 v106, 0xbfb8aa3b, v106
	v_fmac_f32_e32 v107, v7, v108
	v_exp_f32_e32 v106, v106
	v_mul_f32_e32 v107, 0xbfb8aa3b, v107
	v_exp_f32_e32 v107, v107
	v_lshl_add_u64 v[104:105], v[104:105], 0, v[12:13]
	v_add_f32_e32 v106, 1.0, v106
	v_rcp_f32_e32 v106, v106
	global_store_dwordx2 v[104:105], v[98:99], off offset:256
	v_add_f32_e32 v98, 1.0, v107
	v_rcp_f32_e32 v98, v98
	s_nop 0
	s_nop 0
	s_nop 0
	s_nop 0
	s_nop 0
	v_cvt_pk_bf16_f32 v106, v106, v98
	v_mad_i64_i32 v[98:99], s[10:11], v152, s1, v[46:47]
	v_lshl_add_u64 v[104:105], v[98:99], 0, v[2:3]
	global_store_dword v[104:105], v106, off
	v_pk_add_f32 v[104:105], v[70:71], 0 op_sel_hi:[1,0]
	v_pk_add_f32 v[106:107], v[72:73], 0 op_sel_hi:[1,0]
	v_pk_add_f32 v[104:105], v[104:105], v[56:57]
	v_pk_add_f32 v[106:107], v[106:107], v[58:59]
	v_cndmask_b32_e64 v108, 0, v104, s[4:5]
	v_cndmask_b32_e64 v117, 0, v105, s[4:5]
	v_pk_add_f32 v[104:105], v[104:105], v[88:89]
	v_cndmask_b32_e64 v109, 0, v106, s[4:5]
	v_cndmask_b32_e64 v120, 0, v107, s[4:5]
	v_pk_add_f32 v[106:107], v[106:107], v[90:91]
	v_pk_add_f32 v[104:105], v[104:105], v[48:49]
	v_pk_add_f32 v[106:107], v[106:107], v[52:53]
	v_cndmask_b32_e64 v117, v117, v105, s[6:7]
	v_cndmask_b32_e64 v108, v108, v104, s[6:7]
	v_pk_add_f32 v[104:105], v[104:105], v[100:101]
	v_cndmask_b32_e64 v120, v120, v107, s[6:7]
	v_cndmask_b32_e64 v109, v109, v106, s[6:7]
	v_pk_add_f32 v[106:107], v[106:107], v[102:103]
	v_pk_add_f32 v[104:105], v[104:105], v[94:95]
	v_pk_add_f32 v[106:107], v[106:107], v[96:97]
	v_pk_add_f32 v[104:105], v[104:105], v[66:67]
	v_pk_add_f32 v[106:107], v[106:107], v[68:69]
	v_pk_add_f32 v[104:105], v[104:105], v[82:83]
	v_pk_add_f32 v[106:107], v[106:107], v[86:87]
	v_pk_add_f32 v[50:51], v[104:105], v[50:51]
	v_pk_add_f32 v[54:55], v[106:107], v[54:55]
	v_pk_add_f32 v[50:51], v[50:51], v[42:43]
	v_pk_add_f32 v[54:55], v[54:55], v[44:45]
	v_pk_add_f32 v[50:51], v[50:51], v[118:119]
	v_pk_add_f32 v[54:55], v[54:55], v[122:123]
	v_pk_add_f32 v[50:51], v[50:51], v[110:111]
	v_pk_add_f32 v[54:55], v[54:55], v[112:113]
	v_pk_add_f32 v[50:51], v[50:51], v[80:81]
	v_pk_add_f32 v[54:55], v[54:55], v[84:85]
	v_pk_add_f32 v[50:51], v[50:51], v[64:65]
	v_cndmask_b32_e64 v109, v109, v106, s[8:9]
	v_cndmask_b32_e64 v120, v120, v107, s[8:9]
	v_pk_add_f32 v[54:55], v[54:55], v[74:75]
	v_pk_add_f32 v[106:107], v[50:51], v[60:61]
	v_and_b32_e32 v51, 0xffff0000, v92
	v_lshlrev_b32_e32 v50, 16, v92
	v_cndmask_b32_e64 v108, v108, v104, s[8:9]
	v_cndmask_b32_e64 v117, v117, v105, s[8:9]
	v_pk_add_f32 v[104:105], v[54:55], v[62:63]
	v_and_b32_e32 v55, 0xffff0000, v93
	v_lshlrev_b32_e32 v54, 16, v93
	v_pk_add_f32 v[92:93], v[106:107], v[50:51]
	v_add_u32_e32 v106, 14, v144
	v_add_u32_e32 v107, 14, v145
	v_max_i32_e32 v106, 0, v106
	v_min_i32_e32 v107, v107, v136
	v_sub_u32_e32 v106, v107, v106
	v_cvt_f32_i32_e32 v121, v106
	v_pk_add_f32 v[104:105], v[104:105], v[54:55]
	v_cndmask_b32_e64 v106, v117, v93, s[2:3]
	v_cndmask_b32_e64 v93, v109, v104, s[2:3]
	v_rcp_iflag_f32_e32 v104, v121
	v_cndmask_b32_e64 v92, v108, v92, s[2:3]
	v_mov_b32_e32 v108, v56
	v_mov_b32_e32 v109, v58
	v_cndmask_b32_e64 v107, v120, v105, s[2:3]
	v_pk_fma_f32 v[92:93], v[104:105], v[92:93], v[108:109] op_sel_hi:[0,1,1] neg_lo:[0,0,1] neg_hi:[0,0,1]
	v_mov_b32_e32 v108, v57
	v_mov_b32_e32 v109, v59
	v_pk_fma_f32 v[104:105], v[104:105], v[106:107], v[108:109] op_sel_hi:[0,1,1] neg_lo:[0,0,1] neg_hi:[0,0,1]
	v_and_b32_sdwa v107, v92, v135 dst_sel:DWORD dst_unused:UNUSED_PAD src0_sel:WORD_1 src1_sel:DWORD
	v_and_b32_sdwa v106, v93, v135 dst_sel:DWORD dst_unused:UNUSED_PAD src0_sel:WORD_1 src1_sel:DWORD
	v_add3_u32 v92, v92, v107, s0
	v_and_b32_sdwa v107, v104, v135 dst_sel:DWORD dst_unused:UNUSED_PAD src0_sel:WORD_1 src1_sel:DWORD
	v_add3_u32 v93, v93, v106, s0
	v_and_b32_sdwa v106, v105, v135 dst_sel:DWORD dst_unused:UNUSED_PAD src0_sel:WORD_1 src1_sel:DWORD
	v_add3_u32 v104, v104, v107, s0
	v_add3_u32 v105, v105, v106, s0
	v_and_b32_e32 v104, 0xffff0000, v104
	v_and_b32_e32 v105, 0xffff0000, v105
	v_or_b32_sdwa v92, v104, v92 dst_sel:DWORD dst_unused:UNUSED_PAD src0_sel:DWORD src1_sel:WORD_1
	v_lshlrev_b32_e32 v117, 16, v162
	v_sub_f32_e32 v104, v116, v114
	v_or_b32_sdwa v93, v105, v93 dst_sel:DWORD dst_unused:UNUSED_PAD src0_sel:DWORD src1_sel:WORD_1
	v_fma_f32 v104, v4, v104, v114
	v_sub_f32_e32 v105, v117, v114
	v_and_b32_e32 v120, 0xffff0000, v162
	v_fmac_f32_e32 v104, v6, v105
	v_sub_f32_e32 v105, v125, v115
	v_fma_f32 v105, v5, v105, v115
	v_sub_f32_e32 v106, v120, v115
	v_mul_f32_e32 v104, 0xbfb8aa3b, v104
	v_fmac_f32_e32 v105, v7, v106
	v_exp_f32_e32 v104, v104
	v_mul_f32_e32 v105, 0xbfb8aa3b, v105
	v_exp_f32_e32 v105, v105
	v_lshl_add_u64 v[98:99], v[98:99], 0, v[12:13]
	v_add_f32_e32 v104, 1.0, v104
	v_rcp_f32_e32 v104, v104
	global_store_dwordx2 v[98:99], v[92:93], off offset:256
	v_add_f32_e32 v92, 1.0, v105
	v_rcp_f32_e32 v92, v92
	s_nop 0
	s_nop 0
	s_nop 0
	s_nop 0
	s_nop 0
	v_cvt_pk_bf16_f32 v104, v104, v92
	v_mad_i64_i32 v[92:93], s[10:11], v150, s1, v[46:47]
	v_lshl_add_u64 v[98:99], v[92:93], 0, v[2:3]
	global_store_dword v[98:99], v104, off
	v_pk_add_f32 v[98:99], v[56:57], 0 op_sel_hi:[1,0]
	v_pk_add_f32 v[104:105], v[58:59], 0 op_sel_hi:[1,0]
	v_pk_add_f32 v[98:99], v[98:99], v[48:49]
	v_pk_add_f32 v[104:105], v[104:105], v[52:53]
	v_cndmask_b32_e64 v106, 0, v98, s[4:5]
	v_cndmask_b32_e64 v108, 0, v99, s[4:5]
	v_pk_add_f32 v[98:99], v[98:99], v[70:71]
	v_cndmask_b32_e64 v107, 0, v104, s[4:5]
	v_cndmask_b32_e64 v109, 0, v105, s[4:5]
	v_pk_add_f32 v[104:105], v[104:105], v[72:73]
	v_pk_add_f32 v[98:99], v[98:99], v[66:67]
	v_pk_add_f32 v[104:105], v[104:105], v[68:69]
	v_cndmask_b32_e64 v108, v108, v99, s[6:7]
	v_cndmask_b32_e64 v106, v106, v98, s[6:7]
	v_pk_add_f32 v[98:99], v[98:99], v[94:95]
	v_cndmask_b32_e64 v109, v109, v105, s[6:7]
	v_cndmask_b32_e64 v107, v107, v104, s[6:7]
	v_pk_add_f32 v[104:105], v[104:105], v[96:97]
	v_pk_add_f32 v[98:99], v[98:99], v[88:89]
	v_pk_add_f32 v[104:105], v[104:105], v[90:91]
	v_pk_add_f32 v[98:99], v[98:99], v[82:83]
	v_pk_add_f32 v[104:105], v[104:105], v[86:87]
	v_pk_add_f32 v[98:99], v[98:99], v[80:81]
	v_pk_add_f32 v[104:105], v[104:105], v[84:85]
	v_pk_add_f32 v[42:43], v[98:99], v[42:43]
	v_pk_add_f32 v[44:45], v[104:105], v[44:45]
	v_pk_add_f32 v[42:43], v[42:43], v[118:119]
	v_pk_add_f32 v[44:45], v[44:45], v[122:123]
	v_pk_add_f32 v[42:43], v[42:43], v[110:111]
	v_pk_add_f32 v[44:45], v[44:45], v[112:113]
	v_pk_add_f32 v[42:43], v[42:43], v[100:101]
	v_pk_add_f32 v[44:45], v[44:45], v[102:103]
	v_pk_add_f32 v[42:43], v[42:43], v[64:65]
	v_pk_add_f32 v[44:45], v[44:45], v[74:75]
	v_pk_add_f32 v[42:43], v[42:43], v[60:61]
	v_cndmask_b32_e64 v107, v107, v104, s[8:9]
	v_cndmask_b32_e64 v109, v109, v105, s[8:9]
	v_pk_add_f32 v[44:45], v[44:45], v[62:63]
	v_pk_add_f32 v[104:105], v[42:43], v[50:51]
	v_and_b32_e32 v43, 0xffff0000, v78
	v_lshlrev_b32_e32 v42, 16, v78
	v_cndmask_b32_e64 v106, v106, v98, s[8:9]
	v_cndmask_b32_e64 v108, v108, v99, s[8:9]
	v_pk_add_f32 v[98:99], v[44:45], v[54:55]
	v_and_b32_e32 v45, 0xffff0000, v79
	v_lshlrev_b32_e32 v44, 16, v79
	v_pk_add_f32 v[78:79], v[104:105], v[42:43]
	v_add_u32_e32 v104, 15, v144
	v_add_u32_e32 v105, 15, v145
	v_max_i32_e32 v104, 0, v104
	v_min_i32_e32 v105, v105, v136
	v_sub_u32_e32 v104, v105, v104
	v_cvt_f32_i32_e32 v116, v104
	v_pk_add_f32 v[98:99], v[98:99], v[44:45]
	v_cndmask_b32_e64 v104, v108, v79, s[2:3]
	v_cndmask_b32_e64 v79, v107, v98, s[2:3]
	v_rcp_iflag_f32_e32 v98, v116
	v_cndmask_b32_e64 v78, v106, v78, s[2:3]
	v_mov_b32_e32 v106, v48
	v_mov_b32_e32 v107, v52
	v_cndmask_b32_e64 v105, v109, v99, s[2:3]
	v_pk_fma_f32 v[78:79], v[98:99], v[78:79], v[106:107] op_sel_hi:[0,1,1] neg_lo:[0,0,1] neg_hi:[0,0,1]
	v_mov_b32_e32 v106, v49
	v_mov_b32_e32 v107, v53
	v_pk_fma_f32 v[98:99], v[98:99], v[104:105], v[106:107] op_sel_hi:[0,1,1] neg_lo:[0,0,1] neg_hi:[0,0,1]
	v_and_b32_sdwa v105, v78, v135 dst_sel:DWORD dst_unused:UNUSED_PAD src0_sel:WORD_1 src1_sel:DWORD
	v_and_b32_sdwa v104, v79, v135 dst_sel:DWORD dst_unused:UNUSED_PAD src0_sel:WORD_1 src1_sel:DWORD
	v_add3_u32 v78, v78, v105, s0
	v_and_b32_sdwa v105, v98, v135 dst_sel:DWORD dst_unused:UNUSED_PAD src0_sel:WORD_1 src1_sel:DWORD
	v_add3_u32 v79, v79, v104, s0
	v_and_b32_sdwa v104, v99, v135 dst_sel:DWORD dst_unused:UNUSED_PAD src0_sel:WORD_1 src1_sel:DWORD
	v_add3_u32 v98, v98, v105, s0
	v_add3_u32 v99, v99, v104, s0
	v_and_b32_e32 v98, 0xffff0000, v98
	v_and_b32_e32 v99, 0xffff0000, v99
	v_or_b32_sdwa v78, v98, v78 dst_sel:DWORD dst_unused:UNUSED_PAD src0_sel:DWORD src1_sel:WORD_1
	v_lshlrev_b32_e32 v116, 16, v160
	v_sub_f32_e32 v98, v114, v117
	v_or_b32_sdwa v79, v99, v79 dst_sel:DWORD dst_unused:UNUSED_PAD src0_sel:DWORD src1_sel:WORD_1
	v_fma_f32 v98, v4, v98, v117
	v_sub_f32_e32 v99, v116, v117
	v_and_b32_e32 v121, 0xffff0000, v160
	v_fmac_f32_e32 v98, v6, v99
	v_sub_f32_e32 v99, v115, v120
	v_fma_f32 v99, v5, v99, v120
	v_sub_f32_e32 v104, v121, v120
	v_mul_f32_e32 v98, 0xbfb8aa3b, v98
	v_fmac_f32_e32 v99, v7, v104
	v_exp_f32_e32 v98, v98
	v_mul_f32_e32 v99, 0xbfb8aa3b, v99
	v_exp_f32_e32 v99, v99
	v_lshl_add_u64 v[92:93], v[92:93], 0, v[12:13]
	v_add_f32_e32 v98, 1.0, v98
	v_rcp_f32_e32 v98, v98
	global_store_dwordx2 v[92:93], v[78:79], off offset:256
	v_add_f32_e32 v78, 1.0, v99
	v_rcp_f32_e32 v78, v78
	v_bfe_u32 v79, v98, 16, 1
	v_add3_u32 v79, v98, v79, s0
	v_lshrrev_b32_e32 v79, 16, v79
	v_bfe_u32 v92, v78, 16, 1
	v_add3_u32 v78, v78, v92, s0
	v_mad_i64_i32 v[98:99], s[10:11], v148, s1, v[46:47]
	v_and_or_b32 v92, v78, s93, v79
	v_lshl_add_u64 v[78:79], v[98:99], 0, v[2:3]
	global_store_dword v[78:79], v92, off
	v_pk_add_f32 v[78:79], v[48:49], 0 op_sel_hi:[1,0]
	v_pk_add_f32 v[92:93], v[52:53], 0 op_sel_hi:[1,0]
	v_pk_add_f32 v[78:79], v[78:79], v[66:67]
	v_pk_add_f32 v[92:93], v[92:93], v[68:69]
	v_cndmask_b32_e64 v104, 0, v78, s[4:5]
	v_cndmask_b32_e64 v106, 0, v79, s[4:5]
	v_pk_add_f32 v[78:79], v[78:79], v[56:57]
	v_cndmask_b32_e64 v105, 0, v92, s[4:5]
	v_cndmask_b32_e64 v107, 0, v93, s[4:5]
	v_pk_add_f32 v[92:93], v[92:93], v[58:59]
	v_pk_add_f32 v[78:79], v[78:79], v[82:83]
	v_pk_add_f32 v[92:93], v[92:93], v[86:87]
	v_cndmask_b32_e64 v106, v106, v79, s[6:7]
	v_cndmask_b32_e64 v104, v104, v78, s[6:7]
	v_pk_add_f32 v[78:79], v[78:79], v[88:89]
	v_cndmask_b32_e64 v107, v107, v93, s[6:7]
	v_cndmask_b32_e64 v105, v105, v92, s[6:7]
	v_pk_add_f32 v[92:93], v[92:93], v[90:91]
	v_pk_add_f32 v[78:79], v[78:79], v[70:71]
	v_pk_add_f32 v[92:93], v[92:93], v[72:73]
	v_pk_add_f32 v[78:79], v[78:79], v[80:81]
	v_pk_add_f32 v[92:93], v[92:93], v[84:85]
	v_pk_add_f32 v[78:79], v[78:79], v[64:65]
	v_pk_add_f32 v[92:93], v[92:93], v[74:75]
	v_cndmask_b32_e64 v108, v104, v78, s[8:9]
	v_cndmask_b32_e64 v114, v106, v79, s[8:9]
	v_pk_add_f32 v[78:79], v[78:79], v[118:119]
	v_cndmask_b32_e64 v109, v105, v92, s[8:9]
	v_cndmask_b32_e64 v115, v107, v93, s[8:9]
	v_pk_add_f32 v[92:93], v[92:93], v[122:123]
	v_pk_add_f32 v[78:79], v[78:79], v[110:111]
	v_pk_add_f32 v[92:93], v[92:93], v[112:113]
	v_pk_add_f32 v[78:79], v[78:79], v[100:101]
	v_pk_add_f32 v[92:93], v[92:93], v[102:103]
	v_pk_add_f32 v[78:79], v[78:79], v[94:95]
	v_pk_add_f32 v[92:93], v[92:93], v[96:97]
	v_pk_add_f32 v[78:79], v[78:79], v[60:61]
	v_pk_add_f32 v[92:93], v[92:93], v[62:63]
	v_pk_add_f32 v[78:79], v[78:79], v[50:51]
	v_pk_add_f32 v[92:93], v[92:93], v[54:55]
	v_pk_add_f32 v[106:107], v[78:79], v[42:43]
	v_and_b32_e32 v79, 0xffff0000, v76
	v_lshlrev_b32_e32 v78, 16, v76
	v_pk_add_f32 v[104:105], v[92:93], v[44:45]
	v_and_b32_e32 v93, 0xffff0000, v77
	v_lshlrev_b32_e32 v92, 16, v77
	v_pk_add_f32 v[76:77], v[106:107], v[78:79]
	v_add_u32_e32 v106, 16, v144
	v_add_u32_e32 v107, 16, v145
	v_max_i32_e32 v106, 0, v106
	v_min_i32_e32 v107, v107, v136
	v_sub_u32_e32 v106, v107, v106
	v_cvt_f32_i32_e32 v118, v106
	v_pk_add_f32 v[104:105], v[104:105], v[92:93]
	v_cndmask_b32_e64 v106, v114, v77, s[2:3]
	v_cndmask_b32_e64 v77, v109, v104, s[2:3]
	v_rcp_iflag_f32_e32 v104, v118
	v_cndmask_b32_e64 v76, v108, v76, s[2:3]
	v_mov_b32_e32 v108, v66
	v_mov_b32_e32 v109, v68
	v_cndmask_b32_e64 v107, v115, v105, s[2:3]
	v_pk_fma_f32 v[76:77], v[104:105], v[76:77], v[108:109] op_sel_hi:[0,1,1] neg_lo:[0,0,1] neg_hi:[0,0,1]
	v_mov_b32_e32 v108, v67
	v_mov_b32_e32 v109, v69
	v_pk_fma_f32 v[104:105], v[104:105], v[106:107], v[108:109] op_sel_hi:[0,1,1] neg_lo:[0,0,1] neg_hi:[0,0,1]
	v_and_b32_sdwa v107, v76, v135 dst_sel:DWORD dst_unused:UNUSED_PAD src0_sel:WORD_1 src1_sel:DWORD
	v_and_b32_sdwa v106, v77, v135 dst_sel:DWORD dst_unused:UNUSED_PAD src0_sel:WORD_1 src1_sel:DWORD
	v_add3_u32 v76, v76, v107, s0
	v_and_b32_sdwa v107, v104, v135 dst_sel:DWORD dst_unused:UNUSED_PAD src0_sel:WORD_1 src1_sel:DWORD
	v_add3_u32 v77, v77, v106, s0
	v_and_b32_sdwa v106, v105, v135 dst_sel:DWORD dst_unused:UNUSED_PAD src0_sel:WORD_1 src1_sel:DWORD
	v_add3_u32 v104, v104, v107, s0
	v_add3_u32 v105, v105, v106, s0
	v_and_b32_e32 v104, 0xffff0000, v104
	v_and_b32_e32 v105, 0xffff0000, v105
	v_or_b32_sdwa v76, v104, v76 dst_sel:DWORD dst_unused:UNUSED_PAD src0_sel:DWORD src1_sel:WORD_1
	v_lshlrev_b32_e32 v114, 16, v158
	v_sub_f32_e32 v104, v117, v116
	v_or_b32_sdwa v77, v105, v77 dst_sel:DWORD dst_unused:UNUSED_PAD src0_sel:DWORD src1_sel:WORD_1
	v_fma_f32 v104, v4, v104, v116
	v_sub_f32_e32 v105, v114, v116
	v_and_b32_e32 v115, 0xffff0000, v158
	v_fmac_f32_e32 v104, v6, v105
	v_sub_f32_e32 v105, v120, v121
	v_fma_f32 v105, v5, v105, v121
	v_sub_f32_e32 v106, v115, v121
	v_mul_f32_e32 v104, 0xbfb8aa3b, v104
	v_fmac_f32_e32 v105, v7, v106
	v_exp_f32_e32 v104, v104
	v_mul_f32_e32 v105, 0xbfb8aa3b, v105
	v_exp_f32_e32 v105, v105
	v_lshl_add_u64 v[98:99], v[98:99], 0, v[12:13]
	v_add_f32_e32 v104, 1.0, v104
	v_rcp_f32_e32 v104, v104
	global_store_dwordx2 v[98:99], v[76:77], off offset:256
	v_add_f32_e32 v76, 1.0, v105
	v_rcp_f32_e32 v76, v76
	s_nop 0
	s_nop 0
	s_nop 0
	s_nop 0
	s_nop 0
	v_cvt_pk_bf16_f32 v104, v104, v76
	v_mad_i64_i32 v[76:77], s[10:11], v146, s1, v[46:47]
	v_lshl_add_u64 v[98:99], v[76:77], 0, v[2:3]
	global_store_dword v[98:99], v104, off
	v_pk_add_f32 v[98:99], v[66:67], 0 op_sel_hi:[1,0]
	v_pk_add_f32 v[104:105], v[68:69], 0 op_sel_hi:[1,0]
	v_pk_add_f32 v[98:99], v[98:99], v[82:83]
	v_pk_add_f32 v[104:105], v[104:105], v[86:87]
	v_cndmask_b32_e64 v106, 0, v98, s[4:5]
	v_cndmask_b32_e64 v107, 0, v104, s[4:5]
	v_cndmask_b32_e64 v108, 0, v99, s[4:5]
	v_cndmask_b32_e64 v109, 0, v105, s[4:5]
	v_pk_add_f32 v[104:105], v[104:105], v[52:53]
	v_pk_add_f32 v[98:99], v[98:99], v[48:49]
	v_pk_add_f32 v[104:105], v[104:105], v[84:85]
	v_pk_add_f32 v[98:99], v[98:99], v[80:81]
	v_cndmask_b32_e64 v109, v109, v105, s[6:7]
	v_cndmask_b32_e64 v108, v108, v99, s[6:7]
	v_cndmask_b32_e64 v107, v107, v104, s[6:7]
	v_cndmask_b32_e64 v106, v106, v98, s[6:7]
	v_pk_add_f32 v[98:99], v[98:99], v[70:71]
	v_pk_add_f32 v[104:105], v[104:105], v[72:73]
	v_pk_add_f32 v[98:99], v[98:99], v[56:57]
	v_pk_add_f32 v[104:105], v[104:105], v[58:59]
	v_pk_add_f32 v[98:99], v[98:99], v[64:65]
	v_pk_add_f32 v[104:105], v[104:105], v[74:75]
	v_pk_add_f32 v[98:99], v[98:99], v[60:61]
	v_pk_add_f32 v[104:105], v[104:105], v[62:63]
	v_cndmask_b32_e64 v117, v106, v98, s[8:9]
	v_cndmask_b32_e64 v118, v107, v104, s[8:9]
	v_cndmask_b32_e64 v106, v108, v99, s[8:9]
	v_cndmask_b32_e64 v107, v109, v105, s[8:9]
	v_pk_add_f32 v[104:105], v[104:105], v[112:113]
	v_pk_add_f32 v[98:99], v[98:99], v[110:111]
	v_pk_add_f32 v[104:105], v[104:105], v[102:103]
	v_pk_add_f32 v[98:99], v[98:99], v[100:101]
	v_add_u32_e32 v108, 17, v144
	v_add_u32_e32 v109, 17, v145
	v_pk_add_f32 v[104:105], v[104:105], v[96:97]
	v_pk_add_f32 v[98:99], v[98:99], v[94:95]
	v_max_i32_e32 v108, 0, v108
	v_min_i32_e32 v109, v109, v136
	v_pk_add_f32 v[98:99], v[98:99], v[88:89]
	v_pk_add_f32 v[104:105], v[104:105], v[90:91]
	v_sub_u32_e32 v108, v109, v108
	v_pk_add_f32 v[104:105], v[104:105], v[54:55]
	v_pk_add_f32 v[98:99], v[98:99], v[50:51]
	v_cvt_f32_i32_e32 v108, v108
	v_pk_add_f32 v[98:99], v[98:99], v[42:43]
	v_pk_add_f32 v[104:105], v[104:105], v[44:45]
	v_pk_add_f32 v[98:99], v[98:99], v[78:79]
	v_pk_add_f32 v[104:105], v[104:105], v[92:93]
	v_pk_add_f32 v[98:99], v[98:99], v[16:17]
	v_pk_add_f32 v[104:105], v[104:105], v[18:19]
	v_cndmask_b32_e64 v106, v106, v99, s[2:3]
	v_cndmask_b32_e64 v99, v118, v104, s[2:3]
	v_rcp_iflag_f32_e32 v104, v108
	v_cndmask_b32_e64 v98, v117, v98, s[2:3]
	v_mov_b32_e32 v108, v82
	v_mov_b32_e32 v109, v86
	v_cndmask_b32_e64 v107, v107, v105, s[2:3]
	v_pk_fma_f32 v[98:99], v[104:105], v[98:99], v[108:109] op_sel_hi:[0,1,1] neg_lo:[0,0,1] neg_hi:[0,0,1]
	v_mov_b32_e32 v108, v83
	v_mov_b32_e32 v109, v87
	v_pk_fma_f32 v[104:105], v[104:105], v[106:107], v[108:109] op_sel_hi:[0,1,1] neg_lo:[0,0,1] neg_hi:[0,0,1]
	v_and_b32_sdwa v107, v98, v135 dst_sel:DWORD dst_unused:UNUSED_PAD src0_sel:WORD_1 src1_sel:DWORD
	v_and_b32_sdwa v106, v99, v135 dst_sel:DWORD dst_unused:UNUSED_PAD src0_sel:WORD_1 src1_sel:DWORD
	v_add3_u32 v98, v98, v107, s0
	v_and_b32_sdwa v107, v104, v135 dst_sel:DWORD dst_unused:UNUSED_PAD src0_sel:WORD_1 src1_sel:DWORD
	v_add3_u32 v99, v99, v106, s0
	v_and_b32_sdwa v106, v105, v135 dst_sel:DWORD dst_unused:UNUSED_PAD src0_sel:WORD_1 src1_sel:DWORD
	v_add3_u32 v104, v104, v107, s0
	v_add3_u32 v105, v105, v106, s0
	v_and_b32_e32 v104, 0xffff0000, v104
	v_and_b32_e32 v105, 0xffff0000, v105
	v_or_b32_sdwa v98, v104, v98 dst_sel:DWORD dst_unused:UNUSED_PAD src0_sel:DWORD src1_sel:WORD_1
	v_lshlrev_b32_e32 v106, 16, v155
	v_sub_f32_e32 v104, v116, v114
	v_or_b32_sdwa v99, v105, v99 dst_sel:DWORD dst_unused:UNUSED_PAD src0_sel:DWORD src1_sel:WORD_1
	v_fma_f32 v104, v4, v104, v114
	v_sub_f32_e32 v105, v106, v114
	v_and_b32_e32 v107, 0xffff0000, v155
	v_fmac_f32_e32 v104, v6, v105
	v_sub_f32_e32 v105, v121, v115
	v_fma_f32 v105, v5, v105, v115
	v_sub_f32_e32 v108, v107, v115
	v_mul_f32_e32 v104, 0xbfb8aa3b, v104
	v_fmac_f32_e32 v105, v7, v108
	v_exp_f32_e32 v104, v104
	v_mul_f32_e32 v105, 0xbfb8aa3b, v105
	v_exp_f32_e32 v105, v105
	v_lshl_add_u64 v[76:77], v[76:77], 0, v[12:13]
	v_add_f32_e32 v104, 1.0, v104
	v_rcp_f32_e32 v104, v104
	global_store_dwordx2 v[76:77], v[98:99], off offset:256
	v_add_f32_e32 v76, 1.0, v105
	v_rcp_f32_e32 v76, v76
	s_nop 0
	s_nop 0
	s_nop 0
	s_nop 0
	s_nop 0
	v_cvt_pk_bf16_f32 v104, v104, v76
	v_mad_i64_i32 v[76:77], s[10:11], v142, s1, v[46:47]
	v_lshl_add_u64 v[98:99], v[76:77], 0, v[2:3]
	global_store_dword v[98:99], v104, off
	v_pk_add_f32 v[98:99], v[82:83], 0 op_sel_hi:[1,0]
	v_pk_add_f32 v[104:105], v[86:87], 0 op_sel_hi:[1,0]
	v_pk_add_f32 v[98:99], v[98:99], v[80:81]
	v_pk_add_f32 v[104:105], v[104:105], v[84:85]
	v_cndmask_b32_e64 v108, 0, v98, s[4:5]
	v_cndmask_b32_e64 v109, 0, v104, s[4:5]
	v_cndmask_b32_e64 v110, 0, v99, s[4:5]
	v_cndmask_b32_e64 v111, 0, v105, s[4:5]
	v_pk_add_f32 v[104:105], v[104:105], v[68:69]
	v_pk_add_f32 v[98:99], v[98:99], v[66:67]
	v_pk_add_f32 v[104:105], v[104:105], v[74:75]
	v_pk_add_f32 v[98:99], v[98:99], v[64:65]
	v_cndmask_b32_e64 v111, v111, v105, s[6:7]
	v_cndmask_b32_e64 v110, v110, v99, s[6:7]
	v_cndmask_b32_e64 v109, v109, v104, s[6:7]
	v_cndmask_b32_e64 v108, v108, v98, s[6:7]
	v_pk_add_f32 v[98:99], v[98:99], v[56:57]
	v_pk_add_f32 v[104:105], v[104:105], v[58:59]
	v_pk_add_f32 v[98:99], v[98:99], v[48:49]
	v_pk_add_f32 v[104:105], v[104:105], v[52:53]
	v_pk_add_f32 v[98:99], v[98:99], v[60:61]
	v_pk_add_f32 v[104:105], v[104:105], v[62:63]
	v_pk_add_f32 v[98:99], v[98:99], v[50:51]
	v_pk_add_f32 v[104:105], v[104:105], v[54:55]
	v_cndmask_b32_e64 v108, v108, v98, s[8:9]
	v_cndmask_b32_e64 v110, v110, v99, s[8:9]
	v_pk_add_f32 v[102:103], v[104:105], v[102:103]
	v_pk_add_f32 v[98:99], v[98:99], v[100:101]
	v_pk_add_f32 v[100:101], v[102:103], v[96:97]
	v_pk_add_f32 v[98:99], v[98:99], v[94:95]
	v_add_u32_e32 v102, 18, v144
	v_add_u32_e32 v103, 18, v145
	v_pk_add_f32 v[100:101], v[100:101], v[90:91]
	v_pk_add_f32 v[98:99], v[98:99], v[88:89]
	v_max_i32_e32 v102, 0, v102
	v_min_i32_e32 v103, v103, v136
	v_pk_add_f32 v[98:99], v[98:99], v[70:71]
	v_pk_add_f32 v[100:101], v[100:101], v[72:73]
	v_sub_u32_e32 v102, v103, v102
	v_cndmask_b32_e64 v109, v109, v104, s[8:9]
	v_pk_add_f32 v[100:101], v[100:101], v[44:45]
	v_pk_add_f32 v[98:99], v[98:99], v[42:43]
	v_cvt_f32_i32_e32 v104, v102
	v_pk_add_f32 v[98:99], v[98:99], v[78:79]
	v_pk_add_f32 v[100:101], v[100:101], v[92:93]
	v_pk_add_f32 v[98:99], v[98:99], v[16:17]
	v_pk_add_f32 v[100:101], v[100:101], v[18:19]
	v_pk_add_f32 v[98:99], v[98:99], v[14:15]
	v_pk_add_f32 v[100:101], v[100:101], v[20:21]
	v_cndmask_b32_e64 v102, v110, v99, s[2:3]
	v_cndmask_b32_e64 v99, v109, v100, s[2:3]
	v_rcp_iflag_f32_e32 v100, v104
	v_cndmask_b32_e64 v111, v111, v105, s[8:9]
	v_cndmask_b32_e64 v98, v108, v98, s[2:3]
	v_mov_b32_e32 v104, v80
	v_mov_b32_e32 v105, v84
	v_cndmask_b32_e64 v103, v111, v101, s[2:3]
	v_pk_fma_f32 v[98:99], v[100:101], v[98:99], v[104:105] op_sel_hi:[0,1,1] neg_lo:[0,0,1] neg_hi:[0,0,1]
	v_mov_b32_e32 v104, v81
	v_mov_b32_e32 v105, v85
	v_pk_fma_f32 v[100:101], v[100:101], v[102:103], v[104:105] op_sel_hi:[0,1,1] neg_lo:[0,0,1] neg_hi:[0,0,1]
	v_and_b32_sdwa v103, v98, v135 dst_sel:DWORD dst_unused:UNUSED_PAD src0_sel:WORD_1 src1_sel:DWORD
	v_and_b32_sdwa v102, v99, v135 dst_sel:DWORD dst_unused:UNUSED_PAD src0_sel:WORD_1 src1_sel:DWORD
	v_add3_u32 v98, v98, v103, s0
	v_and_b32_sdwa v103, v100, v135 dst_sel:DWORD dst_unused:UNUSED_PAD src0_sel:WORD_1 src1_sel:DWORD
	v_add3_u32 v99, v99, v102, s0
	v_and_b32_sdwa v102, v101, v135 dst_sel:DWORD dst_unused:UNUSED_PAD src0_sel:WORD_1 src1_sel:DWORD
	v_add3_u32 v100, v100, v103, s0
	v_add3_u32 v101, v101, v102, s0
	v_and_b32_e32 v100, 0xffff0000, v100
	v_and_b32_e32 v101, 0xffff0000, v101
	v_or_b32_sdwa v98, v100, v98 dst_sel:DWORD dst_unused:UNUSED_PAD src0_sel:DWORD src1_sel:WORD_1
	v_lshlrev_b32_e32 v102, 16, v153
	v_sub_f32_e32 v100, v114, v106
	v_or_b32_sdwa v99, v101, v99 dst_sel:DWORD dst_unused:UNUSED_PAD src0_sel:DWORD src1_sel:WORD_1
	v_fma_f32 v100, v4, v100, v106
	v_sub_f32_e32 v101, v102, v106
	v_and_b32_e32 v103, 0xffff0000, v153
	v_fmac_f32_e32 v100, v6, v101
	v_sub_f32_e32 v101, v115, v107
	v_fma_f32 v101, v5, v101, v107
	v_sub_f32_e32 v104, v103, v107
	v_mul_f32_e32 v100, 0xbfb8aa3b, v100
	v_fmac_f32_e32 v101, v7, v104
	v_exp_f32_e32 v100, v100
	v_mul_f32_e32 v101, 0xbfb8aa3b, v101
	v_exp_f32_e32 v101, v101
	v_lshl_add_u64 v[76:77], v[76:77], 0, v[12:13]
	v_add_f32_e32 v100, 1.0, v100
	v_rcp_f32_e32 v100, v100
	global_store_dwordx2 v[76:77], v[98:99], off offset:256
	v_add_f32_e32 v76, 1.0, v101
	v_rcp_f32_e32 v76, v76
	s_nop 0
	s_nop 0
	s_nop 0
	s_nop 0
	s_nop 0
	v_cvt_pk_bf16_f32 v100, v100, v76
	v_mad_i64_i32 v[76:77], s[10:11], v141, s1, v[46:47]
	v_lshl_add_u64 v[98:99], v[76:77], 0, v[2:3]
	global_store_dword v[98:99], v100, off
	v_pk_add_f32 v[98:99], v[80:81], 0 op_sel_hi:[1,0]
	v_pk_add_f32 v[100:101], v[84:85], 0 op_sel_hi:[1,0]
	v_pk_add_f32 v[98:99], v[98:99], v[64:65]
	v_pk_add_f32 v[100:101], v[100:101], v[74:75]
	v_cndmask_b32_e64 v104, 0, v98, s[4:5]
	v_cndmask_b32_e64 v105, 0, v100, s[4:5]
	v_cndmask_b32_e64 v108, 0, v99, s[4:5]
	v_cndmask_b32_e64 v109, 0, v101, s[4:5]
	v_pk_add_f32 v[100:101], v[100:101], v[86:87]
	v_pk_add_f32 v[98:99], v[98:99], v[82:83]
	v_pk_add_f32 v[100:101], v[100:101], v[62:63]
	v_pk_add_f32 v[98:99], v[98:99], v[60:61]
	v_cndmask_b32_e64 v109, v109, v101, s[6:7]
	v_cndmask_b32_e64 v108, v108, v99, s[6:7]
	v_cndmask_b32_e64 v105, v105, v100, s[6:7]
	v_cndmask_b32_e64 v104, v104, v98, s[6:7]
	v_pk_add_f32 v[98:99], v[98:99], v[48:49]
	v_pk_add_f32 v[100:101], v[100:101], v[52:53]
	v_pk_add_f32 v[98:99], v[98:99], v[66:67]
	v_pk_add_f32 v[100:101], v[100:101], v[68:69]
	v_pk_add_f32 v[98:99], v[98:99], v[50:51]
	v_pk_add_f32 v[100:101], v[100:101], v[54:55]
	v_pk_add_f32 v[98:99], v[98:99], v[42:43]
	v_pk_add_f32 v[100:101], v[100:101], v[44:45]
	v_pk_add_f32 v[94:95], v[98:99], v[94:95]
	v_pk_add_f32 v[96:97], v[100:101], v[96:97]
	v_cndmask_b32_e64 v104, v104, v98, s[8:9]
	v_cndmask_b32_e64 v108, v108, v99, s[8:9]
	v_pk_add_f32 v[94:95], v[94:95], v[88:89]
	v_pk_add_f32 v[96:97], v[96:97], v[90:91]
	v_add_u32_e32 v98, 19, v144
	v_add_u32_e32 v99, 19, v145
	v_pk_add_f32 v[96:97], v[96:97], v[72:73]
	v_pk_add_f32 v[94:95], v[94:95], v[70:71]
	v_max_i32_e32 v98, 0, v98
	v_min_i32_e32 v99, v99, v136
	v_pk_add_f32 v[94:95], v[94:95], v[56:57]
	v_pk_add_f32 v[96:97], v[96:97], v[58:59]
	v_sub_u32_e32 v98, v99, v98
	v_cndmask_b32_e64 v105, v105, v100, s[8:9]
	v_pk_add_f32 v[96:97], v[96:97], v[92:93]
	v_pk_add_f32 v[94:95], v[94:95], v[78:79]
	v_cvt_f32_i32_e32 v100, v98
	v_pk_add_f32 v[94:95], v[94:95], v[16:17]
	v_pk_add_f32 v[96:97], v[96:97], v[18:19]
	v_pk_add_f32 v[94:95], v[94:95], v[14:15]
	v_pk_add_f32 v[96:97], v[96:97], v[20:21]
	v_pk_add_f32 v[94:95], v[94:95], v[24:25]
	v_pk_add_f32 v[96:97], v[96:97], v[26:27]
	v_cndmask_b32_e64 v98, v108, v95, s[2:3]
	v_cndmask_b32_e64 v95, v105, v96, s[2:3]
	v_rcp_iflag_f32_e32 v96, v100
	v_cndmask_b32_e64 v109, v109, v101, s[8:9]
	v_cndmask_b32_e64 v94, v104, v94, s[2:3]
	v_mov_b32_e32 v100, v64
	v_mov_b32_e32 v101, v74
	v_cndmask_b32_e64 v99, v109, v97, s[2:3]
	v_pk_fma_f32 v[94:95], v[96:97], v[94:95], v[100:101] op_sel_hi:[0,1,1] neg_lo:[0,0,1] neg_hi:[0,0,1]
	v_mov_b32_e32 v100, v65
	v_mov_b32_e32 v101, v75
	v_pk_fma_f32 v[96:97], v[96:97], v[98:99], v[100:101] op_sel_hi:[0,1,1] neg_lo:[0,0,1] neg_hi:[0,0,1]
	v_and_b32_sdwa v99, v94, v135 dst_sel:DWORD dst_unused:UNUSED_PAD src0_sel:WORD_1 src1_sel:DWORD
	v_and_b32_sdwa v98, v95, v135 dst_sel:DWORD dst_unused:UNUSED_PAD src0_sel:WORD_1 src1_sel:DWORD
	v_add3_u32 v94, v94, v99, s0
	v_and_b32_sdwa v99, v96, v135 dst_sel:DWORD dst_unused:UNUSED_PAD src0_sel:WORD_1 src1_sel:DWORD
	v_add3_u32 v95, v95, v98, s0
	v_and_b32_sdwa v98, v97, v135 dst_sel:DWORD dst_unused:UNUSED_PAD src0_sel:WORD_1 src1_sel:DWORD
	v_add3_u32 v96, v96, v99, s0
	v_add3_u32 v97, v97, v98, s0
	v_and_b32_e32 v96, 0xffff0000, v96
	v_and_b32_e32 v97, 0xffff0000, v97
	v_or_b32_sdwa v94, v96, v94 dst_sel:DWORD dst_unused:UNUSED_PAD src0_sel:DWORD src1_sel:WORD_1
	v_lshlrev_b32_e32 v98, 16, v151
	v_sub_f32_e32 v96, v106, v102
	v_or_b32_sdwa v95, v97, v95 dst_sel:DWORD dst_unused:UNUSED_PAD src0_sel:DWORD src1_sel:WORD_1
	v_fma_f32 v96, v4, v96, v102
	v_sub_f32_e32 v97, v98, v102
	v_and_b32_e32 v99, 0xffff0000, v151
	v_fmac_f32_e32 v96, v6, v97
	v_sub_f32_e32 v97, v107, v103
	v_fma_f32 v97, v5, v97, v103
	v_sub_f32_e32 v100, v99, v103
	v_mul_f32_e32 v96, 0xbfb8aa3b, v96
	v_fmac_f32_e32 v97, v7, v100
	v_exp_f32_e32 v96, v96
	v_mul_f32_e32 v97, 0xbfb8aa3b, v97
	v_exp_f32_e32 v97, v97
	v_lshl_add_u64 v[76:77], v[76:77], 0, v[12:13]
	v_add_f32_e32 v96, 1.0, v96
	v_rcp_f32_e32 v96, v96
	global_store_dwordx2 v[76:77], v[94:95], off offset:256
	v_add_f32_e32 v76, 1.0, v97
	v_rcp_f32_e32 v76, v76
	s_nop 0
	s_nop 0
	s_nop 0
	s_nop 0
	s_nop 0
	v_cvt_pk_bf16_f32 v96, v96, v76
	v_mad_i64_i32 v[76:77], s[10:11], v140, s1, v[46:47]
	v_lshl_add_u64 v[94:95], v[76:77], 0, v[2:3]
	global_store_dword v[94:95], v96, off
	v_pk_add_f32 v[94:95], v[64:65], 0 op_sel_hi:[1,0]
	v_pk_add_f32 v[96:97], v[74:75], 0 op_sel_hi:[1,0]
	v_pk_add_f32 v[94:95], v[94:95], v[60:61]
	v_pk_add_f32 v[96:97], v[96:97], v[62:63]
	v_cndmask_b32_e64 v100, 0, v94, s[4:5]
	v_cndmask_b32_e64 v101, 0, v96, s[4:5]
	v_cndmask_b32_e64 v104, 0, v95, s[4:5]
	v_cndmask_b32_e64 v105, 0, v97, s[4:5]
	v_pk_add_f32 v[96:97], v[96:97], v[84:85]
	v_pk_add_f32 v[94:95], v[94:95], v[80:81]
	v_pk_add_f32 v[96:97], v[96:97], v[54:55]
	v_pk_add_f32 v[94:95], v[94:95], v[50:51]
	v_cndmask_b32_e64 v105, v105, v97, s[6:7]
	v_cndmask_b32_e64 v104, v104, v95, s[6:7]
	v_cndmask_b32_e64 v101, v101, v96, s[6:7]
	v_cndmask_b32_e64 v100, v100, v94, s[6:7]
	v_pk_add_f32 v[94:95], v[94:95], v[66:67]
	v_pk_add_f32 v[96:97], v[96:97], v[68:69]
	v_pk_add_f32 v[94:95], v[94:95], v[82:83]
	v_pk_add_f32 v[96:97], v[96:97], v[86:87]
	v_pk_add_f32 v[94:95], v[94:95], v[42:43]
	v_pk_add_f32 v[96:97], v[96:97], v[44:45]
	v_pk_add_f32 v[94:95], v[94:95], v[78:79]
	v_pk_add_f32 v[96:97], v[96:97], v[92:93]
	v_pk_add_f32 v[88:89], v[94:95], v[88:89]
	v_pk_add_f32 v[90:91], v[96:97], v[90:91]
	v_cndmask_b32_e64 v100, v100, v94, s[8:9]
	v_cndmask_b32_e64 v104, v104, v95, s[8:9]
	v_pk_add_f32 v[88:89], v[88:89], v[70:71]
	v_pk_add_f32 v[90:91], v[90:91], v[72:73]
	v_add_u32_e32 v94, 20, v144
	v_add_u32_e32 v95, 20, v145
	v_pk_add_f32 v[90:91], v[90:91], v[58:59]
	v_pk_add_f32 v[88:89], v[88:89], v[56:57]
	v_max_i32_e32 v94, 0, v94
	v_min_i32_e32 v95, v95, v136
	v_pk_add_f32 v[88:89], v[88:89], v[48:49]
	v_pk_add_f32 v[90:91], v[90:91], v[52:53]
	v_sub_u32_e32 v94, v95, v94
	v_cndmask_b32_e64 v101, v101, v96, s[8:9]
	v_pk_add_f32 v[90:91], v[90:91], v[18:19]
	v_pk_add_f32 v[88:89], v[88:89], v[16:17]
	v_cvt_f32_i32_e32 v96, v94
	v_pk_add_f32 v[88:89], v[88:89], v[14:15]
	v_pk_add_f32 v[90:91], v[90:91], v[20:21]
	v_pk_add_f32 v[88:89], v[88:89], v[24:25]
	v_pk_add_f32 v[90:91], v[90:91], v[26:27]
	v_pk_add_f32 v[88:89], v[88:89], v[22:23]
	v_pk_add_f32 v[90:91], v[90:91], v[28:29]
	v_cndmask_b32_e64 v94, v104, v89, s[2:3]
	v_cndmask_b32_e64 v89, v101, v90, s[2:3]
	v_rcp_iflag_f32_e32 v90, v96
	v_cndmask_b32_e64 v105, v105, v97, s[8:9]
	v_cndmask_b32_e64 v88, v100, v88, s[2:3]
	v_mov_b32_e32 v96, v60
	v_mov_b32_e32 v97, v62
	v_cndmask_b32_e64 v95, v105, v91, s[2:3]
	v_pk_fma_f32 v[88:89], v[90:91], v[88:89], v[96:97] op_sel_hi:[0,1,1] neg_lo:[0,0,1] neg_hi:[0,0,1]
	v_mov_b32_e32 v96, v61
	v_mov_b32_e32 v97, v63
	v_pk_fma_f32 v[90:91], v[90:91], v[94:95], v[96:97] op_sel_hi:[0,1,1] neg_lo:[0,0,1] neg_hi:[0,0,1]
	v_and_b32_sdwa v95, v88, v135 dst_sel:DWORD dst_unused:UNUSED_PAD src0_sel:WORD_1 src1_sel:DWORD
	v_and_b32_sdwa v94, v89, v135 dst_sel:DWORD dst_unused:UNUSED_PAD src0_sel:WORD_1 src1_sel:DWORD
	v_add3_u32 v88, v88, v95, s0
	v_and_b32_sdwa v95, v90, v135 dst_sel:DWORD dst_unused:UNUSED_PAD src0_sel:WORD_1 src1_sel:DWORD
	v_add3_u32 v89, v89, v94, s0
	v_and_b32_sdwa v94, v91, v135 dst_sel:DWORD dst_unused:UNUSED_PAD src0_sel:WORD_1 src1_sel:DWORD
	v_add3_u32 v90, v90, v95, s0
	v_add3_u32 v91, v91, v94, s0
	v_and_b32_e32 v90, 0xffff0000, v90
	v_and_b32_e32 v91, 0xffff0000, v91
	v_or_b32_sdwa v88, v90, v88 dst_sel:DWORD dst_unused:UNUSED_PAD src0_sel:DWORD src1_sel:WORD_1
	v_lshlrev_b32_e32 v94, 16, v149
	v_sub_f32_e32 v90, v102, v98
	v_or_b32_sdwa v89, v91, v89 dst_sel:DWORD dst_unused:UNUSED_PAD src0_sel:DWORD src1_sel:WORD_1
	v_fma_f32 v90, v4, v90, v98
	v_sub_f32_e32 v91, v94, v98
	v_and_b32_e32 v95, 0xffff0000, v149
	v_fmac_f32_e32 v90, v6, v91
	v_sub_f32_e32 v91, v103, v99
	v_fma_f32 v91, v5, v91, v99
	v_sub_f32_e32 v96, v95, v99
	v_mul_f32_e32 v90, 0xbfb8aa3b, v90
	v_fmac_f32_e32 v91, v7, v96
	v_exp_f32_e32 v90, v90
	v_mul_f32_e32 v91, 0xbfb8aa3b, v91
	v_exp_f32_e32 v91, v91
	v_lshl_add_u64 v[76:77], v[76:77], 0, v[12:13]
	v_add_f32_e32 v90, 1.0, v90
	v_rcp_f32_e32 v90, v90
	global_store_dwordx2 v[76:77], v[88:89], off offset:256
	v_add_f32_e32 v76, 1.0, v91
	v_rcp_f32_e32 v76, v76
	s_nop 0
	s_nop 0
	s_nop 0
	s_nop 0
	s_nop 0
	v_cvt_pk_bf16_f32 v90, v90, v76
	v_mad_i64_i32 v[76:77], s[10:11], v139, s1, v[46:47]
	v_lshl_add_u64 v[88:89], v[76:77], 0, v[2:3]
	global_store_dword v[88:89], v90, off
	v_pk_add_f32 v[88:89], v[60:61], 0 op_sel_hi:[1,0]
	v_pk_add_f32 v[90:91], v[62:63], 0 op_sel_hi:[1,0]
	v_pk_add_f32 v[88:89], v[88:89], v[50:51]
	v_pk_add_f32 v[90:91], v[90:91], v[54:55]
	v_cndmask_b32_e64 v96, 0, v88, s[4:5]
	v_cndmask_b32_e64 v97, 0, v90, s[4:5]
	v_cndmask_b32_e64 v100, 0, v89, s[4:5]
	v_cndmask_b32_e64 v101, 0, v91, s[4:5]
	v_pk_add_f32 v[90:91], v[90:91], v[74:75]
	v_pk_add_f32 v[88:89], v[88:89], v[64:65]
	v_pk_add_f32 v[90:91], v[90:91], v[44:45]
	v_pk_add_f32 v[88:89], v[88:89], v[42:43]
	v_cndmask_b32_e64 v101, v101, v91, s[6:7]
	v_cndmask_b32_e64 v100, v100, v89, s[6:7]
	v_cndmask_b32_e64 v97, v97, v90, s[6:7]
	v_cndmask_b32_e64 v96, v96, v88, s[6:7]
	v_pk_add_f32 v[88:89], v[88:89], v[82:83]
	v_pk_add_f32 v[90:91], v[90:91], v[86:87]
	v_pk_add_f32 v[88:89], v[88:89], v[80:81]
	v_pk_add_f32 v[90:91], v[90:91], v[84:85]
	v_pk_add_f32 v[88:89], v[88:89], v[78:79]
	v_pk_add_f32 v[90:91], v[90:91], v[92:93]
	v_pk_add_f32 v[88:89], v[88:89], v[16:17]
	v_pk_add_f32 v[90:91], v[90:91], v[18:19]
	v_pk_add_f32 v[70:71], v[88:89], v[70:71]
	v_pk_add_f32 v[72:73], v[90:91], v[72:73]
	v_cndmask_b32_e64 v96, v96, v88, s[8:9]
	v_cndmask_b32_e64 v100, v100, v89, s[8:9]
	v_pk_add_f32 v[70:71], v[70:71], v[56:57]
	v_pk_add_f32 v[72:73], v[72:73], v[58:59]
	v_add_u32_e32 v88, 21, v144
	v_add_u32_e32 v89, 21, v145
	v_pk_add_f32 v[72:73], v[72:73], v[52:53]
	v_pk_add_f32 v[70:71], v[70:71], v[48:49]
	v_max_i32_e32 v88, 0, v88
	v_min_i32_e32 v89, v89, v136
	v_pk_add_f32 v[70:71], v[70:71], v[66:67]
	v_pk_add_f32 v[72:73], v[72:73], v[68:69]
	v_sub_u32_e32 v88, v89, v88
	v_cndmask_b32_e64 v97, v97, v90, s[8:9]
	v_pk_add_f32 v[72:73], v[72:73], v[20:21]
	v_pk_add_f32 v[70:71], v[70:71], v[14:15]
	v_cvt_f32_i32_e32 v90, v88
	v_pk_add_f32 v[70:71], v[70:71], v[24:25]
	v_pk_add_f32 v[72:73], v[72:73], v[26:27]
	v_pk_add_f32 v[70:71], v[70:71], v[22:23]
	v_pk_add_f32 v[72:73], v[72:73], v[28:29]
	v_pk_add_f32 v[70:71], v[70:71], v[32:33]
	v_pk_add_f32 v[72:73], v[72:73], v[34:35]
	v_cndmask_b32_e64 v88, v100, v71, s[2:3]
	v_cndmask_b32_e64 v71, v97, v72, s[2:3]
	v_rcp_iflag_f32_e32 v72, v90
	v_cndmask_b32_e64 v101, v101, v91, s[8:9]
	v_cndmask_b32_e64 v70, v96, v70, s[2:3]
	v_mov_b32_e32 v90, v50
	v_mov_b32_e32 v91, v54
	v_cndmask_b32_e64 v89, v101, v73, s[2:3]
	v_pk_fma_f32 v[70:71], v[72:73], v[70:71], v[90:91] op_sel_hi:[0,1,1] neg_lo:[0,0,1] neg_hi:[0,0,1]
	v_mov_b32_e32 v90, v51
	v_mov_b32_e32 v91, v55
	v_pk_fma_f32 v[72:73], v[72:73], v[88:89], v[90:91] op_sel_hi:[0,1,1] neg_lo:[0,0,1] neg_hi:[0,0,1]
	v_and_b32_sdwa v88, v71, v135 dst_sel:DWORD dst_unused:UNUSED_PAD src0_sel:WORD_1 src1_sel:DWORD
	v_and_b32_sdwa v89, v70, v135 dst_sel:DWORD dst_unused:UNUSED_PAD src0_sel:WORD_1 src1_sel:DWORD
	v_add3_u32 v70, v70, v89, s0
	v_add3_u32 v71, v71, v88, s0
	v_and_b32_sdwa v88, v73, v135 dst_sel:DWORD dst_unused:UNUSED_PAD src0_sel:WORD_1 src1_sel:DWORD
	v_and_b32_sdwa v89, v72, v135 dst_sel:DWORD dst_unused:UNUSED_PAD src0_sel:WORD_1 src1_sel:DWORD
	v_add3_u32 v73, v73, v88, s0
	v_add3_u32 v72, v72, v89, s0
	v_and_b32_e32 v73, 0xffff0000, v73
	v_and_b32_e32 v72, 0xffff0000, v72
	v_or_b32_sdwa v71, v73, v71 dst_sel:DWORD dst_unused:UNUSED_PAD src0_sel:DWORD src1_sel:WORD_1
	v_or_b32_sdwa v70, v72, v70 dst_sel:DWORD dst_unused:UNUSED_PAD src0_sel:DWORD src1_sel:WORD_1
	v_lshl_add_u64 v[72:73], v[76:77], 0, v[12:13]
	v_lshlrev_b32_e32 v88, 16, v147
	v_sub_f32_e32 v76, v98, v94
	v_fma_f32 v76, v4, v76, v94
	v_sub_f32_e32 v77, v88, v94
	v_and_b32_e32 v89, 0xffff0000, v147
	v_fmac_f32_e32 v76, v6, v77
	v_sub_f32_e32 v77, v99, v95
	v_fma_f32 v77, v5, v77, v95
	v_sub_f32_e32 v90, v89, v95
	v_mul_f32_e32 v76, 0xbfb8aa3b, v76
	v_fmac_f32_e32 v77, v7, v90
	v_exp_f32_e32 v76, v76
	v_mul_f32_e32 v77, 0xbfb8aa3b, v77
	v_exp_f32_e32 v77, v77
	global_store_dwordx2 v[72:73], v[70:71], off offset:256
	v_add_f32_e32 v76, 1.0, v76
	v_rcp_f32_e32 v76, v76
	v_add_f32_e32 v70, 1.0, v77
	v_rcp_f32_e32 v70, v70
	v_add_u32_e32 v128, s48, v128
	s_nop 0
	s_nop 0
	s_nop 0
	s_nop 0
	s_nop 0
	v_cvt_pk_bf16_f32 v76, v76, v70
	v_mad_i64_i32 v[70:71], s[10:11], v138, s1, v[46:47]
	v_lshl_add_u64 v[72:73], v[70:71], 0, v[2:3]
	global_store_dword v[72:73], v76, off
	v_pk_add_f32 v[72:73], v[50:51], 0 op_sel_hi:[1,0]
	v_pk_add_f32 v[76:77], v[54:55], 0 op_sel_hi:[1,0]
	v_pk_add_f32 v[72:73], v[72:73], v[42:43]
	v_pk_add_f32 v[76:77], v[76:77], v[44:45]
	v_cndmask_b32_e64 v90, 0, v72, s[4:5]
	v_cndmask_b32_e64 v91, 0, v76, s[4:5]
	v_cndmask_b32_e64 v96, 0, v73, s[4:5]
	v_cndmask_b32_e64 v97, 0, v77, s[4:5]
	v_pk_add_f32 v[76:77], v[76:77], v[62:63]
	v_pk_add_f32 v[72:73], v[72:73], v[60:61]
	v_pk_add_f32 v[76:77], v[76:77], v[92:93]
	v_pk_add_f32 v[72:73], v[72:73], v[78:79]
	v_cndmask_b32_e64 v97, v97, v77, s[6:7]
	v_cndmask_b32_e64 v96, v96, v73, s[6:7]
	v_cndmask_b32_e64 v91, v91, v76, s[6:7]
	v_cndmask_b32_e64 v90, v90, v72, s[6:7]
	v_pk_add_f32 v[72:73], v[72:73], v[80:81]
	v_pk_add_f32 v[76:77], v[76:77], v[84:85]
	v_pk_add_f32 v[72:73], v[72:73], v[64:65]
	v_pk_add_f32 v[76:77], v[76:77], v[74:75]
	v_pk_add_f32 v[72:73], v[72:73], v[16:17]
	v_pk_add_f32 v[76:77], v[76:77], v[18:19]
	v_pk_add_f32 v[72:73], v[72:73], v[14:15]
	v_pk_add_f32 v[76:77], v[76:77], v[20:21]
	v_pk_add_f32 v[56:57], v[72:73], v[56:57]
	v_pk_add_f32 v[58:59], v[76:77], v[58:59]
	v_cndmask_b32_e64 v90, v90, v72, s[8:9]
	v_cndmask_b32_e64 v96, v96, v73, s[8:9]
	v_pk_add_f32 v[56:57], v[56:57], v[48:49]
	v_pk_add_f32 v[58:59], v[58:59], v[52:53]
	v_add_u32_e32 v72, 22, v144
	v_add_u32_e32 v73, 22, v145
	v_pk_add_f32 v[58:59], v[58:59], v[68:69]
	v_pk_add_f32 v[56:57], v[56:57], v[66:67]
	v_max_i32_e32 v72, 0, v72
	v_min_i32_e32 v73, v73, v136
	v_pk_add_f32 v[56:57], v[56:57], v[82:83]
	v_pk_add_f32 v[58:59], v[58:59], v[86:87]
	v_sub_u32_e32 v72, v73, v72
	v_cndmask_b32_e64 v91, v91, v76, s[8:9]
	v_pk_add_f32 v[58:59], v[58:59], v[26:27]
	v_pk_add_f32 v[56:57], v[56:57], v[24:25]
	v_cvt_f32_i32_e32 v76, v72
	v_pk_add_f32 v[56:57], v[56:57], v[22:23]
	v_pk_add_f32 v[58:59], v[58:59], v[28:29]
	v_pk_add_f32 v[56:57], v[56:57], v[32:33]
	v_pk_add_f32 v[58:59], v[58:59], v[34:35]
	v_pk_add_f32 v[56:57], v[56:57], v[30:31]
	v_pk_add_f32 v[58:59], v[58:59], v[36:37]
	v_cndmask_b32_e64 v72, v96, v57, s[2:3]
	v_cndmask_b32_e64 v57, v91, v58, s[2:3]
	v_rcp_iflag_f32_e32 v58, v76
	v_cndmask_b32_e64 v97, v97, v77, s[8:9]
	v_cndmask_b32_e64 v56, v90, v56, s[2:3]
	v_mov_b32_e32 v76, v42
	v_mov_b32_e32 v77, v44
	v_cndmask_b32_e64 v73, v97, v59, s[2:3]
	v_pk_fma_f32 v[56:57], v[58:59], v[56:57], v[76:77] op_sel_hi:[0,1,1] neg_lo:[0,0,1] neg_hi:[0,0,1]
	v_mov_b32_e32 v76, v43
	v_mov_b32_e32 v77, v45
	v_pk_fma_f32 v[58:59], v[58:59], v[72:73], v[76:77] op_sel_hi:[0,1,1] neg_lo:[0,0,1] neg_hi:[0,0,1]
	v_and_b32_sdwa v72, v57, v135 dst_sel:DWORD dst_unused:UNUSED_PAD src0_sel:WORD_1 src1_sel:DWORD
	v_and_b32_sdwa v73, v56, v135 dst_sel:DWORD dst_unused:UNUSED_PAD src0_sel:WORD_1 src1_sel:DWORD
	v_add3_u32 v56, v56, v73, s0
	v_add3_u32 v57, v57, v72, s0
	v_and_b32_sdwa v72, v59, v135 dst_sel:DWORD dst_unused:UNUSED_PAD src0_sel:WORD_1 src1_sel:DWORD
	v_and_b32_sdwa v73, v58, v135 dst_sel:DWORD dst_unused:UNUSED_PAD src0_sel:WORD_1 src1_sel:DWORD
	v_add3_u32 v59, v59, v72, s0
	v_add3_u32 v58, v58, v73, s0
	v_and_b32_e32 v59, 0xffff0000, v59
	v_and_b32_e32 v58, 0xffff0000, v58
	v_or_b32_sdwa v57, v59, v57 dst_sel:DWORD dst_unused:UNUSED_PAD src0_sel:DWORD src1_sel:WORD_1
	v_or_b32_sdwa v56, v58, v56 dst_sel:DWORD dst_unused:UNUSED_PAD src0_sel:DWORD src1_sel:WORD_1
	v_lshl_add_u64 v[58:59], v[70:71], 0, v[12:13]
	v_lshlrev_b32_e32 v70, 16, v143
	v_sub_f32_e32 v72, v94, v88
	v_sub_f32_e32 v70, v70, v88
	v_fmac_f32_e32 v88, v4, v72
	v_and_b32_e32 v71, 0xffff0000, v143
	v_fmac_f32_e32 v88, v6, v70
	v_sub_f32_e32 v70, v95, v89
	v_sub_f32_e32 v71, v71, v89
	v_fmac_f32_e32 v89, v5, v70
	v_mul_f32_e32 v70, 0xbfb8aa3b, v88
	v_fmac_f32_e32 v89, v7, v71
	v_exp_f32_e32 v70, v70
	v_mul_f32_e32 v71, 0xbfb8aa3b, v89
	v_exp_f32_e32 v71, v71
	global_store_dwordx2 v[58:59], v[56:57], off offset:256
	v_add_f32_e32 v70, 1.0, v70
	v_rcp_f32_e32 v70, v70
	v_add_f32_e32 v56, 1.0, v71
	v_rcp_f32_e32 v56, v56
	v_mad_i64_i32 v[46:47], s[10:11], v137, s1, v[46:47]
	s_nop 0
	s_nop 0
	s_nop 0
	s_nop 0
	s_nop 0
	v_pk_add_f32 v[42:43], v[42:43], 0 op_sel_hi:[1,0]
	v_cvt_pk_bf16_f32 v58, v70, v56
	v_lshl_add_u64 v[56:57], v[46:47], 0, v[2:3]
	v_pk_add_f32 v[44:45], v[44:45], 0 op_sel_hi:[1,0]
	v_pk_add_f32 v[42:43], v[42:43], v[78:79]
	global_store_dword v[56:57], v58, off
	v_pk_add_f32 v[44:45], v[44:45], v[92:93]
	v_cndmask_b32_e64 v56, 0, v42, s[4:5]
	v_cndmask_b32_e64 v58, 0, v43, s[4:5]
	v_pk_add_f32 v[42:43], v[42:43], v[50:51]
	v_cndmask_b32_e64 v57, 0, v44, s[4:5]
	v_cndmask_b32_e64 v59, 0, v45, s[4:5]
	v_pk_add_f32 v[44:45], v[44:45], v[54:55]
	v_pk_add_f32 v[16:17], v[42:43], v[16:17]
	v_pk_add_f32 v[18:19], v[44:45], v[18:19]
	v_cndmask_b32_e64 v43, v58, v17, s[6:7]
	v_cndmask_b32_e64 v45, v56, v16, s[6:7]
	v_pk_add_f32 v[16:17], v[16:17], v[64:65]
	v_cndmask_b32_e64 v42, v59, v19, s[6:7]
	v_pk_add_f32 v[16:17], v[16:17], v[60:61]
	v_cndmask_b32_e64 v44, v57, v18, s[6:7]
	v_pk_add_f32 v[18:19], v[18:19], v[74:75]
	v_pk_add_f32 v[14:15], v[16:17], v[14:15]
	v_pk_add_f32 v[18:19], v[18:19], v[62:63]
	v_pk_add_f32 v[14:15], v[14:15], v[24:25]
	v_pk_add_f32 v[16:17], v[18:19], v[20:21]
	v_cndmask_b32_e64 v20, v45, v14, s[8:9]
	v_cndmask_b32_e64 v18, v43, v15, s[8:9]
	v_pk_add_f32 v[14:15], v[14:15], v[48:49]
	v_pk_add_f32 v[16:17], v[16:17], v[26:27]
	v_pk_add_f32 v[14:15], v[14:15], v[66:67]
	v_cndmask_b32_e64 v21, v44, v16, s[8:9]
	v_pk_add_f32 v[14:15], v[14:15], v[82:83]
	v_cndmask_b32_e64 v19, v42, v17, s[8:9]
	v_pk_add_f32 v[16:17], v[16:17], v[52:53]
	v_pk_add_f32 v[14:15], v[14:15], v[80:81]
	v_pk_add_f32 v[16:17], v[16:17], v[68:69]
	v_pk_add_f32 v[14:15], v[14:15], v[22:23]
	v_add_u32_e32 v22, 23, v144
	v_add_u32_e32 v23, 23, v145
	v_pk_add_f32 v[16:17], v[16:17], v[86:87]
	v_max_i32_e32 v22, 0, v22
	v_min_i32_e32 v23, v23, v136
	v_pk_add_f32 v[16:17], v[16:17], v[84:85]
	v_sub_u32_e32 v22, v23, v22
	v_pk_add_f32 v[16:17], v[16:17], v[28:29]
	v_cvt_f32_i32_e32 v22, v22
	v_pk_add_f32 v[14:15], v[14:15], v[32:33]
	v_pk_add_f32 v[16:17], v[16:17], v[34:35]
	v_pk_add_f32 v[14:15], v[14:15], v[30:31]
	v_pk_add_f32 v[16:17], v[16:17], v[36:37]
	v_pk_add_f32 v[14:15], v[14:15], v[40:41]
	v_pk_add_f32 v[16:17], v[16:17], v[38:39]
	v_cndmask_b32_e64 v18, v18, v15, s[2:3]
	v_cndmask_b32_e64 v15, v21, v16, s[2:3]
	v_rcp_iflag_f32_e32 v16, v22
	v_cndmask_b32_e64 v14, v20, v14, s[2:3]
	v_mov_b32_e32 v20, v78
	v_mov_b32_e32 v21, v92
	v_cndmask_b32_e64 v19, v19, v17, s[2:3]
	v_pk_fma_f32 v[14:15], v[16:17], v[14:15], v[20:21] op_sel_hi:[0,1,1] neg_lo:[0,0,1] neg_hi:[0,0,1]
	v_mov_b32_e32 v92, v79
	v_pk_fma_f32 v[16:17], v[16:17], v[18:19], v[92:93] op_sel_hi:[0,1,1] neg_lo:[0,0,1] neg_hi:[0,0,1]
	v_and_b32_sdwa v18, v15, v135 dst_sel:DWORD dst_unused:UNUSED_PAD src0_sel:WORD_1 src1_sel:DWORD
	v_and_b32_sdwa v19, v14, v135 dst_sel:DWORD dst_unused:UNUSED_PAD src0_sel:WORD_1 src1_sel:DWORD
	v_add3_u32 v14, v14, v19, s0
	v_add3_u32 v15, v15, v18, s0
	v_and_b32_sdwa v18, v17, v135 dst_sel:DWORD dst_unused:UNUSED_PAD src0_sel:WORD_1 src1_sel:DWORD
	v_and_b32_sdwa v19, v16, v135 dst_sel:DWORD dst_unused:UNUSED_PAD src0_sel:WORD_1 src1_sel:DWORD
	v_add3_u32 v17, v17, v18, s0
	v_add3_u32 v16, v16, v19, s0
	s_movk_i32 s10, 0x40f
	v_and_b32_e32 v17, 0xffff0000, v17
	v_and_b32_e32 v16, 0xffff0000, v16
	v_cmp_lt_i32_e32 vcc, s10, v128
	v_or_b32_sdwa v15, v17, v15 dst_sel:DWORD dst_unused:UNUSED_PAD src0_sel:DWORD src1_sel:WORD_1
	v_or_b32_sdwa v14, v16, v14 dst_sel:DWORD dst_unused:UNUSED_PAD src0_sel:DWORD src1_sel:WORD_1
	v_lshl_add_u64 v[16:17], v[46:47], 0, v[12:13]
	s_or_b64 s[80:81], vcc, s[80:81]
	v_add_u32_e32 v130, s49, v130
	global_store_dwordx2 v[16:17], v[14:15], off offset:256
	s_andn2_b64 exec, exec, s[80:81]
	s_cbranch_execz .LBB0_468

.LBB0_584:
	v_lshl_add_u32 v154, s43, 8, v148
	v_ashrrev_i32_e32 v155, 31, v154
	v_lshlrev_b64 v[156:157], 11, v[154:155]
	s_nop 0
	s_nop 0
	s_nop 0
	s_nop 0
	s_nop 0
	v_cvt_pk_bf16_f32 v126, v126, v127
	s_nop 0
	s_nop 0
	s_nop 0
	s_nop 0
	s_nop 0
	v_cvt_pk_bf16_f32 v127, v128, v129
	s_nop 0
	s_nop 0
	s_nop 0
	s_nop 0
	s_nop 0
	v_cvt_pk_bf16_f32 v128, v122, v123
	s_nop 0
	s_nop 0
	s_nop 0
	s_nop 0
	s_nop 0
	v_cvt_pk_bf16_f32 v129, v124, v125
	s_nop 0
	s_nop 0
	s_nop 0
	s_nop 0
	s_nop 0
	v_cvt_pk_bf16_f32 v118, v118, v119
	s_nop 0
	s_nop 0
	s_nop 0
	s_nop 0
	s_nop 0
	v_cvt_pk_bf16_f32 v119, v120, v121
	s_nop 0
	s_nop 0
	s_nop 0
	s_nop 0
	s_nop 0
	v_cvt_pk_bf16_f32 v120, v110, v111
	s_nop 0
	s_nop 0
	s_nop 0
	s_nop 0
	s_nop 0
	v_lshl_or_b32 v146, s44, 8, v150
	v_cvt_pk_bf16_f32 v121, v112, v113
	v_or_b32_e32 v110, 16, v154
	v_ashrrev_i32_e32 v147, 31, v146
	v_ashrrev_i32_e32 v111, 31, v110
	v_lshl_add_u64 v[156:157], s[54:55], 0, v[156:157]
	v_lshlrev_b64 v[158:159], 1, v[146:147]
	v_lshlrev_b64 v[110:111], 11, v[110:111]
	v_lshl_add_u64 v[146:147], v[156:157], 0, v[158:159]
	v_lshl_add_u64 v[110:111], s[54:55], 0, v[110:111]
	global_store_dwordx4 v[146:147], v[118:121], off offset:256
	s_nop 0
	s_nop 0
	v_lshl_add_u64 v[118:119], v[110:111], 0, v[158:159]
	s_nop 0
	s_nop 0
	s_nop 0
	s_nop 0
	s_nop 0
	v_cvt_pk_bf16_f32 v110, v114, v115
	s_nop 0
	s_nop 0
	s_nop 0
	v_cvt_pk_bf16_f32 v111, v116, v117
	s_nop 0
	s_nop 0
	s_nop 0
	s_nop 0
	s_nop 0
	v_cvt_pk_bf16_f32 v112, v106, v107
	s_nop 0
	s_nop 0
	s_nop 0
	s_nop 0
	s_nop 0
	v_cvt_pk_bf16_f32 v113, v108, v109
	s_nop 0
	s_nop 0
	s_nop 0
	s_nop 0
	s_nop 0
	v_cvt_pk_bf16_f32 v102, v102, v103
	s_nop 0
	s_nop 0
	s_nop 0
	s_nop 0
	s_nop 0
	v_cvt_pk_bf16_f32 v103, v104, v105
	s_nop 0
	s_nop 0
	s_nop 0
	s_nop 0
	s_nop 0
	v_cvt_pk_bf16_f32 v104, v94, v95
	s_nop 0
	s_nop 0
	s_nop 0
	s_nop 0
	s_nop 0
	v_cvt_pk_bf16_f32 v105, v96, v97
	v_or_b32_e32 v94, 32, v154
	v_ashrrev_i32_e32 v95, 31, v94
	v_lshlrev_b64 v[94:95], 11, v[94:95]
	v_lshl_add_u64 v[94:95], s[54:55], 0, v[94:95]
	global_store_dwordx4 v[118:119], v[102:105], off offset:256
	s_nop 0
	s_nop 0
	v_lshl_add_u64 v[102:103], v[94:95], 0, v[158:159]
	s_nop 0
	s_nop 0
	s_nop 0
	s_nop 0
	s_nop 0
	v_cvt_pk_bf16_f32 v94, v98, v99
	s_nop 0
	s_nop 0
	s_nop 0
	v_cvt_pk_bf16_f32 v95, v100, v101
	s_nop 0
	s_nop 0
	s_nop 0
	s_nop 0
	s_nop 0
	v_cvt_pk_bf16_f32 v96, v90, v91
	s_nop 0
	s_nop 0
	s_nop 0
	s_nop 0
	s_nop 0
	v_cvt_pk_bf16_f32 v97, v92, v93
	s_nop 0
	s_nop 0
	s_nop 0
	s_nop 0
	s_nop 0
	v_cvt_pk_bf16_f32 v86, v86, v87
	s_nop 0
	s_nop 0
	s_nop 0
	s_nop 0
	s_nop 0
	v_cvt_pk_bf16_f32 v87, v88, v89
	s_nop 0
	s_nop 0
	s_nop 0
	s_nop 0
	s_nop 0
	v_cvt_pk_bf16_f32 v88, v78, v79
	s_nop 0
	s_nop 0
	s_nop 0
	s_nop 0
	s_nop 0
	v_cvt_pk_bf16_f32 v89, v80, v81
	v_or_b32_e32 v78, 48, v154
	v_ashrrev_i32_e32 v79, 31, v78
	v_lshlrev_b64 v[78:79], 11, v[78:79]
	v_lshl_add_u64 v[78:79], s[54:55], 0, v[78:79]
	global_store_dwordx4 v[102:103], v[86:89], off offset:256
	s_nop 0
	s_nop 0
	v_lshl_add_u64 v[86:87], v[78:79], 0, v[158:159]
	s_nop 0
	s_nop 0
	s_nop 0
	s_nop 0
	s_nop 0
	v_cvt_pk_bf16_f32 v78, v82, v83
	s_nop 0
	s_nop 0
	s_nop 0
	v_cvt_pk_bf16_f32 v79, v84, v85
	s_nop 0
	s_nop 0
	s_nop 0
	s_nop 0
	s_nop 0
	v_cvt_pk_bf16_f32 v80, v74, v75
	s_nop 0
	s_nop 0
	s_nop 0
	s_nop 0
	s_nop 0
	v_cvt_pk_bf16_f32 v81, v76, v77
	s_nop 0
	s_nop 0
	s_nop 0
	s_nop 0
	s_nop 0
	v_cvt_pk_bf16_f32 v70, v70, v71
	s_nop 0
	s_nop 0
	s_nop 0
	s_nop 0
	s_nop 0
	v_cvt_pk_bf16_f32 v71, v72, v73
	s_nop 0
	s_nop 0
	s_nop 0
	s_nop 0
	s_nop 0
	v_cvt_pk_bf16_f32 v72, v66, v67
	s_nop 0
	s_nop 0
	s_nop 0
	s_nop 0
	s_nop 0
	s_nop 0
	s_nop 0
	v_cvt_pk_bf16_f32 v62, v62, v63
	s_nop 0
	s_nop 0
	s_nop 0
	s_nop 0
	s_nop 0
	v_cvt_pk_bf16_f32 v63, v64, v65
	s_nop 0
	s_nop 0
	s_nop 0
	s_nop 0
	s_nop 0
	s_nop 0
	v_cvt_pk_bf16_f32 v64, v58, v59
	s_nop 0
	s_nop 0
	s_nop 0
	s_mov_b64 s[14:15], 0x40000
	s_nop 0
	s_nop 0
	v_cvt_pk_bf16_f32 v73, v68, v69
	v_lshl_add_u64 v[66:67], v[146:147], 0, s[14:15]
	s_nop 0
	s_nop 0
	s_mov_b32 s14, 0x40000
	v_cvt_pk_bf16_f32 v65, v60, v61
	v_add_co_u32_e32 v58, vcc, s14, v146
	s_mov_b64 s[14:15], 0x48000
	s_nop 0
	v_addc_co_u32_e32 v59, vcc, 0, v147, vcc
	global_store_dwordx4 v[58:59], v[62:65], off
	s_nop 0
	s_nop 0
	s_nop 0
	s_nop 0
	s_nop 0
	v_cvt_pk_bf16_f32 v54, v54, v55
	s_nop 0
	s_nop 0
	s_nop 0
	s_nop 0
	s_nop 0
	v_cvt_pk_bf16_f32 v55, v56, v57
	s_nop 0
	s_nop 0
	s_nop 0
	s_nop 0
	s_nop 0
	v_cvt_pk_bf16_f32 v56, v46, v47
	s_nop 0
	s_nop 0
	s_nop 0
	s_nop 0
	s_nop 0
	v_cvt_pk_bf16_f32 v57, v48, v49
	s_nop 0
	s_nop 0
	s_nop 0
	s_nop 0
	s_nop 0
	v_cvt_pk_bf16_f32 v46, v50, v51
	s_nop 0
	s_nop 0
	s_nop 0
	s_nop 0
	s_nop 0
	v_cvt_pk_bf16_f32 v47, v52, v53
	s_nop 0
	s_nop 0
	s_nop 0
	s_nop 0
	s_nop 0
	v_cvt_pk_bf16_f32 v48, v42, v43
	s_nop 0
	s_nop 0
	s_nop 0
	global_store_dwordx4 v[66:67], v[54:57], off offset:256
	s_nop 0
	s_nop 0
	v_lshl_add_u64 v[54:55], v[146:147], 0, s[14:15]
	s_mov_b32 s14, 0x48000
	v_cvt_pk_bf16_f32 v49, v44, v45
	v_add_co_u32_e32 v42, vcc, s14, v146
	s_mov_b64 s[14:15], 0x50000
	s_nop 0
	v_addc_co_u32_e32 v43, vcc, 0, v147, vcc
	global_store_dwordx4 v[42:43], v[46:49], off
	s_nop 0
	s_nop 0
	s_nop 0
	s_nop 0
	s_nop 0
	v_cvt_pk_bf16_f32 v38, v38, v39
	s_nop 0
	s_nop 0
	s_nop 0
	s_nop 0
	s_nop 0
	v_cvt_pk_bf16_f32 v39, v40, v41
	s_nop 0
	s_nop 0
	s_nop 0
	s_nop 0
	s_nop 0
	v_cvt_pk_bf16_f32 v40, v30, v31
	s_nop 0
	s_nop 0
	s_nop 0
	s_nop 0
	s_nop 0
	v_cvt_pk_bf16_f32 v41, v32, v33
	s_nop 0
	s_nop 0
	s_nop 0
	s_nop 0
	s_nop 0
	v_cvt_pk_bf16_f32 v30, v34, v35
	s_nop 0
	s_nop 0
	s_nop 0
	s_nop 0
	s_nop 0
	v_cvt_pk_bf16_f32 v31, v36, v37
	s_nop 0
	s_nop 0
	s_nop 0
	s_nop 0
	s_nop 0
	v_cvt_pk_bf16_f32 v32, v26, v27
	s_nop 0
	s_nop 0
	s_nop 0
	global_store_dwordx4 v[54:55], v[38:41], off offset:256
	s_nop 0
	s_nop 0
	v_lshl_add_u64 v[38:39], v[146:147], 0, s[14:15]
	s_mov_b32 s14, 0x50000
	v_cvt_pk_bf16_f32 v33, v28, v29
	v_add_co_u32_e32 v26, vcc, s14, v146
	s_mov_b64 s[14:15], 0x58000
	s_nop 0
	v_addc_co_u32_e32 v27, vcc, 0, v147, vcc
	global_store_dwordx4 v[26:27], v[30:33], off
	s_nop 0
	s_nop 0
	s_nop 0
	s_nop 0
	s_nop 0
	v_cvt_pk_bf16_f32 v22, v22, v23
	s_nop 0
	s_nop 0
	s_nop 0
	s_nop 0
	s_nop 0
	v_cvt_pk_bf16_f32 v23, v24, v25
	s_nop 0
	s_nop 0
	s_nop 0
	s_nop 0
	s_nop 0
	v_cvt_pk_bf16_f32 v24, v14, v15
	s_nop 0
	s_nop 0
	s_nop 0
	s_nop 0
	s_nop 0
	v_cvt_pk_bf16_f32 v25, v16, v17
	s_nop 0
	s_nop 0
	s_nop 0
	s_nop 0
	s_nop 0
	v_cvt_pk_bf16_f32 v14, v18, v19
	s_nop 0
	s_nop 0
	s_nop 0
	s_nop 0
	s_nop 0
	v_cvt_pk_bf16_f32 v15, v20, v21
	s_nop 0
	s_nop 0
	s_nop 0
	s_nop 0
	s_nop 0
	v_cvt_pk_bf16_f32 v16, v10, v11
	s_nop 0
	s_nop 0
	s_nop 0
	global_store_dwordx4 v[38:39], v[22:25], off offset:256
	s_nop 0
	s_nop 0
	v_lshl_add_u64 v[22:23], v[146:147], 0, s[14:15]
	s_mov_b32 s14, 0x58000
	v_cvt_pk_bf16_f32 v17, v12, v13
	v_add_co_u32_e32 v10, vcc, s14, v146
	global_store_dwordx4 v[146:147], v[126:129], off
	s_nop 0
	v_addc_co_u32_e32 v11, vcc, 0, v147, vcc
	global_store_dwordx4 v[10:11], v[14:17], off
	s_nop 0
	s_nop 0
	s_nop 0
	s_nop 0
	s_nop 0
	v_cvt_pk_bf16_f32 v6, v6, v7
	s_nop 0
	s_nop 0
	s_nop 0
	s_nop 0
	s_nop 0
	v_cvt_pk_bf16_f32 v7, v8, v9
	s_nop 0
	s_nop 0
	s_nop 0
	s_nop 0
	s_nop 0
	v_cvt_pk_bf16_f32 v8, v2, v3
	s_nop 0
	s_nop 0
	s_nop 0
	s_nop 0
	s_nop 0
	v_cvt_pk_bf16_f32 v9, v4, v5
	s_and_b64 vcc, exec, s[2:3]
	s_mov_b64 s[2:3], -1
	global_store_dwordx4 v[118:119], v[110:113], off
	global_store_dwordx4 v[102:103], v[94:97], off
	global_store_dwordx4 v[86:87], v[78:81], off
	global_store_dwordx4 v[86:87], v[70:73], off offset:256
	global_store_dwordx4 v[22:23], v[6:9], off offset:256
	s_cbranch_vccnz .LBB0_569
	s_andn2_b64 vcc, exec, s[6:7]
	s_cbranch_vccnz .LBB0_568
	s_barrier
	s_branch .LBB0_568

.LBB0_1053:
	s_or_b64 exec, exec, s[2:3]
	s_waitcnt vmcnt(0)
	v_add_f32_e32 v54, v34, v35
	v_add_f32_e32 v69, v36, v37
	v_add_f32_e32 v54, v54, v69
	v_add_f32_e32 v69, v38, v39
	v_add_f32_e32 v71, v40, v41
	v_add_f32_e32 v54, 0, v54
	v_add_f32_e32 v69, v69, v71
	v_add_f32_e32 v54, v54, v69
	v_add_f32_e32 v69, v42, v43
	v_add_f32_e32 v71, v44, v45
	v_mov_b32_e32 v78, v47
	v_mov_b32_e32 v79, v48
	v_mov_b32_e32 v80, v46
	v_mov_b32_e32 v81, v49
	v_add_f32_e32 v69, v69, v71
	v_pk_add_f32 v[78:79], v[78:79], v[80:81]
	v_add_f32_e32 v54, v54, v69
	v_add_f32_e32 v69, v78, v79
	v_add_f32_e32 v54, v54, v69
	v_cmp_gt_i32_e32 vcc, s20, v50
	v_mov_b32_e32 v77, v55
	v_add_f32_dpp v54, v54, v54 quad_perm:[1,0,3,2] row_mask:0xf bank_mask:0xf bound_ctrl:1
	v_mov_b32_e32 v73, v55
	v_lshl_add_u64 v[74:75], v[64:65], 0, v[74:75]
	v_add_f32_dpp v54, v54, v54 quad_perm:[2,3,0,1] row_mask:0xf bank_mask:0xf bound_ctrl:1
	s_nop 1
	v_add_f32_dpp v54, v54, v54 row_ror:4 row_mask:0xf bank_mask:0xf bound_ctrl:1
	s_nop 1
	v_add_f32_dpp v54, v54, v54 row_ror:8 row_mask:0xf bank_mask:0xf bound_ctrl:1
	ds_bpermute_b32 v69, v1, v54
	s_waitcnt lgkmcnt(0)
	v_add_f32_e32 v54, v54, v69
	ds_bpermute_b32 v69, v53, v54
	s_waitcnt lgkmcnt(0)
	v_add_f32_e32 v71, v54, v69
	v_cndmask_b32_e64 v54, v85, 0, vcc
	v_lshl_add_u64 v[78:79], s[58:59], 0, v[54:55]
	v_lshl_add_u64 v[106:107], v[78:79], 0, s[14:15]
	v_lshl_add_u64 v[102:103], v[78:79], 0, s[16:17]
	v_lshl_add_u64 v[78:79], v[106:107], 0, v[76:77]
	v_lshl_add_u64 v[80:81], v[102:103], 0, v[76:77]
	global_load_dwordx4 v[76:79], v[78:79], off
	s_nop 0
	global_load_dwordx4 v[80:83], v[80:81], off
	v_fmamk_f32 v35, v71, 0xba800000, v35
	v_fmamk_f32 v34, v71, 0xba800000, v34
	v_fmamk_f32 v37, v71, 0xba800000, v37
	v_fmac_f32_e32 v36, 0xba800000, v71
	v_pk_mul_f32 v[86:87], v[36:37], v[36:37]
	v_pk_mul_f32 v[88:89], v[34:35], v[34:35]
	v_fmamk_f32 v39, v71, 0xba800000, v39
	v_pk_mov_b32 v[90:91], v[88:89], v[86:87] op_sel:[1,0]
	v_mov_b32_e32 v89, v87
	v_pk_add_f32 v[86:87], v[90:91], v[88:89]
	v_fmamk_f32 v38, v71, 0xba800000, v38
	v_fmamk_f32 v41, v71, 0xba800000, v41
	v_fmac_f32_e32 v40, 0xba800000, v71
	v_pk_add_f32 v[94:95], v[86:87], v[86:87] op_sel_hi:[0,1]
	v_pk_mul_f32 v[86:87], v[40:41], v[40:41]
	v_pk_mul_f32 v[88:89], v[38:39], v[38:39]
	v_mov_b32_e32 v69, v55
	v_pk_mov_b32 v[90:91], v[88:89], v[86:87] op_sel:[1,0]
	v_mov_b32_e32 v89, v87
	v_pk_add_f32 v[86:87], v[90:91], v[88:89]
	v_lshl_add_u64 v[90:91], v[102:103], 0, v[68:69]
	v_pk_add_f32 v[96:97], v[86:87], v[86:87] op_sel_hi:[0,1]
	v_lshl_add_u64 v[86:87], v[106:107], 0, v[68:69]
	global_load_dwordx4 v[86:89], v[86:87], off
	s_nop 0
	global_load_dwordx4 v[90:93], v[90:91], off
	v_fmamk_f32 v42, v71, 0xba800000, v42
	v_fmamk_f32 v43, v71, 0xba800000, v43
	v_fmac_f32_e32 v44, 0xba800000, v71
	v_mul_f32_e32 v54, v42, v42
	v_fmamk_f32 v45, v71, 0xba800000, v45
	v_pk_fma_f32 v[98:99], v[42:43], v[42:43], v[54:55] op_sel_hi:[1,1,0]
	v_mul_f32_e32 v54, v44, v44
	v_pk_fma_f32 v[100:101], v[44:45], v[44:45], v[54:55] op_sel_hi:[1,1,0]
	v_fmamk_f32 v49, v71, 0xba800000, v49
	v_fmamk_f32 v48, v71, 0xba800000, v48
	v_fmamk_f32 v47, v71, 0xba800000, v47
	v_fmac_f32_e32 v46, 0xba800000, v71
	v_mul_f32_e32 v98, v46, v46
	v_mul_f32_e32 v100, v47, v47
	v_mul_f32_e32 v94, v48, v48
	v_mul_f32_e32 v96, v49, v49
	v_pk_add_f32 v[98:99], v[98:99], v[100:101]
	v_pk_add_f32 v[94:95], v[94:95], v[96:97]
	v_mov_b32_e32 v71, v55
	v_pk_add_f32 v[94:95], v[98:99], v[94:95]
	v_lshl_add_u64 v[98:99], v[102:103], 0, v[70:71]
	v_add_f32_e32 v54, v94, v95
	v_lshl_add_u64 v[94:95], v[106:107], 0, v[70:71]
	global_load_dwordx4 v[94:97], v[94:95], off
	s_nop 0
	global_load_dwordx4 v[98:101], v[98:99], off
	v_lshl_add_u64 v[102:103], v[102:103], 0, v[72:73]
	global_load_dwordx4 v[102:105], v[102:103], off
	v_lshl_add_u64 v[106:107], v[106:107], 0, v[72:73]
	global_load_dwordx4 v[106:109], v[106:107], off
	v_add_f32_dpp v54, v54, v54 quad_perm:[1,0,3,2] row_mask:0xf bank_mask:0xf bound_ctrl:1
	s_waitcnt vmcnt(6)
	v_pk_add_f32 v[80:81], v[80:81], 1.0 op_sel_hi:[1,0]
	v_add_f32_dpp v54, v54, v54 quad_perm:[2,3,0,1] row_mask:0xf bank_mask:0xf bound_ctrl:1
	v_pk_add_f32 v[82:83], v[82:83], 1.0 op_sel_hi:[1,0]
	s_nop 0
	v_add_f32_dpp v54, v54, v54 row_ror:4 row_mask:0xf bank_mask:0xf bound_ctrl:1
	s_nop 1
	v_add_f32_dpp v54, v54, v54 row_ror:8 row_mask:0xf bank_mask:0xf bound_ctrl:1
	ds_bpermute_b32 v69, v1, v54
	s_waitcnt lgkmcnt(0)
	v_add_f32_e32 v54, v54, v69
	ds_bpermute_b32 v69, v53, v54
	s_waitcnt lgkmcnt(0)
	v_add_f32_e32 v54, v54, v69
	v_fmamk_f32 v54, v54, 0x3a800000, v84
	v_mul_f32_e32 v69, 0x4b800000, v54
	v_cmp_gt_f32_e32 vcc, s21, v54
	s_nop 1
	v_cndmask_b32_e32 v54, v54, v69, vcc
	v_rsq_f32_e32 v54, v54
	s_nop 0
	v_mul_f32_e32 v69, 0x45800000, v54
	v_cndmask_b32_e32 v54, v54, v69, vcc
	v_pk_mul_f32 v[34:35], v[34:35], v[54:55] op_sel_hi:[1,0]
	v_pk_mul_f32 v[36:37], v[36:37], v[54:55] op_sel_hi:[1,0]
	v_pk_fma_f32 v[34:35], v[2:3], v[34:35], v[6:7]
	v_pk_fma_f32 v[36:37], v[4:5], v[36:37], v[8:9]
	global_store_dwordx4 v[74:75], v[34:37], off
	s_nop 1
	v_pk_fma_f32 v[34:35], v[80:81], v[34:35], v[76:77]
	v_pk_fma_f32 v[36:37], v[82:83], v[36:37], v[78:79]
	s_nop 0
	s_nop 0
	s_nop 0
	s_nop 0
	s_nop 0
	v_cvt_pk_bf16_f32 v34, v34, v35
	s_nop 0
	s_nop 0
	s_nop 0
	s_nop 0
	s_nop 0
	v_cvt_pk_bf16_f32 v35, v36, v37
	v_lshlrev_b64 v[36:37], 11, v[50:51]
	v_lshl_add_u64 v[76:77], v[66:67], 0, v[36:37]
	global_store_dwordx2 v[76:77], v[34:35], off
	v_pk_mul_f32 v[34:35], v[38:39], v[54:55] op_sel_hi:[1,0]
	v_pk_mul_f32 v[36:37], v[40:41], v[54:55] op_sel_hi:[1,0]
	v_pk_fma_f32 v[34:35], v[10:11], v[34:35], v[14:15]
	v_pk_fma_f32 v[36:37], v[12:13], v[36:37], v[16:17]
	s_waitcnt vmcnt(6)
	v_pk_add_f32 v[40:41], v[90:91], 1.0 op_sel_hi:[1,0]
	global_store_dwordx4 v[74:75], v[34:37], off offset:1024
	v_pk_add_f32 v[38:39], v[92:93], 1.0 op_sel_hi:[1,0]
	v_add_u32_e32 v50, s13, v50
	v_pk_fma_f32 v[34:35], v[40:41], v[34:35], v[86:87]
	v_pk_fma_f32 v[36:37], v[38:39], v[36:37], v[88:89]
	s_nop 0
	s_nop 0
	s_nop 0
	s_nop 0
	s_nop 0
	v_cvt_pk_bf16_f32 v34, v34, v35
	s_nop 0
	s_nop 0
	s_nop 0
	s_nop 0
	s_nop 0
	v_cvt_pk_bf16_f32 v35, v36, v37
	global_store_dwordx2 v[76:77], v[34:35], off offset:512
	v_pk_mul_f32 v[34:35], v[42:43], v[54:55] op_sel_hi:[1,0]
	v_pk_mul_f32 v[36:37], v[44:45], v[54:55] op_sel_hi:[1,0]
	v_pk_fma_f32 v[34:35], v[18:19], v[34:35], v[22:23]
	v_pk_fma_f32 v[36:37], v[20:21], v[36:37], v[24:25]
	s_waitcnt vmcnt(6)
	v_pk_add_f32 v[40:41], v[98:99], 1.0 op_sel_hi:[1,0]
	global_store_dwordx4 v[74:75], v[34:37], off offset:2048
	v_pk_add_f32 v[38:39], v[100:101], 1.0 op_sel_hi:[1,0]
	v_cmp_lt_i32_e32 vcc, s24, v50
	v_pk_fma_f32 v[34:35], v[40:41], v[34:35], v[94:95]
	v_pk_fma_f32 v[36:37], v[38:39], v[36:37], v[96:97]
	s_nop 0
	s_nop 0
	s_nop 0
	s_nop 0
	s_nop 0
	v_cvt_pk_bf16_f32 v34, v34, v35
	s_nop 0
	s_nop 0
	s_nop 0
	s_nop 0
	s_nop 0
	v_cvt_pk_bf16_f32 v35, v36, v37
	global_store_dwordx2 v[76:77], v[34:35], off offset:1024
	v_pk_mul_f32 v[34:35], v[46:47], v[54:55] op_sel_hi:[1,0]
	v_pk_mul_f32 v[36:37], v[48:49], v[54:55] op_sel_hi:[1,0]
	v_pk_fma_f32 v[34:35], v[26:27], v[34:35], v[30:31]
	v_pk_fma_f32 v[36:37], v[28:29], v[36:37], v[32:33]
	s_waitcnt vmcnt(7)
	v_pk_add_f32 v[40:41], v[102:103], 1.0 op_sel_hi:[1,0]
	global_store_dwordx4 v[74:75], v[34:37], off offset:3072
	v_pk_add_f32 v[38:39], v[104:105], 1.0 op_sel_hi:[1,0]
	s_or_b64 s[10:11], vcc, s[10:11]
	s_waitcnt vmcnt(7)
	v_pk_fma_f32 v[34:35], v[40:41], v[34:35], v[106:107]
	v_pk_fma_f32 v[36:37], v[38:39], v[36:37], v[108:109]
	s_nop 0
	s_nop 0
	s_nop 0
	s_nop 0
	s_nop 0
	v_cvt_pk_bf16_f32 v34, v34, v35
	s_nop 0
	s_nop 0
	s_nop 0
	s_nop 0
	s_nop 0
	v_cvt_pk_bf16_f32 v35, v36, v37
	global_store_dwordx2 v[76:77], v[34:35], off offset:1536
	s_andn2_b64 exec, exec, s[10:11]
	s_cbranch_execz .LBB0_1070

.LBB0_1158:
	v_mul_f32_e32 v153, 0xbfb8aa3b, v126
	v_exp_f32_e32 v154, v153
	v_mul_f32_e32 v153, 0xbfb8aa3b, v127
	v_mul_f32_e32 v156, 0xbfb8aa3b, v128
	v_exp_f32_e32 v155, v153
	v_exp_f32_e32 v157, v156
	v_mul_f32_e32 v156, 0xbfb8aa3b, v129
	v_exp_f32_e32 v158, v156
	v_add_f32_e32 v155, 1.0, v155
	v_mul_f32_e32 v159, 0xbfb8aa3b, v123
	v_mul_f32_e32 v160, 0xbfb8aa3b, v124
	v_rcp_f32_e32 v156, v155
	v_add_f32_e32 v155, 1.0, v157
	v_add_f32_e32 v157, 1.0, v158
	v_mul_f32_e32 v158, 0xbfb8aa3b, v122
	v_exp_f32_e32 v159, v159
	v_exp_f32_e32 v161, v160
	v_mul_f32_e32 v160, 0xbfb8aa3b, v125
	v_exp_f32_e32 v158, v158
	v_exp_f32_e32 v162, v160
	v_add_f32_e32 v154, 1.0, v154
	v_rcp_f32_e32 v154, v154
	v_rcp_f32_e32 v155, v155
	v_rcp_f32_e32 v157, v157
	v_add_f32_e32 v159, 1.0, v159
	v_add_f32_e32 v158, 1.0, v158
	v_rcp_f32_e32 v160, v159
	v_add_f32_e32 v159, 1.0, v161
	v_add_f32_e32 v161, 1.0, v162
	v_rcp_f32_e32 v158, v158
	v_rcp_f32_e32 v159, v159
	v_rcp_f32_e32 v161, v161
	v_mov_b32_e32 v162, v126
	v_mov_b32_e32 v163, v128
	v_mov_b32_e32 v128, v127
	v_pk_mul_f32 v[154:155], v[162:163], v[154:155]
	v_mov_b32_e32 v163, v120
	v_pk_mul_f32 v[126:127], v[128:129], v[156:157]
	v_mov_b32_e32 v120, v119
	v_mov_b32_e32 v162, v118
	v_pk_mul_f32 v[118:119], v[126:127], v[120:121]
	v_mov_b32_e32 v120, v122
	v_mov_b32_e32 v121, v124
	v_mov_b32_e32 v124, v123
	v_pk_mul_f32 v[120:121], v[120:121], v[158:159]
	v_mov_b32_e32 v126, v114
	v_mov_b32_e32 v127, v116
	v_pk_mul_f32 v[122:123], v[124:125], v[160:161]
	v_mov_b32_e32 v116, v115
	v_pk_mul_f32 v[120:121], v[120:121], v[126:127]
	v_pk_mul_f32 v[114:115], v[122:123], v[116:117]
	s_nop 0
	s_nop 0
	v_pk_mul_f32 v[154:155], v[154:155], v[162:163]
	s_nop 0
	s_nop 0
	s_nop 0
	s_nop 0
	s_nop 0
	s_nop 0
	s_nop 0
	s_nop 0
	s_nop 0
	s_nop 0
	s_nop 0
	s_nop 0
	v_lshl_or_b32 v152, s53, 7, v147
	s_nop 0
	s_nop 0
	s_nop 0
	s_nop 0
	v_lshl_add_u32 v151, s24, 8, v1
	v_ashrrev_i32_e32 v153, 31, v152
	s_nop 0
	s_nop 0
	v_cvt_pk_bf16_f32 v121, v121, v115
	v_cvt_pk_bf16_f32 v120, v120, v114
	v_mov_b64_e32 v[114:115], s[8:9]
	v_cvt_pk_bf16_f32 v119, v155, v119
	v_cvt_pk_bf16_f32 v118, v154, v118
	v_mad_i64_i32 v[122:123], s[26:27], v151, s52, v[114:115]
	v_lshlrev_b64 v[116:117], 1, v[152:153]
	v_lshl_add_u64 v[122:123], v[122:123], 0, v[116:117]
	v_mul_f32_e32 v124, 0xbfb8aa3b, v110
	v_exp_f32_e32 v124, v124
	v_mul_f32_e32 v125, 0xbfb8aa3b, v111
	global_store_dwordx4 v[122:123], v[118:121], off
	v_exp_f32_e32 v125, v125
	v_mul_f32_e32 v123, 0xbfb8aa3b, v107
	v_mul_f32_e32 v120, 0xbfb8aa3b, v112
	v_exp_f32_e32 v121, v120
	v_mul_f32_e32 v120, 0xbfb8aa3b, v113
	v_exp_f32_e32 v122, v120
	v_add_f32_e32 v118, 1.0, v124
	v_mul_f32_e32 v124, 0xbfb8aa3b, v108
	v_add_f32_e32 v119, 1.0, v125
	v_exp_f32_e32 v123, v123
	v_exp_f32_e32 v125, v124
	v_mul_f32_e32 v124, 0xbfb8aa3b, v109
	v_rcp_f32_e32 v120, v119
	v_add_f32_e32 v119, 1.0, v121
	v_add_f32_e32 v121, 1.0, v122
	v_mul_f32_e32 v122, 0xbfb8aa3b, v106
	v_exp_f32_e32 v126, v124
	v_exp_f32_e32 v122, v122
	v_rcp_f32_e32 v118, v118
	v_rcp_f32_e32 v119, v119
	v_rcp_f32_e32 v121, v121
	v_add_f32_e32 v123, 1.0, v123
	v_rcp_f32_e32 v124, v123
	v_add_f32_e32 v123, 1.0, v125
	v_add_f32_e32 v125, 1.0, v126
	v_add_f32_e32 v122, 1.0, v122
	v_rcp_f32_e32 v125, v125
	v_rcp_f32_e32 v122, v122
	v_rcp_f32_e32 v123, v123
	v_mov_b32_e32 v126, v110
	v_mov_b32_e32 v127, v112
	v_mov_b32_e32 v112, v111
	v_pk_mul_f32 v[118:119], v[126:127], v[118:119]
	v_mov_b32_e32 v127, v104
	v_pk_mul_f32 v[110:111], v[112:113], v[120:121]
	v_mov_b32_e32 v104, v103
	v_mov_b32_e32 v126, v102
	v_pk_mul_f32 v[102:103], v[110:111], v[104:105]
	v_mov_b32_e32 v105, v108
	v_mov_b32_e32 v108, v107
	v_mov_b32_e32 v104, v106
	v_mov_b32_e32 v111, v100
	v_pk_mul_f32 v[106:107], v[108:109], v[124:125]
	v_mov_b32_e32 v100, v99
	v_pk_mul_f32 v[104:105], v[104:105], v[122:123]
	v_mov_b32_e32 v110, v98
	v_pk_mul_f32 v[98:99], v[106:107], v[100:101]
	v_pk_mul_f32 v[118:119], v[118:119], v[126:127]
	v_pk_mul_f32 v[104:105], v[104:105], v[110:111]
	s_nop 0
	s_nop 0
	s_nop 0
	s_nop 0
	s_nop 0
	s_nop 0
	s_nop 0
	s_nop 0
	s_nop 0
	s_nop 0
	s_nop 0
	s_nop 0
	s_nop 0
	s_nop 0
	s_nop 0
	s_nop 0
	s_nop 0
	s_nop 0
	s_nop 0
	s_nop 0
	v_cvt_pk_bf16_f32 v100, v104, v98
	v_cvt_pk_bf16_f32 v98, v118, v102
	v_or_b32_e32 v102, 16, v151
	v_cvt_pk_bf16_f32 v101, v105, v99
	v_cvt_pk_bf16_f32 v99, v119, v103
	v_mad_i64_i32 v[102:103], s[26:27], v102, s52, v[114:115]
	v_lshl_add_u64 v[102:103], v[102:103], 0, v[116:117]
	v_mul_f32_e32 v104, 0xbfb8aa3b, v94
	v_exp_f32_e32 v104, v104
	v_mul_f32_e32 v105, 0xbfb8aa3b, v95
	global_store_dwordx4 v[102:103], v[98:101], off
	v_exp_f32_e32 v105, v105
	v_mul_f32_e32 v103, 0xbfb8aa3b, v91
	v_mul_f32_e32 v100, 0xbfb8aa3b, v96
	v_exp_f32_e32 v101, v100
	v_mul_f32_e32 v100, 0xbfb8aa3b, v97
	v_exp_f32_e32 v102, v100
	v_add_f32_e32 v98, 1.0, v104
	v_mul_f32_e32 v104, 0xbfb8aa3b, v92
	v_add_f32_e32 v99, 1.0, v105
	v_exp_f32_e32 v103, v103
	v_exp_f32_e32 v105, v104
	v_mul_f32_e32 v104, 0xbfb8aa3b, v93
	v_rcp_f32_e32 v100, v99
	v_add_f32_e32 v99, 1.0, v101
	v_add_f32_e32 v101, 1.0, v102
	v_mul_f32_e32 v102, 0xbfb8aa3b, v90
	v_exp_f32_e32 v106, v104
	v_exp_f32_e32 v102, v102
	v_rcp_f32_e32 v98, v98
	v_rcp_f32_e32 v99, v99
	v_rcp_f32_e32 v101, v101
	v_add_f32_e32 v103, 1.0, v103
	v_rcp_f32_e32 v104, v103
	v_add_f32_e32 v103, 1.0, v105
	v_add_f32_e32 v105, 1.0, v106
	v_add_f32_e32 v102, 1.0, v102
	v_rcp_f32_e32 v105, v105
	v_rcp_f32_e32 v102, v102
	v_rcp_f32_e32 v103, v103
	v_mov_b32_e32 v106, v94
	v_mov_b32_e32 v107, v96
	v_mov_b32_e32 v96, v95
	v_pk_mul_f32 v[98:99], v[106:107], v[98:99]
	v_mov_b32_e32 v107, v88
	v_pk_mul_f32 v[94:95], v[96:97], v[100:101]
	v_mov_b32_e32 v88, v87
	v_mov_b32_e32 v106, v86
	v_pk_mul_f32 v[86:87], v[94:95], v[88:89]
	v_mov_b32_e32 v89, v92
	v_mov_b32_e32 v92, v91
	v_mov_b32_e32 v88, v90
	v_mov_b32_e32 v95, v84
	v_pk_mul_f32 v[90:91], v[92:93], v[104:105]
	v_mov_b32_e32 v84, v83
	v_pk_mul_f32 v[88:89], v[88:89], v[102:103]
	v_mov_b32_e32 v94, v82
	v_pk_mul_f32 v[82:83], v[90:91], v[84:85]
	v_pk_mul_f32 v[98:99], v[98:99], v[106:107]
	v_pk_mul_f32 v[88:89], v[88:89], v[94:95]
	s_nop 0
	s_nop 0
	s_nop 0
	s_nop 0
	s_nop 0
	s_nop 0
	s_nop 0
	s_nop 0
	s_nop 0
	s_nop 0
	s_nop 0
	s_nop 0
	s_nop 0
	s_nop 0
	s_nop 0
	s_nop 0
	s_nop 0
	s_nop 0
	s_nop 0
	s_nop 0
	v_cvt_pk_bf16_f32 v84, v88, v82
	v_cvt_pk_bf16_f32 v82, v98, v86
	v_or_b32_e32 v86, 32, v151
	v_cvt_pk_bf16_f32 v85, v89, v83
	v_cvt_pk_bf16_f32 v83, v99, v87
	v_mad_i64_i32 v[86:87], s[26:27], v86, s52, v[114:115]
	v_lshl_add_u64 v[86:87], v[86:87], 0, v[116:117]
	v_mul_f32_e32 v88, 0xbfb8aa3b, v78
	v_exp_f32_e32 v88, v88
	v_mul_f32_e32 v89, 0xbfb8aa3b, v79
	global_store_dwordx4 v[86:87], v[82:85], off
	v_exp_f32_e32 v89, v89
	v_mul_f32_e32 v87, 0xbfb8aa3b, v75
	v_mul_f32_e32 v84, 0xbfb8aa3b, v80
	v_exp_f32_e32 v85, v84
	v_mul_f32_e32 v84, 0xbfb8aa3b, v81
	v_exp_f32_e32 v86, v84
	v_add_f32_e32 v82, 1.0, v88
	v_mul_f32_e32 v88, 0xbfb8aa3b, v76
	v_add_f32_e32 v83, 1.0, v89
	v_exp_f32_e32 v87, v87
	v_exp_f32_e32 v89, v88
	v_mul_f32_e32 v88, 0xbfb8aa3b, v77
	v_rcp_f32_e32 v84, v83
	v_add_f32_e32 v83, 1.0, v85
	v_add_f32_e32 v85, 1.0, v86
	v_mul_f32_e32 v86, 0xbfb8aa3b, v74
	v_exp_f32_e32 v90, v88
	v_exp_f32_e32 v86, v86
	v_rcp_f32_e32 v82, v82
	v_rcp_f32_e32 v83, v83
	v_rcp_f32_e32 v85, v85
	v_add_f32_e32 v87, 1.0, v87
	v_rcp_f32_e32 v88, v87
	v_add_f32_e32 v87, 1.0, v89
	v_add_f32_e32 v89, 1.0, v90
	v_add_f32_e32 v86, 1.0, v86
	v_rcp_f32_e32 v89, v89
	v_rcp_f32_e32 v86, v86
	v_rcp_f32_e32 v87, v87
	v_mov_b32_e32 v90, v78
	v_mov_b32_e32 v91, v80
	v_mov_b32_e32 v80, v79
	v_pk_mul_f32 v[82:83], v[90:91], v[82:83]
	v_mov_b32_e32 v91, v72
	v_pk_mul_f32 v[78:79], v[80:81], v[84:85]
	v_mov_b32_e32 v72, v71
	v_mov_b32_e32 v90, v70
	v_pk_mul_f32 v[70:71], v[78:79], v[72:73]
	v_mov_b32_e32 v73, v76
	v_mov_b32_e32 v76, v75
	v_mov_b32_e32 v72, v74
	v_mov_b32_e32 v79, v68
	v_pk_mul_f32 v[74:75], v[76:77], v[88:89]
	v_mov_b32_e32 v68, v67
	v_pk_mul_f32 v[72:73], v[72:73], v[86:87]
	v_mov_b32_e32 v78, v66
	v_pk_mul_f32 v[66:67], v[74:75], v[68:69]
	v_pk_mul_f32 v[82:83], v[82:83], v[90:91]
	v_pk_mul_f32 v[72:73], v[72:73], v[78:79]
	s_nop 0
	s_nop 0
	s_nop 0
	s_nop 0
	s_nop 0
	s_nop 0
	s_nop 0
	s_nop 0
	s_nop 0
	s_nop 0
	s_nop 0
	s_nop 0
	s_nop 0
	s_nop 0
	s_nop 0
	s_nop 0
	s_nop 0
	s_nop 0
	s_nop 0
	s_nop 0
	v_cvt_pk_bf16_f32 v68, v72, v66
	v_cvt_pk_bf16_f32 v66, v82, v70
	v_or_b32_e32 v70, 48, v151
	v_cvt_pk_bf16_f32 v69, v73, v67
	v_cvt_pk_bf16_f32 v67, v83, v71
	v_mad_i64_i32 v[70:71], s[26:27], v70, s52, v[114:115]
	v_lshl_add_u64 v[70:71], v[70:71], 0, v[116:117]
	global_store_dwordx4 v[70:71], v[66:69], off
	v_mul_f32_e32 v71, 0xbfb8aa3b, v59
	v_mul_f32_e32 v72, 0xbfb8aa3b, v60
	v_mul_f32_e32 v67, 0xbfb8aa3b, v63
	v_mul_f32_e32 v68, 0xbfb8aa3b, v64
	v_exp_f32_e32 v67, v67
	v_exp_f32_e32 v69, v68
	v_mul_f32_e32 v68, 0xbfb8aa3b, v65
	v_exp_f32_e32 v70, v68
	v_mul_f32_e32 v66, 0xbfb8aa3b, v62
	v_exp_f32_e32 v66, v66
	v_add_f32_e32 v67, 1.0, v67
	v_exp_f32_e32 v71, v71
	v_exp_f32_e32 v73, v72
	v_mul_f32_e32 v72, 0xbfb8aa3b, v61
	v_rcp_f32_e32 v68, v67
	v_add_f32_e32 v67, 1.0, v69
	v_add_f32_e32 v69, 1.0, v70
	v_mul_f32_e32 v70, 0xbfb8aa3b, v58
	v_exp_f32_e32 v74, v72
	v_exp_f32_e32 v70, v70
	v_add_f32_e32 v66, 1.0, v66
	v_rcp_f32_e32 v66, v66
	v_rcp_f32_e32 v67, v67
	v_rcp_f32_e32 v69, v69
	v_add_f32_e32 v71, 1.0, v71
	v_rcp_f32_e32 v72, v71
	v_add_f32_e32 v71, 1.0, v73
	v_add_f32_e32 v73, 1.0, v74
	v_add_f32_e32 v70, 1.0, v70
	v_rcp_f32_e32 v73, v73
	v_rcp_f32_e32 v70, v70
	v_rcp_f32_e32 v71, v71
	v_mov_b32_e32 v74, v62
	v_mov_b32_e32 v75, v64
	v_mov_b32_e32 v64, v63
	v_pk_mul_f32 v[66:67], v[74:75], v[66:67]
	v_mov_b32_e32 v75, v56
	v_pk_mul_f32 v[62:63], v[64:65], v[68:69]
	v_mov_b32_e32 v56, v55
	v_mov_b32_e32 v74, v54
	v_pk_mul_f32 v[54:55], v[62:63], v[56:57]
	v_mov_b32_e32 v57, v60
	v_mov_b32_e32 v60, v59
	v_mov_b32_e32 v56, v58
	v_mov_b32_e32 v63, v52
	v_pk_mul_f32 v[58:59], v[60:61], v[72:73]
	v_mov_b32_e32 v52, v51
	v_pk_mul_f32 v[56:57], v[56:57], v[70:71]
	v_mov_b32_e32 v62, v50
	v_pk_mul_f32 v[50:51], v[58:59], v[52:53]
	v_pk_mul_f32 v[66:67], v[66:67], v[74:75]
	v_pk_mul_f32 v[56:57], v[56:57], v[62:63]
	s_nop 0
	s_nop 0
	s_nop 0
	s_nop 0
	s_nop 0
	s_nop 0
	s_nop 0
	s_nop 0
	s_nop 0
	s_nop 0
	s_nop 0
	s_nop 0
	s_nop 0
	s_nop 0
	s_nop 0
	s_nop 0
	v_add_u32_e32 v76, 0x80, v151
	s_nop 0
	s_nop 0
	s_nop 0
	s_nop 0
	v_cvt_pk_bf16_f32 v53, v57, v51
	v_cvt_pk_bf16_f32 v52, v56, v50
	v_cvt_pk_bf16_f32 v51, v67, v55
	v_cvt_pk_bf16_f32 v50, v66, v54
	v_mad_i64_i32 v[54:55], s[26:27], v76, s52, v[114:115]
	v_lshl_add_u64 v[54:55], v[54:55], 0, v[116:117]
	v_mul_f32_e32 v56, 0xbfb8aa3b, v46
	v_exp_f32_e32 v56, v56
	v_mul_f32_e32 v57, 0xbfb8aa3b, v47
	global_store_dwordx4 v[54:55], v[50:53], off
	v_exp_f32_e32 v57, v57
	v_mul_f32_e32 v55, 0xbfb8aa3b, v43
	v_mul_f32_e32 v52, 0xbfb8aa3b, v48
	v_exp_f32_e32 v53, v52
	v_mul_f32_e32 v52, 0xbfb8aa3b, v49
	v_exp_f32_e32 v54, v52
	v_add_f32_e32 v50, 1.0, v56
	v_mul_f32_e32 v56, 0xbfb8aa3b, v44
	v_add_f32_e32 v51, 1.0, v57
	v_exp_f32_e32 v55, v55
	v_exp_f32_e32 v57, v56
	v_mul_f32_e32 v56, 0xbfb8aa3b, v45
	v_rcp_f32_e32 v52, v51
	v_add_f32_e32 v51, 1.0, v53
	v_add_f32_e32 v53, 1.0, v54
	v_mul_f32_e32 v54, 0xbfb8aa3b, v42
	v_exp_f32_e32 v58, v56
	v_exp_f32_e32 v54, v54
	v_rcp_f32_e32 v50, v50
	v_rcp_f32_e32 v51, v51
	v_rcp_f32_e32 v53, v53
	v_add_f32_e32 v55, 1.0, v55
	v_rcp_f32_e32 v56, v55
	v_add_f32_e32 v55, 1.0, v57
	v_add_f32_e32 v57, 1.0, v58
	v_add_f32_e32 v54, 1.0, v54
	v_rcp_f32_e32 v57, v57
	v_rcp_f32_e32 v54, v54
	v_rcp_f32_e32 v55, v55
	v_mov_b32_e32 v58, v46
	v_mov_b32_e32 v59, v48
	v_mov_b32_e32 v48, v47
	v_pk_mul_f32 v[50:51], v[58:59], v[50:51]
	v_mov_b32_e32 v59, v40
	v_pk_mul_f32 v[46:47], v[48:49], v[52:53]
	v_mov_b32_e32 v40, v39
	v_mov_b32_e32 v58, v38
	v_pk_mul_f32 v[38:39], v[46:47], v[40:41]
	v_mov_b32_e32 v41, v44
	v_mov_b32_e32 v44, v43
	v_mov_b32_e32 v40, v42
	v_mov_b32_e32 v47, v36
	v_pk_mul_f32 v[42:43], v[44:45], v[56:57]
	v_mov_b32_e32 v36, v35
	v_pk_mul_f32 v[40:41], v[40:41], v[54:55]
	v_mov_b32_e32 v46, v34
	v_pk_mul_f32 v[34:35], v[42:43], v[36:37]
	v_pk_mul_f32 v[50:51], v[50:51], v[58:59]
	v_pk_mul_f32 v[40:41], v[40:41], v[46:47]
	s_nop 0
	s_nop 0
	s_nop 0
	s_nop 0
	s_nop 0
	s_nop 0
	s_nop 0
	s_nop 0
	s_nop 0
	s_nop 0
	s_nop 0
	s_nop 0
	s_nop 0
	s_nop 0
	s_nop 0
	s_nop 0
	s_nop 0
	s_nop 0
	s_nop 0
	s_nop 0
	v_cvt_pk_bf16_f32 v36, v40, v34
	v_cvt_pk_bf16_f32 v34, v50, v38
	v_add_u32_e32 v38, 0x90, v151
	v_cvt_pk_bf16_f32 v37, v41, v35
	v_cvt_pk_bf16_f32 v35, v51, v39
	v_mad_i64_i32 v[38:39], s[26:27], v38, s52, v[114:115]
	v_lshl_add_u64 v[38:39], v[38:39], 0, v[116:117]
	v_mul_f32_e32 v40, 0xbfb8aa3b, v30
	v_exp_f32_e32 v40, v40
	v_mul_f32_e32 v41, 0xbfb8aa3b, v31
	global_store_dwordx4 v[38:39], v[34:37], off
	v_exp_f32_e32 v41, v41
	v_mul_f32_e32 v39, 0xbfb8aa3b, v27
	v_mul_f32_e32 v36, 0xbfb8aa3b, v32
	v_exp_f32_e32 v37, v36
	v_mul_f32_e32 v36, 0xbfb8aa3b, v33
	v_exp_f32_e32 v38, v36
	v_add_f32_e32 v34, 1.0, v40
	v_mul_f32_e32 v40, 0xbfb8aa3b, v28
	v_add_f32_e32 v35, 1.0, v41
	v_exp_f32_e32 v39, v39
	v_exp_f32_e32 v41, v40
	v_mul_f32_e32 v40, 0xbfb8aa3b, v29
	v_rcp_f32_e32 v36, v35
	v_add_f32_e32 v35, 1.0, v37
	v_add_f32_e32 v37, 1.0, v38
	v_mul_f32_e32 v38, 0xbfb8aa3b, v26
	v_exp_f32_e32 v42, v40
	v_exp_f32_e32 v38, v38
	v_rcp_f32_e32 v34, v34
	v_rcp_f32_e32 v35, v35
	v_rcp_f32_e32 v37, v37
	v_add_f32_e32 v39, 1.0, v39
	v_rcp_f32_e32 v40, v39
	v_add_f32_e32 v39, 1.0, v41
	v_add_f32_e32 v41, 1.0, v42
	v_add_f32_e32 v38, 1.0, v38
	v_rcp_f32_e32 v41, v41
	v_rcp_f32_e32 v38, v38
	v_rcp_f32_e32 v39, v39
	v_mov_b32_e32 v42, v30
	v_mov_b32_e32 v43, v32
	v_mov_b32_e32 v32, v31
	v_pk_mul_f32 v[34:35], v[42:43], v[34:35]
	v_mov_b32_e32 v43, v24
	v_pk_mul_f32 v[30:31], v[32:33], v[36:37]
	v_mov_b32_e32 v24, v23
	v_mov_b32_e32 v42, v22
	v_pk_mul_f32 v[22:23], v[30:31], v[24:25]
	v_mov_b32_e32 v25, v28
	v_mov_b32_e32 v28, v27
	v_mov_b32_e32 v24, v26
	v_mov_b32_e32 v31, v20
	v_pk_mul_f32 v[26:27], v[28:29], v[40:41]
	v_mov_b32_e32 v20, v19
	v_pk_mul_f32 v[24:25], v[24:25], v[38:39]
	v_mov_b32_e32 v30, v18
	v_pk_mul_f32 v[18:19], v[26:27], v[20:21]
	v_pk_mul_f32 v[34:35], v[34:35], v[42:43]
	v_pk_mul_f32 v[24:25], v[24:25], v[30:31]
	s_nop 0
	s_nop 0
	s_nop 0
	s_nop 0
	s_nop 0
	s_nop 0
	s_nop 0
	s_nop 0
	s_nop 0
	s_nop 0
	s_nop 0
	s_nop 0
	s_nop 0
	s_nop 0
	s_nop 0
	s_nop 0
	s_nop 0
	s_nop 0
	s_nop 0
	s_nop 0
	v_cvt_pk_bf16_f32 v20, v24, v18
	v_cvt_pk_bf16_f32 v18, v34, v22
	v_add_u32_e32 v22, 0xa0, v151
	v_cvt_pk_bf16_f32 v21, v25, v19
	v_cvt_pk_bf16_f32 v19, v35, v23
	v_mad_i64_i32 v[22:23], s[26:27], v22, s52, v[114:115]
	v_lshl_add_u64 v[22:23], v[22:23], 0, v[116:117]
	v_mul_f32_e32 v24, 0xbfb8aa3b, v14
	v_exp_f32_e32 v24, v24
	v_mul_f32_e32 v25, 0xbfb8aa3b, v15
	global_store_dwordx4 v[22:23], v[18:21], off
	v_exp_f32_e32 v25, v25
	v_mul_f32_e32 v23, 0xbfb8aa3b, v11
	v_mul_f32_e32 v20, 0xbfb8aa3b, v16
	v_exp_f32_e32 v21, v20
	v_mul_f32_e32 v20, 0xbfb8aa3b, v17
	v_exp_f32_e32 v22, v20
	v_add_f32_e32 v18, 1.0, v24
	v_mul_f32_e32 v24, 0xbfb8aa3b, v12
	v_add_f32_e32 v19, 1.0, v25
	v_exp_f32_e32 v23, v23
	v_exp_f32_e32 v25, v24
	v_mul_f32_e32 v24, 0xbfb8aa3b, v13
	v_rcp_f32_e32 v20, v19
	v_add_f32_e32 v19, 1.0, v21
	v_add_f32_e32 v21, 1.0, v22
	v_mul_f32_e32 v22, 0xbfb8aa3b, v10
	v_exp_f32_e32 v26, v24
	v_exp_f32_e32 v22, v22
	v_rcp_f32_e32 v18, v18
	v_rcp_f32_e32 v19, v19
	v_rcp_f32_e32 v21, v21
	v_add_f32_e32 v23, 1.0, v23
	v_rcp_f32_e32 v24, v23
	v_add_f32_e32 v23, 1.0, v25
	v_add_f32_e32 v25, 1.0, v26
	v_add_f32_e32 v22, 1.0, v22
	v_rcp_f32_e32 v25, v25
	v_rcp_f32_e32 v22, v22
	v_rcp_f32_e32 v23, v23
	v_mov_b32_e32 v26, v14
	v_mov_b32_e32 v27, v16
	v_mov_b32_e32 v16, v15
	v_pk_mul_f32 v[18:19], v[26:27], v[18:19]
	v_mov_b32_e32 v27, v8
	v_pk_mul_f32 v[14:15], v[16:17], v[20:21]
	v_mov_b32_e32 v8, v7
	v_mov_b32_e32 v26, v6
	v_pk_mul_f32 v[6:7], v[14:15], v[8:9]
	v_mov_b32_e32 v9, v12
	v_mov_b32_e32 v12, v11
	v_mov_b32_e32 v8, v10
	v_mov_b32_e32 v15, v4
	v_pk_mul_f32 v[10:11], v[12:13], v[24:25]
	v_mov_b32_e32 v4, v3
	v_pk_mul_f32 v[8:9], v[8:9], v[22:23]
	v_mov_b32_e32 v14, v2
	v_pk_mul_f32 v[2:3], v[10:11], v[4:5]
	v_pk_mul_f32 v[18:19], v[18:19], v[26:27]
	v_pk_mul_f32 v[8:9], v[8:9], v[14:15]
	s_nop 0
	s_nop 0
	s_nop 0
	s_nop 0
	s_nop 0
	s_nop 0
	s_nop 0
	s_nop 0
	s_nop 0
	s_nop 0
	s_nop 0
	s_nop 0
	s_nop 0
	s_nop 0
	s_nop 0
	s_nop 0
	s_nop 0
	s_nop 0
	s_nop 0
	s_nop 0
	v_cvt_pk_bf16_f32 v4, v8, v2
	v_cvt_pk_bf16_f32 v2, v18, v6
	v_add_u32_e32 v6, 0xb0, v151
	v_cvt_pk_bf16_f32 v5, v9, v3
	v_cvt_pk_bf16_f32 v3, v19, v7
	v_mad_i64_i32 v[6:7], s[26:27], v6, s52, v[114:115]
	v_lshl_add_u64 v[6:7], v[6:7], 0, v[116:117]
	s_andn2_b64 vcc, exec, s[2:3]
	s_mov_b64 s[2:3], -1
	global_store_dwordx4 v[6:7], v[2:5], off
	s_cbranch_vccnz .LBB0_1147
	s_andn2_b64 vcc, exec, s[10:11]
	s_cbranch_vccnz .LBB0_1146
	s_barrier
	s_branch .LBB0_1146

.LBB0_1366:
	s_or_b64 exec, exec, s[2:3]
	s_waitcnt vmcnt(0)
	v_add_f32_e32 v54, v34, v35
	v_add_f32_e32 v69, v36, v37
	v_add_f32_e32 v54, v54, v69
	v_add_f32_e32 v69, v38, v39
	v_add_f32_e32 v71, v40, v41
	v_add_f32_e32 v54, 0, v54
	v_add_f32_e32 v69, v69, v71
	v_add_f32_e32 v54, v54, v69
	v_add_f32_e32 v69, v42, v43
	v_add_f32_e32 v71, v44, v45
	v_mov_b32_e32 v78, v47
	v_mov_b32_e32 v79, v48
	v_mov_b32_e32 v80, v46
	v_mov_b32_e32 v81, v49
	v_add_f32_e32 v69, v69, v71
	v_pk_add_f32 v[78:79], v[78:79], v[80:81]
	v_add_f32_e32 v54, v54, v69
	v_add_f32_e32 v69, v78, v79
	v_add_f32_e32 v54, v54, v69
	v_cmp_gt_i32_e32 vcc, s24, v50
	v_mov_b32_e32 v77, v55
	v_add_f32_dpp v54, v54, v54 quad_perm:[1,0,3,2] row_mask:0xf bank_mask:0xf bound_ctrl:1
	v_mov_b32_e32 v73, v55
	v_lshl_add_u64 v[74:75], v[64:65], 0, v[74:75]
	v_add_f32_dpp v54, v54, v54 quad_perm:[2,3,0,1] row_mask:0xf bank_mask:0xf bound_ctrl:1
	s_nop 1
	v_add_f32_dpp v54, v54, v54 row_ror:4 row_mask:0xf bank_mask:0xf bound_ctrl:1
	s_nop 1
	v_add_f32_dpp v54, v54, v54 row_ror:8 row_mask:0xf bank_mask:0xf bound_ctrl:1
	ds_bpermute_b32 v69, v1, v54
	s_waitcnt lgkmcnt(0)
	v_add_f32_e32 v54, v54, v69
	ds_bpermute_b32 v69, v53, v54
	s_waitcnt lgkmcnt(0)
	v_add_f32_e32 v71, v54, v69
	v_cndmask_b32_e64 v54, v85, 0, vcc
	v_lshl_add_u64 v[86:87], s[12:13], 0, v[54:55]
	v_lshl_add_u64 v[106:107], v[86:87], 0, s[16:17]
	v_lshl_add_u64 v[78:79], v[106:107], 0, v[76:77]
	global_load_dwordx4 v[78:81], v[78:79], off
	v_lshl_add_u64 v[76:77], v[86:87], 0, v[76:77]
	global_load_dwordx4 v[86:89], v[76:77], off
	v_fmamk_f32 v35, v71, 0xba800000, v35
	v_fmamk_f32 v34, v71, 0xba800000, v34
	v_fmamk_f32 v37, v71, 0xba800000, v37
	v_fmac_f32_e32 v36, 0xba800000, v71
	v_pk_mul_f32 v[82:83], v[36:37], v[36:37]
	v_pk_mul_f32 v[90:91], v[34:35], v[34:35]
	v_fmamk_f32 v39, v71, 0xba800000, v39
	v_pk_mov_b32 v[92:93], v[90:91], v[82:83] op_sel:[1,0]
	v_mov_b32_e32 v91, v83
	v_fmamk_f32 v38, v71, 0xba800000, v38
	v_fmamk_f32 v41, v71, 0xba800000, v41
	v_fmac_f32_e32 v40, 0xba800000, v71
	v_pk_add_f32 v[82:83], v[92:93], v[90:91]
	v_pk_mul_f32 v[90:91], v[40:41], v[40:41]
	v_pk_mul_f32 v[92:93], v[38:39], v[38:39]
	v_mov_b32_e32 v69, v55
	v_pk_mov_b32 v[94:95], v[92:93], v[90:91] op_sel:[1,0]
	v_mov_b32_e32 v93, v91
	v_pk_add_f32 v[90:91], v[94:95], v[92:93]
	global_load_dwordx4 v[94:97], v[76:77], off offset:1024
	v_pk_add_f32 v[98:99], v[90:91], v[90:91] op_sel_hi:[0,1]
	v_lshl_add_u64 v[90:91], v[106:107], 0, v[68:69]
	global_load_dwordx4 v[90:93], v[90:91], off
	v_fmamk_f32 v42, v71, 0xba800000, v42
	v_fmamk_f32 v43, v71, 0xba800000, v43
	v_fmac_f32_e32 v44, 0xba800000, v71
	v_mul_f32_e32 v54, v42, v42
	v_fmamk_f32 v45, v71, 0xba800000, v45
	v_pk_fma_f32 v[100:101], v[42:43], v[42:43], v[54:55] op_sel_hi:[1,1,0]
	v_mul_f32_e32 v54, v44, v44
	v_pk_add_f32 v[82:83], v[82:83], v[82:83] op_sel_hi:[0,1]
	v_pk_fma_f32 v[102:103], v[44:45], v[44:45], v[54:55] op_sel_hi:[1,1,0]
	v_fmamk_f32 v49, v71, 0xba800000, v49
	v_fmamk_f32 v48, v71, 0xba800000, v48
	v_fmamk_f32 v47, v71, 0xba800000, v47
	v_fmac_f32_e32 v46, 0xba800000, v71
	v_mul_f32_e32 v100, v46, v46
	v_mul_f32_e32 v102, v47, v47
	v_mul_f32_e32 v82, v48, v48
	v_mul_f32_e32 v98, v49, v49
	v_pk_add_f32 v[100:101], v[100:101], v[102:103]
	v_pk_add_f32 v[82:83], v[82:83], v[98:99]
	v_mov_b32_e32 v71, v55
	v_pk_add_f32 v[82:83], v[100:101], v[82:83]
	global_load_dwordx4 v[102:105], v[76:77], off offset:2048
	v_add_f32_e32 v54, v82, v83
	v_lshl_add_u64 v[82:83], v[106:107], 0, v[70:71]
	global_load_dwordx4 v[98:101], v[82:83], off
	v_lshl_add_u64 v[82:83], v[106:107], 0, v[72:73]
	global_load_dwordx4 v[106:109], v[82:83], off
	global_load_dwordx4 v[110:113], v[76:77], off offset:3072
	v_add_f32_dpp v54, v54, v54 quad_perm:[1,0,3,2] row_mask:0xf bank_mask:0xf bound_ctrl:1
	s_waitcnt vmcnt(7)
	v_pk_add_f32 v[78:79], v[78:79], 1.0 op_sel_hi:[1,0]
	v_add_f32_dpp v54, v54, v54 quad_perm:[2,3,0,1] row_mask:0xf bank_mask:0xf bound_ctrl:1
	v_pk_add_f32 v[76:77], v[80:81], 1.0 op_sel_hi:[1,0]
	s_nop 0
	v_add_f32_dpp v54, v54, v54 row_ror:4 row_mask:0xf bank_mask:0xf bound_ctrl:1
	s_nop 1
	v_add_f32_dpp v54, v54, v54 row_ror:8 row_mask:0xf bank_mask:0xf bound_ctrl:1
	ds_bpermute_b32 v69, v1, v54
	s_waitcnt lgkmcnt(0)
	v_add_f32_e32 v54, v54, v69
	ds_bpermute_b32 v69, v53, v54
	s_waitcnt lgkmcnt(0)
	v_add_f32_e32 v54, v54, v69
	v_fmamk_f32 v54, v54, 0x3a800000, v84
	v_mul_f32_e32 v69, 0x4b800000, v54
	v_cmp_gt_f32_e32 vcc, s25, v54
	s_nop 1
	v_cndmask_b32_e32 v54, v54, v69, vcc
	v_rsq_f32_e32 v54, v54
	s_nop 0
	v_mul_f32_e32 v69, 0x45800000, v54
	v_cndmask_b32_e32 v54, v54, v69, vcc
	v_pk_mul_f32 v[34:35], v[34:35], v[54:55] op_sel_hi:[1,0]
	v_pk_mul_f32 v[36:37], v[36:37], v[54:55] op_sel_hi:[1,0]
	v_pk_fma_f32 v[34:35], v[2:3], v[34:35], v[6:7]
	v_pk_fma_f32 v[36:37], v[4:5], v[36:37], v[8:9]
	global_store_dwordx4 v[74:75], v[34:37], off
	s_waitcnt vmcnt(7)
	s_nop 0
	v_pk_fma_f32 v[34:35], v[78:79], v[34:35], v[86:87]
	v_pk_fma_f32 v[36:37], v[76:77], v[36:37], v[88:89]
	s_nop 0
	s_nop 0
	s_nop 0
	s_nop 0
	s_nop 0
	v_cvt_pk_bf16_f32 v34, v34, v35
	s_nop 0
	s_nop 0
	s_nop 0
	s_nop 0
	s_nop 0
	v_cvt_pk_bf16_f32 v35, v36, v37
	v_lshlrev_b64 v[36:37], 11, v[50:51]
	v_lshl_add_u64 v[76:77], v[66:67], 0, v[36:37]
	global_store_dwordx2 v[76:77], v[34:35], off
	v_pk_mul_f32 v[34:35], v[38:39], v[54:55] op_sel_hi:[1,0]
	v_pk_mul_f32 v[36:37], v[40:41], v[54:55] op_sel_hi:[1,0]
	v_pk_fma_f32 v[34:35], v[10:11], v[34:35], v[14:15]
	v_pk_fma_f32 v[36:37], v[12:13], v[36:37], v[16:17]
	s_waitcnt vmcnt(6)
	v_pk_add_f32 v[40:41], v[90:91], 1.0 op_sel_hi:[1,0]
	global_store_dwordx4 v[74:75], v[34:37], off offset:1024
	v_pk_add_f32 v[38:39], v[92:93], 1.0 op_sel_hi:[1,0]
	v_add_u32_e32 v50, s21, v50
	v_pk_fma_f32 v[34:35], v[40:41], v[34:35], v[94:95]
	v_pk_fma_f32 v[36:37], v[38:39], v[36:37], v[96:97]
	s_nop 0
	s_nop 0
	s_nop 0
	s_nop 0
	s_nop 0
	v_cvt_pk_bf16_f32 v34, v34, v35
	s_nop 0
	s_nop 0
	s_nop 0
	s_nop 0
	s_nop 0
	v_cvt_pk_bf16_f32 v35, v36, v37
	global_store_dwordx2 v[76:77], v[34:35], off offset:512
	v_pk_mul_f32 v[34:35], v[42:43], v[54:55] op_sel_hi:[1,0]
	v_pk_mul_f32 v[36:37], v[44:45], v[54:55] op_sel_hi:[1,0]
	v_pk_fma_f32 v[34:35], v[18:19], v[34:35], v[22:23]
	v_pk_fma_f32 v[36:37], v[20:21], v[36:37], v[24:25]
	s_waitcnt vmcnt(6)
	v_pk_add_f32 v[40:41], v[98:99], 1.0 op_sel_hi:[1,0]
	global_store_dwordx4 v[74:75], v[34:37], off offset:2048
	v_pk_add_f32 v[38:39], v[100:101], 1.0 op_sel_hi:[1,0]
	v_cmp_lt_i32_e32 vcc, s28, v50
	v_pk_fma_f32 v[34:35], v[40:41], v[34:35], v[102:103]
	v_pk_fma_f32 v[36:37], v[38:39], v[36:37], v[104:105]
	s_nop 0
	s_nop 0
	s_nop 0
	s_nop 0
	s_nop 0
	v_cvt_pk_bf16_f32 v34, v34, v35
	s_nop 0
	s_nop 0
	s_nop 0
	s_nop 0
	s_nop 0
	v_cvt_pk_bf16_f32 v35, v36, v37
	global_store_dwordx2 v[76:77], v[34:35], off offset:1024
	v_pk_mul_f32 v[34:35], v[46:47], v[54:55] op_sel_hi:[1,0]
	v_pk_mul_f32 v[36:37], v[48:49], v[54:55] op_sel_hi:[1,0]
	v_pk_fma_f32 v[34:35], v[26:27], v[34:35], v[30:31]
	v_pk_fma_f32 v[36:37], v[28:29], v[36:37], v[32:33]
	s_waitcnt vmcnt(7)
	v_pk_add_f32 v[40:41], v[106:107], 1.0 op_sel_hi:[1,0]
	global_store_dwordx4 v[74:75], v[34:37], off offset:3072
	v_pk_add_f32 v[38:39], v[108:109], 1.0 op_sel_hi:[1,0]
	s_or_b64 s[18:19], vcc, s[18:19]
	s_waitcnt vmcnt(7)
	v_pk_fma_f32 v[34:35], v[40:41], v[34:35], v[110:111]
	v_pk_fma_f32 v[36:37], v[38:39], v[36:37], v[112:113]
	s_nop 0
	s_nop 0
	s_nop 0
	s_nop 0
	s_nop 0
	v_cvt_pk_bf16_f32 v34, v34, v35
	s_nop 0
	s_nop 0
	s_nop 0
	s_nop 0
	s_nop 0
	v_cvt_pk_bf16_f32 v35, v36, v37
	global_store_dwordx2 v[76:77], v[34:35], off offset:1536
	s_andn2_b64 exec, exec, s[18:19]
	s_cbranch_execz .LBB0_1383

.LBB0_1474:
	s_and_b64 vcc, exec, s[30:31]
	s_cbranch_vccz .LBB0_1476
	v_lshlrev_b64 v[150:151], 12, v[146:147]
	s_nop 0
	s_nop 0
	s_nop 0
	s_nop 0
	s_nop 0
	v_cvt_pk_bf16_f32 v126, v126, v127
	s_nop 0
	s_nop 0
	s_nop 0
	s_nop 0
	s_nop 0
	v_cvt_pk_bf16_f32 v127, v128, v129
	s_nop 0
	s_nop 0
	s_nop 0
	s_nop 0
	s_nop 0
	v_cvt_pk_bf16_f32 v128, v122, v123
	s_nop 0
	s_nop 0
	s_nop 0
	s_nop 0
	s_nop 0
	v_cvt_pk_bf16_f32 v129, v124, v125
	s_nop 0
	s_nop 0
	s_nop 0
	s_nop 0
	s_nop 0
	v_cvt_pk_bf16_f32 v118, v118, v119
	s_nop 0
	s_nop 0
	s_nop 0
	s_nop 0
	s_nop 0
	v_cvt_pk_bf16_f32 v119, v120, v121
	s_nop 0
	s_nop 0
	s_nop 0
	s_nop 0
	s_nop 0
	v_cvt_pk_bf16_f32 v120, v110, v111
	s_nop 0
	s_nop 0
	s_nop 0
	s_nop 0
	s_nop 0
	v_cvt_pk_bf16_f32 v121, v112, v113
	v_or_b32_e32 v110, 16, v146
	v_ashrrev_i32_e32 v149, 31, v148
	v_ashrrev_i32_e32 v111, 31, v110
	v_lshl_add_u64 v[150:151], s[88:89], 0, v[150:151]
	v_lshlrev_b64 v[152:153], 1, v[148:149]
	v_lshlrev_b64 v[110:111], 12, v[110:111]
	v_lshl_add_u64 v[148:149], v[150:151], 0, v[152:153]
	v_lshl_add_u64 v[110:111], s[88:89], 0, v[110:111]
	global_store_dwordx4 v[148:149], v[118:121], off offset:256
	s_nop 0
	s_nop 0
	v_lshl_add_u64 v[118:119], v[110:111], 0, v[152:153]
	s_nop 0
	s_nop 0
	s_nop 0
	s_nop 0
	s_nop 0
	v_cvt_pk_bf16_f32 v110, v114, v115
	s_nop 0
	s_nop 0
	s_nop 0
	v_cvt_pk_bf16_f32 v111, v116, v117
	s_nop 0
	s_nop 0
	s_nop 0
	s_nop 0
	s_nop 0
	v_cvt_pk_bf16_f32 v112, v106, v107
	s_nop 0
	s_nop 0
	s_nop 0
	s_nop 0
	s_nop 0
	v_cvt_pk_bf16_f32 v113, v108, v109
	s_nop 0
	s_nop 0
	s_nop 0
	s_nop 0
	s_nop 0
	v_cvt_pk_bf16_f32 v102, v102, v103
	s_nop 0
	s_nop 0
	s_nop 0
	s_nop 0
	s_nop 0
	v_cvt_pk_bf16_f32 v103, v104, v105
	s_nop 0
	s_nop 0
	s_nop 0
	s_nop 0
	s_nop 0
	v_cvt_pk_bf16_f32 v104, v94, v95
	s_nop 0
	s_nop 0
	s_nop 0
	s_nop 0
	s_nop 0
	v_cvt_pk_bf16_f32 v105, v96, v97
	v_or_b32_e32 v94, 32, v146
	v_ashrrev_i32_e32 v95, 31, v94
	v_lshlrev_b64 v[94:95], 12, v[94:95]
	v_lshl_add_u64 v[94:95], s[88:89], 0, v[94:95]
	global_store_dwordx4 v[118:119], v[102:105], off offset:256
	s_nop 0
	s_nop 0
	v_lshl_add_u64 v[102:103], v[94:95], 0, v[152:153]
	s_nop 0
	s_nop 0
	s_nop 0
	s_nop 0
	s_nop 0
	v_cvt_pk_bf16_f32 v94, v98, v99
	s_nop 0
	s_nop 0
	s_nop 0
	v_cvt_pk_bf16_f32 v95, v100, v101
	s_nop 0
	s_nop 0
	s_nop 0
	s_nop 0
	s_nop 0
	v_cvt_pk_bf16_f32 v96, v90, v91
	s_nop 0
	s_nop 0
	s_nop 0
	s_nop 0
	s_nop 0
	v_cvt_pk_bf16_f32 v97, v92, v93
	s_nop 0
	s_nop 0
	s_nop 0
	s_nop 0
	s_nop 0
	v_cvt_pk_bf16_f32 v86, v86, v87
	s_nop 0
	s_nop 0
	s_nop 0
	s_nop 0
	s_nop 0
	v_cvt_pk_bf16_f32 v87, v88, v89
	s_nop 0
	s_nop 0
	s_nop 0
	s_nop 0
	s_nop 0
	v_cvt_pk_bf16_f32 v88, v78, v79
	s_nop 0
	s_nop 0
	s_nop 0
	s_nop 0
	s_nop 0
	v_cvt_pk_bf16_f32 v89, v80, v81
	v_or_b32_e32 v78, 48, v146
	v_ashrrev_i32_e32 v79, 31, v78
	v_lshlrev_b64 v[78:79], 12, v[78:79]
	v_lshl_add_u64 v[78:79], s[88:89], 0, v[78:79]
	global_store_dwordx4 v[102:103], v[86:89], off offset:256
	s_nop 0
	s_nop 0
	v_lshl_add_u64 v[86:87], v[78:79], 0, v[152:153]
	s_nop 0
	s_nop 0
	s_nop 0
	s_nop 0
	s_nop 0
	v_cvt_pk_bf16_f32 v78, v82, v83
	s_nop 0
	s_nop 0
	s_nop 0
	v_cvt_pk_bf16_f32 v79, v84, v85
	s_nop 0
	s_nop 0
	s_nop 0
	s_nop 0
	s_nop 0
	v_cvt_pk_bf16_f32 v80, v74, v75
	s_nop 0
	s_nop 0
	s_nop 0
	s_nop 0
	s_nop 0
	v_cvt_pk_bf16_f32 v81, v76, v77
	s_nop 0
	s_nop 0
	s_nop 0
	s_nop 0
	s_nop 0
	v_cvt_pk_bf16_f32 v70, v70, v71
	s_nop 0
	s_nop 0
	s_nop 0
	s_nop 0
	s_nop 0
	v_cvt_pk_bf16_f32 v71, v72, v73
	s_nop 0
	s_nop 0
	s_nop 0
	s_nop 0
	s_nop 0
	v_cvt_pk_bf16_f32 v72, v66, v67
	v_bfe_u32 v66, v68, 16, 1
	v_add3_u32 v66, v68, v66, s68
	s_nop 0
	s_nop 0
	s_nop 0
	s_nop 0
	s_nop 0
	v_cvt_pk_bf16_f32 v62, v62, v63
	s_nop 0
	s_nop 0
	s_nop 0
	s_nop 0
	s_nop 0
	v_cvt_pk_bf16_f32 v63, v64, v65
	s_nop 0
	s_nop 0
	s_nop 0
	s_nop 0
	s_nop 0
	v_cvt_pk_bf16_f32 v64, v58, v59
	s_nop 0
	s_nop 0
	s_nop 0
	s_nop 0
	s_nop 0
	v_cvt_pk_bf16_f32 v65, v60, v61
	v_add_co_u32_e32 v58, vcc, s73, v148
	v_bfe_u32 v67, v69, 16, 1
	s_nop 0
	v_addc_co_u32_e32 v59, vcc, 0, v149, vcc
	global_store_dwordx4 v[58:59], v[62:65], off
	s_nop 0
	s_nop 0
	s_nop 0
	s_nop 0
	s_nop 0
	v_cvt_pk_bf16_f32 v54, v54, v55
	s_nop 0
	s_nop 0
	s_nop 0
	s_nop 0
	s_nop 0
	v_cvt_pk_bf16_f32 v55, v56, v57
	s_nop 0
	s_nop 0
	s_nop 0
	s_nop 0
	s_nop 0
	v_cvt_pk_bf16_f32 v56, v46, v47
	s_nop 0
	s_nop 0
	s_nop 0
	s_nop 0
	s_nop 0
	v_cvt_pk_bf16_f32 v57, v48, v49
	s_nop 0
	s_nop 0
	s_nop 0
	s_nop 0
	s_nop 0
	v_cvt_pk_bf16_f32 v46, v50, v51
	s_nop 0
	s_nop 0
	s_nop 0
	s_nop 0
	s_nop 0
	v_cvt_pk_bf16_f32 v47, v52, v53
	s_nop 0
	s_nop 0
	s_nop 0
	s_nop 0
	s_nop 0
	v_cvt_pk_bf16_f32 v48, v42, v43
	s_nop 0
	s_nop 0
	s_nop 0
	s_nop 0
	s_nop 0
	v_cvt_pk_bf16_f32 v49, v44, v45
	v_add_co_u32_e32 v42, vcc, s74, v148
	v_lshrrev_b32_e32 v66, 16, v66
	s_nop 0
	v_addc_co_u32_e32 v43, vcc, 0, v149, vcc
	global_store_dwordx4 v[42:43], v[46:49], off
	s_nop 0
	s_nop 0
	s_nop 0
	s_nop 0
	s_nop 0
	v_cvt_pk_bf16_f32 v38, v38, v39
	s_nop 0
	s_nop 0
	s_nop 0
	s_nop 0
	s_nop 0
	v_cvt_pk_bf16_f32 v39, v40, v41
	s_nop 0
	s_nop 0
	s_nop 0
	s_nop 0
	s_nop 0
	v_cvt_pk_bf16_f32 v40, v30, v31
	s_nop 0
	s_nop 0
	s_nop 0
	s_nop 0
	s_nop 0
	v_cvt_pk_bf16_f32 v41, v32, v33
	s_nop 0
	s_nop 0
	s_nop 0
	s_nop 0
	s_nop 0
	v_cvt_pk_bf16_f32 v30, v34, v35
	s_nop 0
	s_nop 0
	s_nop 0
	s_nop 0
	s_nop 0
	v_cvt_pk_bf16_f32 v31, v36, v37
	s_nop 0
	s_nop 0
	s_nop 0
	s_nop 0
	s_nop 0
	v_cvt_pk_bf16_f32 v32, v26, v27
	s_nop 0
	s_nop 0
	s_nop 0
	s_nop 0
	s_nop 0
	v_cvt_pk_bf16_f32 v33, v28, v29
	v_add_co_u32_e32 v26, vcc, s75, v148
	v_add3_u32 v67, v69, v67, s68
	s_nop 0
	v_addc_co_u32_e32 v27, vcc, 0, v149, vcc
	global_store_dwordx4 v[26:27], v[30:33], off
	s_nop 0
	s_nop 0
	s_nop 0
	s_nop 0
	s_nop 0
	v_cvt_pk_bf16_f32 v22, v22, v23
	s_nop 0
	s_nop 0
	s_nop 0
	s_nop 0
	s_nop 0
	v_cvt_pk_bf16_f32 v23, v24, v25
	s_nop 0
	s_nop 0
	s_nop 0
	s_nop 0
	s_nop 0
	v_cvt_pk_bf16_f32 v24, v14, v15
	s_nop 0
	s_nop 0
	s_nop 0
	s_nop 0
	s_nop 0
	v_cvt_pk_bf16_f32 v25, v16, v17
	s_nop 0
	s_nop 0
	s_nop 0
	s_nop 0
	s_nop 0
	v_cvt_pk_bf16_f32 v14, v18, v19
	s_nop 0
	s_nop 0
	s_nop 0
	s_nop 0
	s_nop 0
	v_cvt_pk_bf16_f32 v15, v20, v21
	s_nop 0
	s_nop 0
	s_nop 0
	s_nop 0
	s_nop 0
	v_cvt_pk_bf16_f32 v16, v10, v11
	s_nop 0
	s_nop 0
	s_nop 0
	s_nop 0
	s_nop 0
	v_cvt_pk_bf16_f32 v17, v12, v13
	v_add_co_u32_e32 v10, vcc, s76, v148
	v_and_or_b32 v73, v67, s72, v66
	s_nop 0
	v_addc_co_u32_e32 v11, vcc, 0, v149, vcc
	global_store_dwordx4 v[10:11], v[14:17], off
	s_nop 0
	s_nop 0
	s_nop 0
	s_nop 0
	s_nop 0
	v_cvt_pk_bf16_f32 v6, v6, v7
	s_nop 0
	s_nop 0
	s_nop 0
	s_nop 0
	s_nop 0
	v_cvt_pk_bf16_f32 v7, v8, v9
	s_nop 0
	s_nop 0
	s_nop 0
	s_nop 0
	s_nop 0
	v_lshl_add_u64 v[66:67], v[148:149], 0, s[14:15]
	v_cvt_pk_bf16_f32 v8, v2, v3
	s_nop 0
	global_store_dwordx4 v[66:67], v[54:57], off offset:256
	s_nop 0
	s_nop 0
	v_lshl_add_u64 v[54:55], v[148:149], 0, s[16:17]
	global_store_dwordx4 v[54:55], v[38:41], off offset:256
	s_nop 0
	s_nop 0
	v_lshl_add_u64 v[38:39], v[148:149], 0, s[18:19]
	global_store_dwordx4 v[38:39], v[22:25], off offset:256
	v_cvt_pk_bf16_f32 v9, v4, v5
	global_store_dwordx4 v[148:149], v[126:129], off
	v_lshl_add_u64 v[22:23], v[148:149], 0, s[20:21]
	global_store_dwordx4 v[118:119], v[110:113], off
	global_store_dwordx4 v[102:103], v[94:97], off
	global_store_dwordx4 v[86:87], v[78:81], off
	global_store_dwordx4 v[86:87], v[70:73], off offset:256
	global_store_dwordx4 v[22:23], v[6:9], off offset:256

.LBB0_1575:
	v_sub_f32_e32 v151, v216, v209
	v_mul_f32_e32 v151, 0x3fb8aa3b, v151
	v_exp_f32_e32 v155, v151
	v_sub_f32_e32 v151, v152, v209
	v_mul_f32_e32 v151, 0x3fb8aa3b, v151
	v_sub_f32_e32 v148, v148, v209
	v_exp_f32_e32 v152, v151
	v_sub_f32_e32 v151, v153, v209
	v_mul_f32_e32 v148, 0x3fb8aa3b, v148
	v_mul_f32_e32 v151, 0x3fb8aa3b, v151
	v_exp_f32_e32 v216, v148
	v_sub_f32_e32 v148, v150, v209
	v_exp_f32_e32 v153, v151
	v_sub_f32_e32 v151, v154, v209
	v_mul_f32_e32 v148, 0x3fb8aa3b, v148
	v_mul_f32_e32 v151, 0x3fb8aa3b, v151
	v_sub_f32_e32 v2, v2, v209
	v_exp_f32_e32 v217, v148
	v_sub_f32_e32 v148, v149, v209
	v_exp_f32_e32 v154, v151
	v_mul_f32_e32 v2, 0x3fb8aa3b, v2
	v_mul_f32_e32 v148, 0x3fb8aa3b, v148
	v_exp_f32_e32 v2, v2
	v_exp_f32_e32 v218, v148
	s_nop 0
	s_nop 0
	s_nop 0
	s_nop 0
	s_nop 0
	s_nop 0
	s_nop 0
	s_nop 0
	s_nop 0
	s_nop 0
	s_nop 0
	s_nop 0
	s_nop 0
	s_nop 0
	s_nop 0
	s_nop 0
	s_nop 0
	s_nop 0
	s_nop 0
	s_nop 0
	v_cvt_pk_bf16_f32 v151, v218, v217
	v_cvt_pk_bf16_f32 v150, v2, v216
	v_cvt_pk_bf16_f32 v149, v153, v154
	v_cvt_pk_bf16_f32 v148, v155, v152
	v_add_f32_e32 v155, 0, v155
	v_add_f32_e32 v152, v152, v155
	v_add_f32_e32 v152, v153, v152
	v_add_f32_e32 v152, v154, v152
	v_add_f32_e32 v2, v2, v152
	v_mfma_f32_16x16x32_bf16 v[96:99], v[148:151], v[128:131], v[96:99]
	v_add_f32_e32 v2, v216, v2
	v_add_f32_e32 v2, v218, v2
	v_add_f32_e32 v2, v217, v2
	v_mfma_f32_16x16x32_bf16 v[76:79], v[148:151], v[124:127], v[76:79]
	v_add_f32_e32 v179, v179, v2
	v_mfma_f32_16x16x32_bf16 v[64:67], v[148:151], v[120:123], v[64:67]
	v_mfma_f32_16x16x32_bf16 v[52:55], v[148:151], v[116:119], v[52:55]

.LBB0_1595:
	v_sub_f32_e32 v151, v216, v208
	v_mul_f32_e32 v151, 0x3fb8aa3b, v151
	v_exp_f32_e32 v155, v151
	v_sub_f32_e32 v151, v152, v208
	v_mul_f32_e32 v151, 0x3fb8aa3b, v151
	v_sub_f32_e32 v148, v148, v208
	v_exp_f32_e32 v152, v151
	v_sub_f32_e32 v151, v153, v208
	v_mul_f32_e32 v148, 0x3fb8aa3b, v148
	v_mul_f32_e32 v151, 0x3fb8aa3b, v151
	v_exp_f32_e32 v216, v148
	v_sub_f32_e32 v148, v150, v208
	v_exp_f32_e32 v153, v151
	v_sub_f32_e32 v151, v154, v208
	v_mul_f32_e32 v148, 0x3fb8aa3b, v148
	v_mul_f32_e32 v151, 0x3fb8aa3b, v151
	v_sub_f32_e32 v2, v2, v208
	v_exp_f32_e32 v217, v148
	v_sub_f32_e32 v148, v149, v208
	v_exp_f32_e32 v154, v151
	v_mul_f32_e32 v2, 0x3fb8aa3b, v2
	v_mul_f32_e32 v148, 0x3fb8aa3b, v148
	v_exp_f32_e32 v2, v2
	v_exp_f32_e32 v218, v148
	s_nop 0
	s_nop 0
	s_nop 0
	s_nop 0
	s_nop 0
	s_nop 0
	s_nop 0
	s_nop 0
	s_nop 0
	s_nop 0
	s_nop 0
	s_nop 0
	s_nop 0
	s_nop 0
	s_nop 0
	s_nop 0
	s_nop 0
	s_nop 0
	s_nop 0
	s_nop 0
	v_cvt_pk_bf16_f32 v151, v218, v217
	v_cvt_pk_bf16_f32 v150, v2, v216
	v_cvt_pk_bf16_f32 v149, v153, v154
	v_cvt_pk_bf16_f32 v148, v155, v152
	v_add_f32_e32 v155, 0, v155
	v_add_f32_e32 v152, v152, v155
	v_add_f32_e32 v152, v153, v152
	v_add_f32_e32 v152, v154, v152
	v_add_f32_e32 v2, v2, v152
	v_mfma_f32_16x16x32_bf16 v[48:51], v[148:151], v[128:131], v[48:51]
	v_add_f32_e32 v2, v216, v2
	v_add_f32_e32 v2, v218, v2
	v_add_f32_e32 v2, v217, v2
	v_mfma_f32_16x16x32_bf16 v[44:47], v[148:151], v[124:127], v[44:47]
	v_add_f32_e32 v177, v177, v2
	v_mfma_f32_16x16x32_bf16 v[40:43], v[148:151], v[120:123], v[40:43]
	v_mfma_f32_16x16x32_bf16 v[36:39], v[148:151], v[116:119], v[36:39]

.LBB0_1615:
	v_sub_f32_e32 v151, v216, v207
	v_mul_f32_e32 v151, 0x3fb8aa3b, v151
	v_exp_f32_e32 v155, v151
	v_sub_f32_e32 v151, v152, v207
	v_mul_f32_e32 v151, 0x3fb8aa3b, v151
	v_sub_f32_e32 v148, v148, v207
	v_exp_f32_e32 v152, v151
	v_sub_f32_e32 v151, v153, v207
	v_mul_f32_e32 v148, 0x3fb8aa3b, v148
	v_mul_f32_e32 v151, 0x3fb8aa3b, v151
	v_exp_f32_e32 v216, v148
	v_sub_f32_e32 v148, v150, v207
	v_exp_f32_e32 v153, v151
	v_sub_f32_e32 v151, v154, v207
	v_mul_f32_e32 v148, 0x3fb8aa3b, v148
	v_mul_f32_e32 v151, 0x3fb8aa3b, v151
	v_sub_f32_e32 v2, v2, v207
	v_exp_f32_e32 v217, v148
	v_sub_f32_e32 v148, v149, v207
	v_exp_f32_e32 v154, v151
	v_mul_f32_e32 v2, 0x3fb8aa3b, v2
	v_mul_f32_e32 v148, 0x3fb8aa3b, v148
	v_exp_f32_e32 v2, v2
	v_exp_f32_e32 v218, v148
	s_nop 0
	s_nop 0
	s_nop 0
	s_nop 0
	s_nop 0
	s_nop 0
	s_nop 0
	s_nop 0
	s_nop 0
	s_nop 0
	s_nop 0
	s_nop 0
	s_nop 0
	s_nop 0
	s_nop 0
	s_nop 0
	s_nop 0
	s_nop 0
	s_nop 0
	s_nop 0
	v_cvt_pk_bf16_f32 v151, v218, v217
	v_cvt_pk_bf16_f32 v150, v2, v216
	v_cvt_pk_bf16_f32 v149, v153, v154
	v_cvt_pk_bf16_f32 v148, v155, v152
	v_add_f32_e32 v155, 0, v155
	v_add_f32_e32 v152, v152, v155
	v_add_f32_e32 v152, v153, v152
	v_add_f32_e32 v152, v154, v152
	v_add_f32_e32 v2, v2, v152
	v_mfma_f32_16x16x32_bf16 v[32:35], v[148:151], v[128:131], v[32:35]
	v_add_f32_e32 v2, v216, v2
	v_add_f32_e32 v2, v218, v2
	v_add_f32_e32 v2, v217, v2
	v_mfma_f32_16x16x32_bf16 v[28:31], v[148:151], v[124:127], v[28:31]
	v_add_f32_e32 v175, v175, v2
	v_mfma_f32_16x16x32_bf16 v[24:27], v[148:151], v[120:123], v[24:27]
	v_mfma_f32_16x16x32_bf16 v[20:23], v[148:151], v[116:119], v[20:23]

.LBB0_1635:
	v_sub_f32_e32 v135, v136, v206
	v_mul_f32_e32 v135, 0x3fb8aa3b, v135
	v_exp_f32_e32 v136, v135
	v_sub_f32_e32 v135, v137, v206
	v_mul_f32_e32 v135, 0x3fb8aa3b, v135
	v_sub_f32_e32 v132, v132, v206
	v_exp_f32_e32 v137, v135
	v_sub_f32_e32 v135, v138, v206
	v_mul_f32_e32 v132, 0x3fb8aa3b, v132
	v_mul_f32_e32 v135, 0x3fb8aa3b, v135
	v_exp_f32_e32 v140, v132
	v_sub_f32_e32 v132, v134, v206
	v_exp_f32_e32 v138, v135
	v_sub_f32_e32 v135, v139, v206
	v_mul_f32_e32 v132, 0x3fb8aa3b, v132
	v_mul_f32_e32 v135, 0x3fb8aa3b, v135
	v_sub_f32_e32 v2, v2, v206
	v_exp_f32_e32 v141, v132
	v_sub_f32_e32 v132, v133, v206
	v_exp_f32_e32 v139, v135
	v_mul_f32_e32 v2, 0x3fb8aa3b, v2
	v_mul_f32_e32 v132, 0x3fb8aa3b, v132
	v_exp_f32_e32 v2, v2
	v_exp_f32_e32 v142, v132
	s_nop 0
	s_nop 0
	s_nop 0
	s_nop 0
	s_nop 0
	s_nop 0
	s_nop 0
	s_nop 0
	s_nop 0
	s_nop 0
	s_nop 0
	s_nop 0
	s_nop 0
	s_nop 0
	s_nop 0
	s_nop 0
	s_nop 0
	s_nop 0
	s_nop 0
	s_nop 0
	v_cvt_pk_bf16_f32 v135, v142, v141
	v_cvt_pk_bf16_f32 v134, v2, v140
	v_cvt_pk_bf16_f32 v133, v138, v139
	v_cvt_pk_bf16_f32 v132, v136, v137
	s_nop 1
	v_mfma_f32_16x16x32_bf16 v[16:19], v[132:135], v[128:131], v[16:19]
	v_add_f32_e32 v128, 0, v136
	v_add_f32_e32 v128, v137, v128
	v_add_f32_e32 v128, v138, v128
	v_mfma_f32_16x16x32_bf16 v[12:15], v[132:135], v[124:127], v[12:15]
	v_add_f32_e32 v124, v139, v128
	v_add_f32_e32 v2, v2, v124
	v_add_f32_e32 v2, v140, v2
	v_mfma_f32_16x16x32_bf16 v[8:11], v[132:135], v[120:123], v[8:11]
	v_add_f32_e32 v2, v142, v2
	v_add_f32_e32 v2, v141, v2
	v_add_f32_e32 v173, v173, v2
	v_mfma_f32_16x16x32_bf16 v[4:7], v[132:135], v[116:119], v[4:7]

.LBB0_1648:
	v_sub_f32_e32 v218, v218, v207
	v_sub_f32_e32 v217, v217, v207
	v_mul_f32_e32 v218, 0x3fb8aa3b, v218
	v_sub_f32_e32 v219, v219, v207
	v_sub_f32_e32 v221, v221, v207
	v_sub_f32_e32 v224, v224, v207
	v_mul_f32_e32 v217, 0x3fb8aa3b, v217
	v_exp_f32_e32 v218, v218
	v_mul_f32_e32 v219, 0x3fb8aa3b, v219
	v_sub_f32_e32 v220, v220, v207
	v_mul_f32_e32 v221, 0x3fb8aa3b, v221
	v_sub_f32_e32 v222, v222, v207
	v_sub_f32_e32 v223, v223, v207
	v_mul_f32_e32 v224, 0x3fb8aa3b, v224
	v_exp_f32_e32 v217, v217
	v_exp_f32_e32 v219, v219
	v_mul_f32_e32 v220, 0x3fb8aa3b, v220
	v_exp_f32_e32 v221, v221
	v_mul_f32_e32 v222, 0x3fb8aa3b, v222
	v_mul_f32_e32 v223, 0x3fb8aa3b, v223
	v_exp_f32_e32 v224, v224
	v_exp_f32_e32 v220, v220
	v_exp_f32_e32 v222, v222
	v_exp_f32_e32 v223, v223
	s_nop 0
	s_nop 0
	s_nop 0
	s_nop 0
	s_nop 0
	s_nop 0
	s_nop 0
	s_nop 0
	s_nop 0
	s_nop 0
	s_nop 0
	s_nop 0
	s_nop 0
	s_nop 0
	s_nop 0
	s_nop 0
	s_nop 0
	s_nop 0
	s_nop 0
	s_nop 0
	v_cvt_pk_bf16_f32 v229, v224, v223
	v_cvt_pk_bf16_f32 v228, v221, v222
	v_cvt_pk_bf16_f32 v227, v219, v220
	v_cvt_pk_bf16_f32 v226, v217, v218
	v_mfma_f32_16x16x32_bf16 v[148:151], v[148:151], v[88:91], 0
	s_nop 0
	v_mfma_f32_16x16x32_bf16 v[32:35], v[226:229], v[112:115], v[32:35]
	v_mfma_f32_16x16x32_bf16 v[28:31], v[226:229], v[108:111], v[28:31]
	v_mfma_f32_16x16x32_bf16 v[24:27], v[226:229], v[104:107], v[24:27]
	v_mfma_f32_16x16x32_bf16 v[20:23], v[226:229], v[100:103], v[20:23]
	v_mfma_f32_16x16x32_bf16 v[226:229], v[152:155], v[92:95], v[148:151]
	v_mfma_f32_16x16x32_bf16 v[148:151], v[156:159], v[88:91], 0
	v_mfma_f32_16x16x32_bf16 v[156:159], v[160:163], v[92:95], v[148:151]
	s_nop 5
	v_mul_f32_e32 v155, 0x3e000000, v226
	v_mul_f32_e32 v154, 0x3e000000, v227
	v_mul_f32_e32 v153, 0x3e000000, v228
	v_mul_f32_e32 v152, 0x3e000000, v229
	v_mul_f32_e32 v148, 0x3e000000, v158
	v_mul_f32_e32 v149, 0x3e000000, v159
	v_mul_f32_e32 v151, 0x3e000000, v156
	v_mul_f32_e32 v150, 0x3e000000, v157
	v_max_f32_e32 v158, v148, v149
	v_max_f32_e32 v156, v155, v154
	v_max_f32_e32 v157, v153, v152
	v_max3_f32 v158, v151, v150, v158
	v_max3_f32 v157, v156, v157, v158
	v_add_f32_e32 v156, 0x41000000, v206
	v_cmp_gt_f32_e32 vcc, v157, v156
	s_cbranch_vccz .LBB0_1650
	ds_bpermute_b32 v158, v193, v157
	v_max_f32_e32 v157, v157, v157
	s_waitcnt lgkmcnt(0)
	v_max_f32_e32 v158, v158, v158
	v_max_f32_e32 v157, v157, v158
	ds_bpermute_b32 v158, v194, v157
	s_waitcnt lgkmcnt(0)
	v_max_f32_e32 v158, v158, v158
	v_max_f32_e32 v157, v157, v158
	v_cmp_gt_f32_e32 vcc, v157, v156
	s_nop 1
	v_cndmask_b32_e32 v160, v206, v157, vcc
	v_sub_f32_e32 v156, v206, v160
	v_mul_f32_e32 v156, 0x3fb8aa3b, v156
	v_exp_f32_e32 v161, v156
	v_mov_b32_e32 v206, v160
	ds_bpermute_b32 v156, v195, v161
	ds_bpermute_b32 v158, v197, v161
	ds_bpermute_b32 v159, v198, v161
	ds_bpermute_b32 v157, v196, v161
	v_mul_f32_e32 v173, v173, v161
	s_waitcnt lgkmcnt(1)
	v_pk_mul_f32 v[18:19], v[18:19], v[158:159]
	s_waitcnt lgkmcnt(0)
	v_pk_mul_f32 v[16:17], v[16:17], v[156:157]
	v_pk_mul_f32 v[14:15], v[14:15], v[158:159]
	v_pk_mul_f32 v[12:13], v[12:13], v[156:157]
	v_pk_mul_f32 v[10:11], v[10:11], v[158:159]
	v_pk_mul_f32 v[8:9], v[8:9], v[156:157]
	v_pk_mul_f32 v[6:7], v[6:7], v[158:159]
	v_pk_mul_f32 v[4:5], v[4:5], v[156:157]
.LBB0_1650:
	v_add_f32_e32 v156, 0, v217
	v_add_f32_e32 v156, v218, v156
	v_add_f32_e32 v156, v219, v156
	v_add_f32_e32 v156, v220, v156
	v_add_f32_e32 v156, v221, v156
	v_add_f32_e32 v156, v222, v156
	v_add_f32_e32 v156, v224, v156
	v_add_f32_e32 v156, v223, v156
	v_add_f32_e32 v175, v175, v156
	v_add_f32_e32 v156, 0, v187
	v_add_f32_e32 v156, v210, v156
	v_add_f32_e32 v156, v211, v156
	v_add_f32_e32 v156, v212, v156
	v_add_f32_e32 v156, v213, v156
	v_add_f32_e32 v156, v214, v156
	v_add_f32_e32 v156, v216, v156
	v_sub_f32_e32 v154, v154, v206
	v_sub_f32_e32 v152, v152, v206
	v_add_f32_e32 v156, v215, v156
	v_sub_f32_e32 v155, v155, v206
	v_mul_f32_e32 v154, 0x3fb8aa3b, v154
	v_sub_f32_e32 v153, v153, v206
	v_mul_f32_e32 v152, 0x3fb8aa3b, v152
	v_sub_f32_e32 v151, v151, v206
	v_sub_f32_e32 v148, v148, v206
	v_add_f32_e32 v177, v177, v156
	v_add_f32_e32 v156, 0, v180
	v_mul_f32_e32 v155, 0x3fb8aa3b, v155
	v_exp_f32_e32 v154, v154
	v_mul_f32_e32 v153, 0x3fb8aa3b, v153
	v_exp_f32_e32 v152, v152
	v_mul_f32_e32 v151, 0x3fb8aa3b, v151
	v_sub_f32_e32 v150, v150, v206
	v_sub_f32_e32 v149, v149, v206
	v_mul_f32_e32 v148, 0x3fb8aa3b, v148
	v_add_f32_e32 v156, v181, v156
	v_exp_f32_e32 v155, v155
	v_exp_f32_e32 v153, v153
	v_exp_f32_e32 v157, v151
	v_mul_f32_e32 v150, 0x3fb8aa3b, v150
	v_mul_f32_e32 v149, 0x3fb8aa3b, v149
	v_exp_f32_e32 v160, v148
	v_add_f32_e32 v156, v182, v156
	v_exp_f32_e32 v158, v150
	v_exp_f32_e32 v159, v149
	v_add_f32_e32 v156, v183, v156
	v_add_f32_e32 v156, v184, v156
	s_nop 0
	s_nop 0
	v_add_f32_e32 v156, v185, v156
	s_nop 0
	s_nop 0
	s_nop 0
	s_nop 0
	s_nop 0
	s_nop 0
	v_add_f32_e32 v156, v186, v156
	s_nop 0
	s_nop 0
	s_nop 0
	s_nop 0
	s_nop 0
	s_nop 0
	s_nop 0
	s_nop 0
	s_nop 0
	s_nop 0
	s_nop 0
	s_nop 0
	v_add_f32_e32 v2, v2, v156
	v_cvt_pk_bf16_f32 v151, v160, v159
	v_cvt_pk_bf16_f32 v150, v157, v158
	v_cvt_pk_bf16_f32 v149, v153, v152
	v_cvt_pk_bf16_f32 v148, v155, v154
	v_add_f32_e32 v179, v179, v2
	v_add_f32_e32 v2, 0, v155
	v_add_f32_e32 v2, v154, v2
	v_add_f32_e32 v2, v153, v2
	v_add_f32_e32 v2, v152, v2
	v_add_f32_e32 v2, v157, v2
	v_mfma_f32_16x16x32_bf16 v[16:19], v[148:151], v[112:115], v[16:19]
	v_add_f32_e32 v2, v158, v2
	v_add_f32_e32 v2, v160, v2
	v_add_f32_e32 v2, v159, v2
	v_mfma_f32_16x16x32_bf16 v[12:15], v[148:151], v[108:111], v[12:15]
	s_add_i32 s0, s0, 1
	v_add_f32_e32 v173, v173, v2
	s_cmp_eq_u32 s0, 9
	v_mfma_f32_16x16x32_bf16 v[8:11], v[148:151], v[104:107], v[8:11]
	v_mfma_f32_16x16x32_bf16 v[4:7], v[148:151], v[100:103], v[4:7]
	s_cbranch_scc1 .LBB0_1553
	s_waitcnt lgkmcnt(7)
	v_mov_b64_e32 v[150:151], v[118:119]
	s_waitcnt lgkmcnt(6)
	v_mov_b64_e32 v[154:155], v[122:123]
	s_waitcnt lgkmcnt(5)
	v_mov_b64_e32 v[158:159], v[126:127]
	s_waitcnt lgkmcnt(4)
	v_mov_b64_e32 v[162:163], v[130:131]
	s_waitcnt lgkmcnt(0)
	v_mov_b64_e32 v[100:101], v[144:145]
	v_mov_b64_e32 v[104:105], v[140:141]
	v_mov_b64_e32 v[108:109], v[136:137]
	v_mov_b64_e32 v[112:113], v[132:133]
	v_mov_b64_e32 v[102:103], v[146:147]
	v_mov_b64_e32 v[106:107], v[142:143]
	v_mov_b64_e32 v[110:111], v[138:139]
	v_mov_b64_e32 v[114:115], v[134:135]
	v_mov_b64_e32 v[148:149], v[116:117]
	v_mov_b64_e32 v[152:153], v[120:121]
	v_mov_b64_e32 v[156:157], v[124:125]
	v_mov_b64_e32 v[160:161], v[128:129]
	s_branch .LBB0_1642

.LBB0_1847:
	v_ashrrev_i32_e32 v55, 31, v54
	v_lshlrev_b64 v[92:93], 12, v[54:55]
	v_lshl_add_u64 v[94:95], v[56:57], 0, v[92:93]
	global_load_dwordx4 v[80:83], v[94:95], off
	global_load_dwordx4 v[84:87], v[94:95], off offset:1024
	global_load_dwordx4 v[88:91], v[94:95], off offset:2048
	global_load_dwordx4 v[50:53], v[94:95], off offset:3072
	v_lshl_add_u64 v[92:93], v[58:59], 0, v[92:93]
	s_waitcnt vmcnt(3)
	v_mov_b32_e32 v94, v81
	v_mov_b32_e32 v95, v82
	v_mov_b32_e32 v96, v80
	v_mov_b32_e32 v97, v83
	s_waitcnt vmcnt(2)
	v_mov_b32_e32 v98, v85
	v_mov_b32_e32 v99, v86
	v_mov_b32_e32 v100, v84
	v_mov_b32_e32 v101, v87
	v_pk_add_f32 v[94:95], v[94:95], v[96:97]
	v_pk_add_f32 v[96:97], v[98:99], v[100:101]
	v_add_f32_e32 v100, v94, v95
	v_pk_add_f32 v[94:95], v[96:97], v[96:97] op_sel:[0,1] op_sel_hi:[1,0]
	s_waitcnt vmcnt(1)
	v_add_f32_e32 v102, v88, v89
	v_add_f32_e32 v104, v90, v91
	s_waitcnt vmcnt(0)
	v_mov_b32_e32 v107, v50
	v_mov_b32_e32 v103, v52
	v_mov_b32_e32 v105, v53
	v_add_f32_e32 v106, 0, v100
	v_mov_b32_e32 v95, v51
	v_pk_add_f32 v[98:99], v[102:103], v[104:105]
	v_pk_add_f32 v[94:95], v[106:107], v[94:95]
	s_nop 0
	v_pk_add_f32 v[94:95], v[94:95], v[98:99]
	s_nop 0
	v_add_f32_e32 v94, v94, v95
	s_nop 1
	v_add_f32_dpp v94, v94, v94 quad_perm:[1,0,3,2] row_mask:0xf bank_mask:0xf bound_ctrl:1
	s_nop 1
	v_add_f32_dpp v94, v94, v94 quad_perm:[2,3,0,1] row_mask:0xf bank_mask:0xf bound_ctrl:1
	s_nop 1
	v_add_f32_dpp v94, v94, v94 row_ror:4 row_mask:0xf bank_mask:0xf bound_ctrl:1
	s_nop 1
	v_add_f32_dpp v94, v94, v94 row_ror:8 row_mask:0xf bank_mask:0xf bound_ctrl:1
	ds_bpermute_b32 v95, v78, v94
	s_waitcnt lgkmcnt(0)
	v_add_f32_e32 v94, v94, v95
	ds_bpermute_b32 v95, v79, v94
	s_waitcnt lgkmcnt(0)
	v_add_f32_e32 v94, v94, v95
	v_fmamk_f32 v81, v94, 0xba800000, v81
	v_fmamk_f32 v80, v94, 0xba800000, v80
	v_fmamk_f32 v83, v94, 0xba800000, v83
	v_fmac_f32_e32 v82, 0xba800000, v94
	v_fmamk_f32 v85, v94, 0xba800000, v85
	v_fmamk_f32 v84, v94, 0xba800000, v84
	v_fmamk_f32 v87, v94, 0xba800000, v87
	v_fmac_f32_e32 v86, 0xba800000, v94
	v_fmamk_f32 v89, v94, 0xba800000, v89
	v_fmamk_f32 v88, v94, 0xba800000, v88
	v_fmamk_f32 v91, v94, 0xba800000, v91
	v_fmac_f32_e32 v90, 0xba800000, v94
	v_fmamk_f32 v53, v94, 0xba800000, v53
	v_fmamk_f32 v52, v94, 0xba800000, v52
	v_fmamk_f32 v51, v94, 0xba800000, v51
	v_fmac_f32_e32 v50, 0xba800000, v94
	v_pk_mul_f32 v[94:95], v[82:83], v[82:83]
	v_pk_mul_f32 v[96:97], v[80:81], v[80:81]
	v_pk_mul_f32 v[98:99], v[86:87], v[86:87]
	v_pk_mul_f32 v[100:101], v[84:85], v[84:85]
	v_pk_mov_b32 v[106:107], v[96:97], v[94:95] op_sel:[1,0]
	v_mov_b32_e32 v97, v95
	v_pk_mov_b32 v[94:95], v[100:101], v[98:99] op_sel:[1,0]
	v_mov_b32_e32 v101, v99
	v_mul_f32_e32 v102, v88, v88
	v_mul_f32_e32 v104, v90, v90
	v_pk_add_f32 v[96:97], v[106:107], v[96:97]
	v_pk_add_f32 v[94:95], v[94:95], v[100:101]
	v_pk_fma_f32 v[98:99], v[88:89], v[88:89], v[102:103] op_sel_hi:[1,1,0]
	v_pk_fma_f32 v[102:103], v[90:91], v[90:91], v[104:105] op_sel_hi:[1,1,0]
	v_pk_add_f32 v[96:97], v[96:97], v[96:97] op_sel_hi:[0,1]
	v_pk_add_f32 v[94:95], v[94:95], v[94:95] op_sel_hi:[0,1]
	v_mul_f32_e32 v98, v50, v50
	v_mul_f32_e32 v102, v51, v51
	v_mul_f32_e32 v96, v52, v52
	v_mul_f32_e32 v94, v53, v53
	v_pk_add_f32 v[98:99], v[98:99], v[102:103]
	v_pk_add_f32 v[94:95], v[96:97], v[94:95]
	s_nop 0
	v_pk_add_f32 v[94:95], v[98:99], v[94:95]
	s_nop 0
	v_add_f32_e32 v94, v94, v95
	s_nop 1
	v_add_f32_dpp v94, v94, v94 quad_perm:[1,0,3,2] row_mask:0xf bank_mask:0xf bound_ctrl:1
	s_nop 1
	v_add_f32_dpp v94, v94, v94 quad_perm:[2,3,0,1] row_mask:0xf bank_mask:0xf bound_ctrl:1
	s_nop 1
	v_add_f32_dpp v94, v94, v94 row_ror:4 row_mask:0xf bank_mask:0xf bound_ctrl:1
	s_nop 1
	v_add_f32_dpp v94, v94, v94 row_ror:8 row_mask:0xf bank_mask:0xf bound_ctrl:1
	ds_bpermute_b32 v95, v78, v94
	s_waitcnt lgkmcnt(0)
	v_add_f32_e32 v94, v94, v95
	ds_bpermute_b32 v95, v79, v94
	s_waitcnt lgkmcnt(0)
	v_add_f32_e32 v94, v94, v95
	v_fmamk_f32 v94, v94, 0x3a800000, v1
	v_mul_f32_e32 v95, 0x4b800000, v94
	v_cmp_gt_f32_e32 vcc, s11, v94
	s_nop 1
	v_cndmask_b32_e32 v94, v94, v95, vcc
	v_rsq_f32_e32 v96, v94
	v_lshlrev_b64 v[94:95], 11, v[54:55]
	v_lshl_add_u64 v[94:95], v[60:61], 0, v[94:95]
	v_add_u32_e32 v54, s10, v54
	v_mul_f32_e32 v55, 0x45800000, v96
	v_cndmask_b32_e32 v96, v96, v55, vcc
	v_pk_mul_f32 v[80:81], v[80:81], v[96:97] op_sel_hi:[1,0]
	v_pk_mul_f32 v[82:83], v[82:83], v[96:97] op_sel_hi:[1,0]
	v_pk_mul_f32 v[84:85], v[84:85], v[96:97] op_sel_hi:[1,0]
	v_pk_mul_f32 v[86:87], v[86:87], v[96:97] op_sel_hi:[1,0]
	v_pk_fma_f32 v[82:83], v[4:5], v[82:83], v[8:9]
	v_pk_fma_f32 v[80:81], v[2:3], v[80:81], v[6:7]
	v_pk_fma_f32 v[86:87], v[12:13], v[86:87], v[16:17]
	v_pk_fma_f32 v[84:85], v[10:11], v[84:85], v[14:15]
	global_store_dwordx4 v[92:93], v[80:83], off
	v_pk_mul_f32 v[88:89], v[88:89], v[96:97] op_sel_hi:[1,0]
	v_pk_mul_f32 v[90:91], v[90:91], v[96:97] op_sel_hi:[1,0]
	v_pk_fma_f32 v[82:83], v[62:63], v[82:83], v[20:21]
	v_pk_fma_f32 v[80:81], v[64:65], v[80:81], v[18:19]
	global_store_dwordx4 v[92:93], v[84:87], off offset:1024
	v_bfe_u32 v55, v80, 16, 1
	v_bfe_u32 v97, v81, 16, 1
	v_pk_fma_f32 v[86:87], v[66:67], v[86:87], v[24:25]
	v_pk_fma_f32 v[84:85], v[68:69], v[84:85], v[22:23]
	v_bfe_u32 v98, v82, 16, 1
	v_pk_fma_f32 v[90:91], v[36:37], v[90:91], v[40:41]
	v_pk_fma_f32 v[88:89], v[34:35], v[88:89], v[38:39]
	v_bfe_u32 v99, v83, 16, 1
	v_bfe_u32 v100, v84, 16, 1
	v_bfe_u32 v101, v85, 16, 1
	s_nop 0
	v_add3_u32 v55, v80, v55, s12
	v_add3_u32 v80, v81, v97, s12
	v_add3_u32 v81, v82, v98, s12
	global_store_dwordx4 v[92:93], v[88:91], off offset:2048
	s_nop 0
	v_add3_u32 v82, v83, v99, s12
	v_pk_fma_f32 v[90:91], v[70:71], v[90:91], v[28:29]
	v_add3_u32 v83, v84, v100, s12
	v_add3_u32 v84, v85, v101, s12
	s_nop 0
	v_lshrrev_b32_e32 v55, 16, v55
	v_lshrrev_b32_e32 v81, 16, v81
	s_nop 0
	v_lshrrev_b32_e32 v83, 16, v83
	s_nop 0
	v_and_or_b32 v80, v80, s13, v55
	v_and_or_b32 v81, v82, s13, v81
	s_nop 0
	v_pk_mul_f32 v[50:51], v[50:51], v[96:97] op_sel_hi:[1,0]
	v_pk_mul_f32 v[52:53], v[52:53], v[96:97] op_sel_hi:[1,0]
	v_and_or_b32 v82, v84, s13, v83
	v_cvt_pk_bf16_f32 v83, v86, v87
	global_store_dwordx2 v[94:95], v[80:81], off
	global_store_dwordx2 v[94:95], v[82:83], off offset:512
	s_nop 0
	s_nop 0
	v_pk_fma_f32 v[52:53], v[44:45], v[52:53], v[48:49]
	v_pk_fma_f32 v[50:51], v[42:43], v[50:51], v[46:47]
	s_nop 0
	s_nop 0
	global_store_dwordx4 v[92:93], v[50:53], off offset:3072
	v_cvt_pk_bf16_f32 v81, v90, v91
	v_pk_fma_f32 v[88:89], v[72:73], v[88:89], v[26:27]
	v_pk_fma_f32 v[50:51], v[76:77], v[50:51], v[30:31]
	v_pk_fma_f32 v[52:53], v[74:75], v[52:53], v[32:33]
	s_nop 0
	s_nop 0
	s_nop 0
	s_nop 0
	s_nop 0
	s_nop 0
	v_cvt_pk_bf16_f32 v50, v50, v51
	s_nop 0
	s_nop 0
	s_nop 0
	s_nop 0
	s_nop 0
	s_nop 0
	s_nop 0
	s_nop 0
	s_nop 0
	v_cmp_lt_i32_e32 vcc, s14, v54
	v_cvt_pk_bf16_f32 v80, v88, v89
	v_cvt_pk_bf16_f32 v51, v52, v53
	s_or_b64 s[4:5], vcc, s[4:5]
	global_store_dwordx2 v[94:95], v[80:81], off offset:1024
	global_store_dwordx2 v[94:95], v[50:51], off offset:1536
	s_andn2_b64 exec, exec, s[4:5]
	s_cbranch_execnz .LBB0_1847

.LBB0_1928:
	v_mul_f32_e32 v153, 0xbfb8aa3b, v126
	v_exp_f32_e32 v154, v153
	v_mul_f32_e32 v153, 0xbfb8aa3b, v127
	v_mul_f32_e32 v156, 0xbfb8aa3b, v128
	v_exp_f32_e32 v155, v153
	v_exp_f32_e32 v157, v156
	v_mul_f32_e32 v156, 0xbfb8aa3b, v129
	v_exp_f32_e32 v158, v156
	v_add_f32_e32 v155, 1.0, v155
	v_mul_f32_e32 v159, 0xbfb8aa3b, v123
	v_mul_f32_e32 v160, 0xbfb8aa3b, v124
	v_rcp_f32_e32 v156, v155
	v_add_f32_e32 v155, 1.0, v157
	v_add_f32_e32 v157, 1.0, v158
	v_mul_f32_e32 v158, 0xbfb8aa3b, v122
	v_exp_f32_e32 v159, v159
	v_exp_f32_e32 v161, v160
	v_mul_f32_e32 v160, 0xbfb8aa3b, v125
	v_exp_f32_e32 v158, v158
	v_exp_f32_e32 v162, v160
	v_add_f32_e32 v154, 1.0, v154
	v_rcp_f32_e32 v154, v154
	v_rcp_f32_e32 v155, v155
	v_rcp_f32_e32 v157, v157
	v_add_f32_e32 v159, 1.0, v159
	v_add_f32_e32 v158, 1.0, v158
	v_rcp_f32_e32 v160, v159
	v_add_f32_e32 v159, 1.0, v161
	v_add_f32_e32 v161, 1.0, v162
	v_rcp_f32_e32 v158, v158
	v_rcp_f32_e32 v159, v159
	v_rcp_f32_e32 v161, v161
	v_mov_b32_e32 v162, v126
	v_mov_b32_e32 v163, v128
	v_mov_b32_e32 v128, v127
	v_pk_mul_f32 v[154:155], v[162:163], v[154:155]
	v_mov_b32_e32 v163, v120
	v_pk_mul_f32 v[126:127], v[128:129], v[156:157]
	v_mov_b32_e32 v120, v119
	v_mov_b32_e32 v162, v118
	v_pk_mul_f32 v[118:119], v[126:127], v[120:121]
	v_mov_b32_e32 v120, v122
	v_mov_b32_e32 v121, v124
	v_mov_b32_e32 v124, v123
	v_pk_mul_f32 v[120:121], v[120:121], v[158:159]
	v_mov_b32_e32 v126, v114
	v_mov_b32_e32 v127, v116
	v_pk_mul_f32 v[122:123], v[124:125], v[160:161]
	v_mov_b32_e32 v116, v115
	v_pk_mul_f32 v[120:121], v[120:121], v[126:127]
	v_pk_mul_f32 v[114:115], v[122:123], v[116:117]
	s_nop 0
	s_nop 0
	v_pk_mul_f32 v[154:155], v[154:155], v[162:163]
	s_nop 0
	s_nop 0
	s_nop 0
	s_nop 0
	s_nop 0
	s_nop 0
	s_nop 0
	s_nop 0
	s_nop 0
	s_nop 0
	s_nop 0
	s_nop 0
	v_lshl_or_b32 v152, s52, 7, v147
	s_nop 0
	s_nop 0
	s_nop 0
	s_nop 0
	v_lshl_add_u32 v151, s22, 8, v1
	v_ashrrev_i32_e32 v153, 31, v152
	s_nop 0
	s_nop 0
	v_cvt_pk_bf16_f32 v121, v121, v115
	v_cvt_pk_bf16_f32 v120, v120, v114
	v_mov_b64_e32 v[114:115], s[8:9]
	v_cvt_pk_bf16_f32 v119, v155, v119
	v_cvt_pk_bf16_f32 v118, v154, v118
	v_mad_i64_i32 v[122:123], s[24:25], v151, s49, v[114:115]
	v_lshlrev_b64 v[116:117], 1, v[152:153]
	v_lshl_add_u64 v[122:123], v[122:123], 0, v[116:117]
	v_mul_f32_e32 v124, 0xbfb8aa3b, v110
	v_exp_f32_e32 v124, v124
	v_mul_f32_e32 v125, 0xbfb8aa3b, v111
	global_store_dwordx4 v[122:123], v[118:121], off
	v_exp_f32_e32 v125, v125
	v_mul_f32_e32 v123, 0xbfb8aa3b, v107
	v_mul_f32_e32 v120, 0xbfb8aa3b, v112
	v_exp_f32_e32 v121, v120
	v_mul_f32_e32 v120, 0xbfb8aa3b, v113
	v_exp_f32_e32 v122, v120
	v_add_f32_e32 v118, 1.0, v124
	v_mul_f32_e32 v124, 0xbfb8aa3b, v108
	v_add_f32_e32 v119, 1.0, v125
	v_exp_f32_e32 v123, v123
	v_exp_f32_e32 v125, v124
	v_mul_f32_e32 v124, 0xbfb8aa3b, v109
	v_rcp_f32_e32 v120, v119
	v_add_f32_e32 v119, 1.0, v121
	v_add_f32_e32 v121, 1.0, v122
	v_mul_f32_e32 v122, 0xbfb8aa3b, v106
	v_exp_f32_e32 v126, v124
	v_exp_f32_e32 v122, v122
	v_rcp_f32_e32 v118, v118
	v_rcp_f32_e32 v119, v119
	v_rcp_f32_e32 v121, v121
	v_add_f32_e32 v123, 1.0, v123
	v_rcp_f32_e32 v124, v123
	v_add_f32_e32 v123, 1.0, v125
	v_add_f32_e32 v125, 1.0, v126
	v_add_f32_e32 v122, 1.0, v122
	v_rcp_f32_e32 v125, v125
	v_rcp_f32_e32 v122, v122
	v_rcp_f32_e32 v123, v123
	v_mov_b32_e32 v126, v110
	v_mov_b32_e32 v127, v112
	v_mov_b32_e32 v112, v111
	v_pk_mul_f32 v[118:119], v[126:127], v[118:119]
	v_mov_b32_e32 v127, v104
	v_pk_mul_f32 v[110:111], v[112:113], v[120:121]
	v_mov_b32_e32 v104, v103
	v_mov_b32_e32 v126, v102
	v_pk_mul_f32 v[102:103], v[110:111], v[104:105]
	v_mov_b32_e32 v105, v108
	v_mov_b32_e32 v108, v107
	v_mov_b32_e32 v104, v106
	v_mov_b32_e32 v111, v100
	v_pk_mul_f32 v[106:107], v[108:109], v[124:125]
	v_mov_b32_e32 v100, v99
	v_pk_mul_f32 v[104:105], v[104:105], v[122:123]
	v_mov_b32_e32 v110, v98
	v_pk_mul_f32 v[98:99], v[106:107], v[100:101]
	v_pk_mul_f32 v[118:119], v[118:119], v[126:127]
	v_pk_mul_f32 v[104:105], v[104:105], v[110:111]
	s_nop 0
	s_nop 0
	s_nop 0
	s_nop 0
	s_nop 0
	s_nop 0
	s_nop 0
	s_nop 0
	s_nop 0
	s_nop 0
	s_nop 0
	s_nop 0
	s_nop 0
	s_nop 0
	s_nop 0
	s_nop 0
	s_nop 0
	s_nop 0
	s_nop 0
	s_nop 0
	v_cvt_pk_bf16_f32 v100, v104, v98
	v_cvt_pk_bf16_f32 v98, v118, v102
	v_or_b32_e32 v102, 16, v151
	v_cvt_pk_bf16_f32 v101, v105, v99
	v_cvt_pk_bf16_f32 v99, v119, v103
	v_mad_i64_i32 v[102:103], s[24:25], v102, s49, v[114:115]
	v_lshl_add_u64 v[102:103], v[102:103], 0, v[116:117]
	v_mul_f32_e32 v104, 0xbfb8aa3b, v94
	v_exp_f32_e32 v104, v104
	v_mul_f32_e32 v105, 0xbfb8aa3b, v95
	global_store_dwordx4 v[102:103], v[98:101], off
	v_exp_f32_e32 v105, v105
	v_mul_f32_e32 v103, 0xbfb8aa3b, v91
	v_mul_f32_e32 v100, 0xbfb8aa3b, v96
	v_exp_f32_e32 v101, v100
	v_mul_f32_e32 v100, 0xbfb8aa3b, v97
	v_exp_f32_e32 v102, v100
	v_add_f32_e32 v98, 1.0, v104
	v_mul_f32_e32 v104, 0xbfb8aa3b, v92
	v_add_f32_e32 v99, 1.0, v105
	v_exp_f32_e32 v103, v103
	v_exp_f32_e32 v105, v104
	v_mul_f32_e32 v104, 0xbfb8aa3b, v93
	v_rcp_f32_e32 v100, v99
	v_add_f32_e32 v99, 1.0, v101
	v_add_f32_e32 v101, 1.0, v102
	v_mul_f32_e32 v102, 0xbfb8aa3b, v90
	v_exp_f32_e32 v106, v104
	v_exp_f32_e32 v102, v102
	v_rcp_f32_e32 v98, v98
	v_rcp_f32_e32 v99, v99
	v_rcp_f32_e32 v101, v101
	v_add_f32_e32 v103, 1.0, v103
	v_rcp_f32_e32 v104, v103
	v_add_f32_e32 v103, 1.0, v105
	v_add_f32_e32 v105, 1.0, v106
	v_add_f32_e32 v102, 1.0, v102
	v_rcp_f32_e32 v105, v105
	v_rcp_f32_e32 v102, v102
	v_rcp_f32_e32 v103, v103
	v_mov_b32_e32 v106, v94
	v_mov_b32_e32 v107, v96
	v_mov_b32_e32 v96, v95
	v_pk_mul_f32 v[98:99], v[106:107], v[98:99]
	v_mov_b32_e32 v107, v88
	v_pk_mul_f32 v[94:95], v[96:97], v[100:101]
	v_mov_b32_e32 v88, v87
	v_mov_b32_e32 v106, v86
	v_pk_mul_f32 v[86:87], v[94:95], v[88:89]
	v_mov_b32_e32 v89, v92
	v_mov_b32_e32 v92, v91
	v_mov_b32_e32 v88, v90
	v_mov_b32_e32 v95, v84
	v_pk_mul_f32 v[90:91], v[92:93], v[104:105]
	v_mov_b32_e32 v84, v83
	v_pk_mul_f32 v[88:89], v[88:89], v[102:103]
	v_mov_b32_e32 v94, v82
	v_pk_mul_f32 v[82:83], v[90:91], v[84:85]
	v_pk_mul_f32 v[98:99], v[98:99], v[106:107]
	v_pk_mul_f32 v[88:89], v[88:89], v[94:95]
	s_nop 0
	s_nop 0
	s_nop 0
	s_nop 0
	s_nop 0
	s_nop 0
	s_nop 0
	s_nop 0
	s_nop 0
	s_nop 0
	s_nop 0
	s_nop 0
	s_nop 0
	s_nop 0
	s_nop 0
	s_nop 0
	s_nop 0
	s_nop 0
	s_nop 0
	s_nop 0
	v_cvt_pk_bf16_f32 v84, v88, v82
	v_cvt_pk_bf16_f32 v82, v98, v86
	v_or_b32_e32 v86, 32, v151
	v_cvt_pk_bf16_f32 v85, v89, v83
	v_cvt_pk_bf16_f32 v83, v99, v87
	v_mad_i64_i32 v[86:87], s[24:25], v86, s49, v[114:115]
	v_lshl_add_u64 v[86:87], v[86:87], 0, v[116:117]
	v_mul_f32_e32 v88, 0xbfb8aa3b, v78
	v_exp_f32_e32 v88, v88
	v_mul_f32_e32 v89, 0xbfb8aa3b, v79
	global_store_dwordx4 v[86:87], v[82:85], off
	v_exp_f32_e32 v89, v89
	v_mul_f32_e32 v87, 0xbfb8aa3b, v75
	v_mul_f32_e32 v84, 0xbfb8aa3b, v80
	v_exp_f32_e32 v85, v84
	v_mul_f32_e32 v84, 0xbfb8aa3b, v81
	v_exp_f32_e32 v86, v84
	v_add_f32_e32 v82, 1.0, v88
	v_mul_f32_e32 v88, 0xbfb8aa3b, v76
	v_add_f32_e32 v83, 1.0, v89
	v_exp_f32_e32 v87, v87
	v_exp_f32_e32 v89, v88
	v_mul_f32_e32 v88, 0xbfb8aa3b, v77
	v_rcp_f32_e32 v84, v83
	v_add_f32_e32 v83, 1.0, v85
	v_add_f32_e32 v85, 1.0, v86
	v_mul_f32_e32 v86, 0xbfb8aa3b, v74
	v_exp_f32_e32 v90, v88
	v_exp_f32_e32 v86, v86
	v_rcp_f32_e32 v82, v82
	v_rcp_f32_e32 v83, v83
	v_rcp_f32_e32 v85, v85
	v_add_f32_e32 v87, 1.0, v87
	v_rcp_f32_e32 v88, v87
	v_add_f32_e32 v87, 1.0, v89
	v_add_f32_e32 v89, 1.0, v90
	v_add_f32_e32 v86, 1.0, v86
	v_rcp_f32_e32 v89, v89
	v_rcp_f32_e32 v86, v86
	v_rcp_f32_e32 v87, v87
	v_mov_b32_e32 v90, v78
	v_mov_b32_e32 v91, v80
	v_mov_b32_e32 v80, v79
	v_pk_mul_f32 v[82:83], v[90:91], v[82:83]
	v_mov_b32_e32 v91, v72
	v_pk_mul_f32 v[78:79], v[80:81], v[84:85]
	v_mov_b32_e32 v72, v71
	v_mov_b32_e32 v90, v70
	v_pk_mul_f32 v[70:71], v[78:79], v[72:73]
	v_mov_b32_e32 v73, v76
	v_mov_b32_e32 v76, v75
	v_mov_b32_e32 v72, v74
	v_mov_b32_e32 v79, v68
	v_pk_mul_f32 v[74:75], v[76:77], v[88:89]
	v_mov_b32_e32 v68, v67
	v_pk_mul_f32 v[72:73], v[72:73], v[86:87]
	v_mov_b32_e32 v78, v66
	v_pk_mul_f32 v[66:67], v[74:75], v[68:69]
	v_pk_mul_f32 v[82:83], v[82:83], v[90:91]
	v_pk_mul_f32 v[72:73], v[72:73], v[78:79]
	s_nop 0
	s_nop 0
	s_nop 0
	s_nop 0
	s_nop 0
	s_nop 0
	s_nop 0
	s_nop 0
	s_nop 0
	s_nop 0
	s_nop 0
	s_nop 0
	s_nop 0
	s_nop 0
	s_nop 0
	s_nop 0
	s_nop 0
	s_nop 0
	s_nop 0
	s_nop 0
	v_cvt_pk_bf16_f32 v68, v72, v66
	v_cvt_pk_bf16_f32 v66, v82, v70
	v_or_b32_e32 v70, 48, v151
	v_cvt_pk_bf16_f32 v69, v73, v67
	v_cvt_pk_bf16_f32 v67, v83, v71
	v_mad_i64_i32 v[70:71], s[24:25], v70, s49, v[114:115]
	v_lshl_add_u64 v[70:71], v[70:71], 0, v[116:117]
	global_store_dwordx4 v[70:71], v[66:69], off
	v_mul_f32_e32 v71, 0xbfb8aa3b, v59
	v_mul_f32_e32 v72, 0xbfb8aa3b, v60
	v_mul_f32_e32 v67, 0xbfb8aa3b, v63
	v_mul_f32_e32 v68, 0xbfb8aa3b, v64
	v_exp_f32_e32 v67, v67
	v_exp_f32_e32 v69, v68
	v_mul_f32_e32 v68, 0xbfb8aa3b, v65
	v_exp_f32_e32 v70, v68
	v_mul_f32_e32 v66, 0xbfb8aa3b, v62
	v_exp_f32_e32 v66, v66
	v_add_f32_e32 v67, 1.0, v67
	v_exp_f32_e32 v71, v71
	v_exp_f32_e32 v73, v72
	v_mul_f32_e32 v72, 0xbfb8aa3b, v61
	v_rcp_f32_e32 v68, v67
	v_add_f32_e32 v67, 1.0, v69
	v_add_f32_e32 v69, 1.0, v70
	v_mul_f32_e32 v70, 0xbfb8aa3b, v58
	v_exp_f32_e32 v74, v72
	v_exp_f32_e32 v70, v70
	v_add_f32_e32 v66, 1.0, v66
	v_rcp_f32_e32 v66, v66
	v_rcp_f32_e32 v67, v67
	v_rcp_f32_e32 v69, v69
	v_add_f32_e32 v71, 1.0, v71
	v_rcp_f32_e32 v72, v71
	v_add_f32_e32 v71, 1.0, v73
	v_add_f32_e32 v73, 1.0, v74
	v_add_f32_e32 v70, 1.0, v70
	v_rcp_f32_e32 v73, v73
	v_rcp_f32_e32 v70, v70
	v_rcp_f32_e32 v71, v71
	v_mov_b32_e32 v74, v62
	v_mov_b32_e32 v75, v64
	v_mov_b32_e32 v64, v63
	v_pk_mul_f32 v[66:67], v[74:75], v[66:67]
	v_mov_b32_e32 v75, v56
	v_pk_mul_f32 v[62:63], v[64:65], v[68:69]
	v_mov_b32_e32 v56, v55
	v_mov_b32_e32 v74, v54
	v_pk_mul_f32 v[54:55], v[62:63], v[56:57]
	v_mov_b32_e32 v57, v60
	v_mov_b32_e32 v60, v59
	v_mov_b32_e32 v56, v58
	v_mov_b32_e32 v63, v52
	v_pk_mul_f32 v[58:59], v[60:61], v[72:73]
	v_mov_b32_e32 v52, v51
	v_pk_mul_f32 v[56:57], v[56:57], v[70:71]
	v_mov_b32_e32 v62, v50
	v_pk_mul_f32 v[50:51], v[58:59], v[52:53]
	v_pk_mul_f32 v[66:67], v[66:67], v[74:75]
	v_pk_mul_f32 v[56:57], v[56:57], v[62:63]
	s_nop 0
	s_nop 0
	s_nop 0
	s_nop 0
	s_nop 0
	s_nop 0
	s_nop 0
	s_nop 0
	s_nop 0
	s_nop 0
	s_nop 0
	s_nop 0
	s_nop 0
	s_nop 0
	s_nop 0
	s_nop 0
	v_add_u32_e32 v76, 0x80, v151
	s_nop 0
	s_nop 0
	s_nop 0
	s_nop 0
	v_cvt_pk_bf16_f32 v53, v57, v51
	v_cvt_pk_bf16_f32 v52, v56, v50
	v_cvt_pk_bf16_f32 v51, v67, v55
	v_cvt_pk_bf16_f32 v50, v66, v54
	v_mad_i64_i32 v[54:55], s[24:25], v76, s49, v[114:115]
	v_lshl_add_u64 v[54:55], v[54:55], 0, v[116:117]
	v_mul_f32_e32 v56, 0xbfb8aa3b, v46
	v_exp_f32_e32 v56, v56
	v_mul_f32_e32 v57, 0xbfb8aa3b, v47
	global_store_dwordx4 v[54:55], v[50:53], off
	v_exp_f32_e32 v57, v57
	v_mul_f32_e32 v55, 0xbfb8aa3b, v43
	v_mul_f32_e32 v52, 0xbfb8aa3b, v48
	v_exp_f32_e32 v53, v52
	v_mul_f32_e32 v52, 0xbfb8aa3b, v49
	v_exp_f32_e32 v54, v52
	v_add_f32_e32 v50, 1.0, v56
	v_mul_f32_e32 v56, 0xbfb8aa3b, v44
	v_add_f32_e32 v51, 1.0, v57
	v_exp_f32_e32 v55, v55
	v_exp_f32_e32 v57, v56
	v_mul_f32_e32 v56, 0xbfb8aa3b, v45
	v_rcp_f32_e32 v52, v51
	v_add_f32_e32 v51, 1.0, v53
	v_add_f32_e32 v53, 1.0, v54
	v_mul_f32_e32 v54, 0xbfb8aa3b, v42
	v_exp_f32_e32 v58, v56
	v_exp_f32_e32 v54, v54
	v_rcp_f32_e32 v50, v50
	v_rcp_f32_e32 v51, v51
	v_rcp_f32_e32 v53, v53
	v_add_f32_e32 v55, 1.0, v55
	v_rcp_f32_e32 v56, v55
	v_add_f32_e32 v55, 1.0, v57
	v_add_f32_e32 v57, 1.0, v58
	v_add_f32_e32 v54, 1.0, v54
	v_rcp_f32_e32 v57, v57
	v_rcp_f32_e32 v54, v54
	v_rcp_f32_e32 v55, v55
	v_mov_b32_e32 v58, v46
	v_mov_b32_e32 v59, v48
	v_mov_b32_e32 v48, v47
	v_pk_mul_f32 v[50:51], v[58:59], v[50:51]
	v_mov_b32_e32 v59, v40
	v_pk_mul_f32 v[46:47], v[48:49], v[52:53]
	v_mov_b32_e32 v40, v39
	v_mov_b32_e32 v58, v38
	v_pk_mul_f32 v[38:39], v[46:47], v[40:41]
	v_mov_b32_e32 v41, v44
	v_mov_b32_e32 v44, v43
	v_mov_b32_e32 v40, v42
	v_mov_b32_e32 v47, v36
	v_pk_mul_f32 v[42:43], v[44:45], v[56:57]
	v_mov_b32_e32 v36, v35
	v_pk_mul_f32 v[40:41], v[40:41], v[54:55]
	v_mov_b32_e32 v46, v34
	v_pk_mul_f32 v[34:35], v[42:43], v[36:37]
	v_pk_mul_f32 v[50:51], v[50:51], v[58:59]
	v_pk_mul_f32 v[40:41], v[40:41], v[46:47]
	s_nop 0
	s_nop 0
	s_nop 0
	s_nop 0
	s_nop 0
	s_nop 0
	s_nop 0
	s_nop 0
	s_nop 0
	s_nop 0
	s_nop 0
	s_nop 0
	s_nop 0
	s_nop 0
	s_nop 0
	s_nop 0
	s_nop 0
	s_nop 0
	s_nop 0
	s_nop 0
	v_cvt_pk_bf16_f32 v36, v40, v34
	v_cvt_pk_bf16_f32 v34, v50, v38
	v_add_u32_e32 v38, 0x90, v151
	v_cvt_pk_bf16_f32 v37, v41, v35
	v_cvt_pk_bf16_f32 v35, v51, v39
	v_mad_i64_i32 v[38:39], s[24:25], v38, s49, v[114:115]
	v_lshl_add_u64 v[38:39], v[38:39], 0, v[116:117]
	v_mul_f32_e32 v40, 0xbfb8aa3b, v30
	v_exp_f32_e32 v40, v40
	v_mul_f32_e32 v41, 0xbfb8aa3b, v31
	global_store_dwordx4 v[38:39], v[34:37], off
	v_exp_f32_e32 v41, v41
	v_mul_f32_e32 v39, 0xbfb8aa3b, v27
	v_mul_f32_e32 v36, 0xbfb8aa3b, v32
	v_exp_f32_e32 v37, v36
	v_mul_f32_e32 v36, 0xbfb8aa3b, v33
	v_exp_f32_e32 v38, v36
	v_add_f32_e32 v34, 1.0, v40
	v_mul_f32_e32 v40, 0xbfb8aa3b, v28
	v_add_f32_e32 v35, 1.0, v41
	v_exp_f32_e32 v39, v39
	v_exp_f32_e32 v41, v40
	v_mul_f32_e32 v40, 0xbfb8aa3b, v29
	v_rcp_f32_e32 v36, v35
	v_add_f32_e32 v35, 1.0, v37
	v_add_f32_e32 v37, 1.0, v38
	v_mul_f32_e32 v38, 0xbfb8aa3b, v26
	v_exp_f32_e32 v42, v40
	v_exp_f32_e32 v38, v38
	v_rcp_f32_e32 v34, v34
	v_rcp_f32_e32 v35, v35
	v_rcp_f32_e32 v37, v37
	v_add_f32_e32 v39, 1.0, v39
	v_rcp_f32_e32 v40, v39
	v_add_f32_e32 v39, 1.0, v41
	v_add_f32_e32 v41, 1.0, v42
	v_add_f32_e32 v38, 1.0, v38
	v_rcp_f32_e32 v41, v41
	v_rcp_f32_e32 v38, v38
	v_rcp_f32_e32 v39, v39
	v_mov_b32_e32 v42, v30
	v_mov_b32_e32 v43, v32
	v_mov_b32_e32 v32, v31
	v_pk_mul_f32 v[34:35], v[42:43], v[34:35]
	v_mov_b32_e32 v43, v24
	v_pk_mul_f32 v[30:31], v[32:33], v[36:37]
	v_mov_b32_e32 v24, v23
	v_mov_b32_e32 v42, v22
	v_pk_mul_f32 v[22:23], v[30:31], v[24:25]
	v_mov_b32_e32 v25, v28
	v_mov_b32_e32 v28, v27
	v_mov_b32_e32 v24, v26
	v_mov_b32_e32 v31, v20
	v_pk_mul_f32 v[26:27], v[28:29], v[40:41]
	v_mov_b32_e32 v20, v19
	v_pk_mul_f32 v[24:25], v[24:25], v[38:39]
	v_mov_b32_e32 v30, v18
	v_pk_mul_f32 v[18:19], v[26:27], v[20:21]
	v_pk_mul_f32 v[34:35], v[34:35], v[42:43]
	v_pk_mul_f32 v[24:25], v[24:25], v[30:31]
	s_nop 0
	s_nop 0
	s_nop 0
	s_nop 0
	s_nop 0
	s_nop 0
	s_nop 0
	s_nop 0
	s_nop 0
	s_nop 0
	s_nop 0
	s_nop 0
	s_nop 0
	s_nop 0
	s_nop 0
	s_nop 0
	s_nop 0
	s_nop 0
	s_nop 0
	s_nop 0
	v_cvt_pk_bf16_f32 v20, v24, v18
	v_cvt_pk_bf16_f32 v18, v34, v22
	v_add_u32_e32 v22, 0xa0, v151
	v_cvt_pk_bf16_f32 v21, v25, v19
	v_cvt_pk_bf16_f32 v19, v35, v23
	v_mad_i64_i32 v[22:23], s[24:25], v22, s49, v[114:115]
	v_lshl_add_u64 v[22:23], v[22:23], 0, v[116:117]
	v_mul_f32_e32 v24, 0xbfb8aa3b, v14
	v_exp_f32_e32 v24, v24
	v_mul_f32_e32 v25, 0xbfb8aa3b, v15
	global_store_dwordx4 v[22:23], v[18:21], off
	v_exp_f32_e32 v25, v25
	v_mul_f32_e32 v23, 0xbfb8aa3b, v11
	v_mul_f32_e32 v20, 0xbfb8aa3b, v16
	v_exp_f32_e32 v21, v20
	v_mul_f32_e32 v20, 0xbfb8aa3b, v17
	v_exp_f32_e32 v22, v20
	v_add_f32_e32 v18, 1.0, v24
	v_mul_f32_e32 v24, 0xbfb8aa3b, v12
	v_add_f32_e32 v19, 1.0, v25
	v_exp_f32_e32 v23, v23
	v_exp_f32_e32 v25, v24
	v_mul_f32_e32 v24, 0xbfb8aa3b, v13
	v_rcp_f32_e32 v20, v19
	v_add_f32_e32 v19, 1.0, v21
	v_add_f32_e32 v21, 1.0, v22
	v_mul_f32_e32 v22, 0xbfb8aa3b, v10
	v_exp_f32_e32 v26, v24
	v_exp_f32_e32 v22, v22
	v_rcp_f32_e32 v18, v18
	v_rcp_f32_e32 v19, v19
	v_rcp_f32_e32 v21, v21
	v_add_f32_e32 v23, 1.0, v23
	v_rcp_f32_e32 v24, v23
	v_add_f32_e32 v23, 1.0, v25
	v_add_f32_e32 v25, 1.0, v26
	v_add_f32_e32 v22, 1.0, v22
	v_rcp_f32_e32 v25, v25
	v_rcp_f32_e32 v22, v22
	v_rcp_f32_e32 v23, v23
	v_mov_b32_e32 v26, v14
	v_mov_b32_e32 v27, v16
	v_mov_b32_e32 v16, v15
	v_pk_mul_f32 v[18:19], v[26:27], v[18:19]
	v_mov_b32_e32 v27, v8
	v_pk_mul_f32 v[14:15], v[16:17], v[20:21]
	v_mov_b32_e32 v8, v7
	v_mov_b32_e32 v26, v6
	v_pk_mul_f32 v[6:7], v[14:15], v[8:9]
	v_mov_b32_e32 v9, v12
	v_mov_b32_e32 v12, v11
	v_mov_b32_e32 v8, v10
	v_mov_b32_e32 v15, v4
	v_pk_mul_f32 v[10:11], v[12:13], v[24:25]
	v_mov_b32_e32 v4, v3
	v_pk_mul_f32 v[8:9], v[8:9], v[22:23]
	v_mov_b32_e32 v14, v2
	v_pk_mul_f32 v[2:3], v[10:11], v[4:5]
	v_pk_mul_f32 v[18:19], v[18:19], v[26:27]
	v_pk_mul_f32 v[8:9], v[8:9], v[14:15]
	s_nop 0
	s_nop 0
	s_nop 0
	s_nop 0
	s_nop 0
	s_nop 0
	s_nop 0
	s_nop 0
	s_nop 0
	s_nop 0
	s_nop 0
	s_nop 0
	s_nop 0
	s_nop 0
	s_nop 0
	s_nop 0
	s_nop 0
	s_nop 0
	s_nop 0
	s_nop 0
	v_cvt_pk_bf16_f32 v4, v8, v2
	v_cvt_pk_bf16_f32 v2, v18, v6
	v_add_u32_e32 v6, 0xb0, v151
	v_cvt_pk_bf16_f32 v5, v9, v3
	v_cvt_pk_bf16_f32 v3, v19, v7
	v_mad_i64_i32 v[6:7], s[24:25], v6, s49, v[114:115]
	v_lshl_add_u64 v[6:7], v[6:7], 0, v[116:117]
	s_andn2_b64 vcc, exec, s[2:3]
	s_mov_b64 s[2:3], -1
	global_store_dwordx4 v[6:7], v[2:5], off
	s_cbranch_vccnz .LBB0_1921
	s_andn2_b64 vcc, exec, s[4:5]
	s_cbranch_vccnz .LBB0_1920
	s_barrier
	s_branch .LBB0_1920
